# GEMM K-loops only: LDS-DMA via SGPR base + 32-bit VGPR offset (saddr) instead of per-DMA 64-bit VALU address adds
# speedup vs baseline: 1.0119x; 1.0019x over previous
; #define PG8_STAGE(bufoff, gbase, voff) do { _Pragma("unroll") for (int _i = 0; _i < 2; ++_i) \
;         __builtin_amdgcn_global_load_lds((const unsigned*)((const char*)(gbase) + (voff)[_i]), (LAS unsigned*)(lds + (bufoff) + ldsw + _i * 8192), 16, 0, 0); } while (0)
; #define PG8_LDA(dst, b, h) do { _Pragma("unroll") for (int m = 0; m < 4; ++m) _Pragma("unroll") for (int k = 0; k < 2; ++k) dst[m][k] = *(const LAS bf16x8*)(lds + PG8_SA(b, h) + aoff + m * 2048 + k * 1024); } while (0)
; #define PG8_LDB(dst, b, h) do { _Pragma("unroll") for (int n = 0; n < 2; ++n) _Pragma("unroll") for (int k = 0; k < 2; ++k) dst[n][k] = *(const LAS bf16x8*)(lds + PG8_SB(b, h) + boff + n * 2048 + k * 1024); } while (0)
; #define PG8_MMA(ai, bj, At, Bt) do { __builtin_amdgcn_s_setprio(1); _Pragma("unroll") for (int m = 0; m < 4; ++m) _Pragma("unroll") for (int n = 0; n < 2; ++n) _Pragma("unroll") for (int k = 0; k < 2; ++k) \
;         acc[ai][bj][m][n] = __builtin_amdgcn_mfma_f32_16x16x32_bf16(Bt[n][k], At[m][k], acc[ai][bj][m][n], 0, 0, 0); __builtin_amdgcn_s_setprio(0); } while (0)
; #define PG8_WAIT_V(n) asm volatile("s_waitcnt vmcnt(" #n ")" ::: "memory")
; template <class Epi, class Sched, bool ALIGN_EPI, class Hook = NoHook>
; __device__ __forceinline__ void gemm_phase(LAS unsigned char* lds, const Gemm g, const Sched& S, const Epi& E, const Hook& H = Hook()) {
;     ...
;             PG8_LDB(B0, 0, 0); PG8_LDB(B1, 0, 1); PG8_SCHED; PG8_LDA(At, 0, 0); PG8_STAGE(PG8_SA(1, 1), a1 + hA, voffA);
;             PG8_WAIT_V(8); PG8_WAIT_L(0); PG8_BAR; PG8_MMA(0, 0, At, B0); PG8_MMA(0, 1, At, B1); PG8_BAR; PG8_SCHED;
;             PG8_LDA(At, 0, 1); PG8_STAGE(PG8_SB(0, 0), b2, voffB); PG8_STAGE(PG8_SB(0, 1), b2 + hB, voffB); PG8_STAGE(PG8_SA(0, 0), a2, voffA);
;             PG8_WAIT_V(8); PG8_WAIT_L(0); PG8_BAR; PG8_MMA(1, 0, At, B0); PG8_MMA(1, 1, At, B1); PG8_BAR; PG8_SCHED;
;             PG8_LDB(B0, 1, 0); PG8_LDB(B1, 1, 1); PG8_SCHED; PG8_LDA(At, 1, 0); PG8_STAGE(PG8_SA(0, 1), a2 + hA, voffA);
;             PG8_WAIT_V(8); PG8_WAIT_L(0); PG8_BAR; PG8_MMA(0, 0, At, B0); PG8_MMA(0, 1, At, B1); PG8_BAR; PG8_SCHED;
;             PG8_LDA(At, 1, 1); PG8_STAGE(PG8_SB(1, 0), b3, voffB); PG8_STAGE(PG8_SB(1, 1), b3 + hB, voffB); PG8_STAGE(PG8_SA(1, 0), a3, voffA);
;             PG8_WAIT_V(8); PG8_WAIT_L(0); PG8_BAR; PG8_MMA(1, 0, At, B0); PG8_MMA(1, 1, At, B1); PG8_BAR; PG8_SCHED;
.LBB0_199:
	ds_read_b128 v[130:133], v217
	ds_read_b128 v[134:137], v217 offset:1024
	ds_read_b128 v[138:141], v217 offset:2048
	ds_read_b128 v[142:145], v217 offset:3072
	ds_read_b128 v[146:149], v218
	ds_read_b128 v[150:153], v218 offset:1024
	ds_read_b128 v[154:157], v218 offset:2048
	ds_read_b128 v[158:161], v218 offset:3072
	s_add_u32 s34, s4, 0x100
	s_addc_u32 s35, s5, 0
	s_cmp_eq_u32 s64, 60
	s_cselect_b32 s39, s7, s35
	s_cselect_b32 s38, s8, s34
	s_cselect_b32 s37, s23, s63
	s_cselect_b32 s36, s25, s31
	s_add_i32 m0, s40, 0xc000
	ds_read_b128 v[180:183], v219
	ds_read_b128 v[184:187], v219 offset:1024
	ds_read_b128 v[188:191], v219 offset:2048
	ds_read_b128 v[192:195], v219 offset:3072
	ds_read_b128 v[196:199], v219 offset:4096
	ds_read_b128 v[200:203], v219 offset:5120
	ds_read_b128 v[204:207], v219 offset:6144
	ds_read_b128 v[208:211], v219 offset:7168
	global_load_lds_dwordx4 v172, s[4:5]
	s_add_i32 m0, s40, 0xe000
	s_nop 0
	global_load_lds_dwordx4 v174, s[4:5]
	s_waitcnt vmcnt(8)
	s_waitcnt lgkmcnt(0)
	s_barrier
	s_setprio 1
	s_waitcnt lgkmcnt(0)
	v_mfma_f32_16x16x32_bf16 v[126:129], v[130:133], v[180:183], v[126:129]
	v_mfma_f32_16x16x32_bf16 v[94:97], v[138:141], v[180:183], v[94:97]
	v_mfma_f32_16x16x32_bf16 v[122:125], v[130:133], v[188:191], v[122:125]
	v_mfma_f32_16x16x32_bf16 v[90:93], v[138:141], v[188:191], v[90:93]
	v_mfma_f32_16x16x32_bf16 v[118:121], v[130:133], v[196:199], v[118:121]
	v_mfma_f32_16x16x32_bf16 v[86:89], v[138:141], v[196:199], v[86:89]
	v_mfma_f32_16x16x32_bf16 v[114:117], v[130:133], v[204:207], v[114:117]
	v_mfma_f32_16x16x32_bf16 v[82:85], v[138:141], v[204:207], v[82:85]
	v_mfma_f32_16x16x32_bf16 v[126:129], v[134:137], v[184:187], v[126:129]
	v_mfma_f32_16x16x32_bf16 v[94:97], v[142:145], v[184:187], v[94:97]
	v_mfma_f32_16x16x32_bf16 v[122:125], v[134:137], v[192:195], v[122:125]
	v_mfma_f32_16x16x32_bf16 v[90:93], v[142:145], v[192:195], v[90:93]
	v_mfma_f32_16x16x32_bf16 v[118:121], v[134:137], v[200:203], v[118:121]
	v_mfma_f32_16x16x32_bf16 v[86:89], v[142:145], v[200:203], v[86:89]
	v_mfma_f32_16x16x32_bf16 v[114:117], v[134:137], v[208:211], v[114:117]
	v_mfma_f32_16x16x32_bf16 v[82:85], v[142:145], v[208:211], v[82:85]
	s_setprio 0
	s_setprio 1
	v_mfma_f32_16x16x32_bf16 v[62:65], v[146:149], v[180:183], v[62:65]
	v_mfma_f32_16x16x32_bf16 v[30:33], v[154:157], v[180:183], v[30:33]
	v_mfma_f32_16x16x32_bf16 v[58:61], v[146:149], v[188:191], v[58:61]
	v_mfma_f32_16x16x32_bf16 v[26:29], v[154:157], v[188:191], v[26:29]
	v_mfma_f32_16x16x32_bf16 v[54:57], v[146:149], v[196:199], v[54:57]
	v_mfma_f32_16x16x32_bf16 v[22:25], v[154:157], v[196:199], v[22:25]
	v_mfma_f32_16x16x32_bf16 v[50:53], v[146:149], v[204:207], v[50:53]
	v_mfma_f32_16x16x32_bf16 v[18:21], v[154:157], v[204:207], v[18:21]
	v_mfma_f32_16x16x32_bf16 v[62:65], v[150:153], v[184:187], v[62:65]
	v_mfma_f32_16x16x32_bf16 v[30:33], v[158:161], v[184:187], v[30:33]
	v_mfma_f32_16x16x32_bf16 v[58:61], v[150:153], v[192:195], v[58:61]
	v_mfma_f32_16x16x32_bf16 v[26:29], v[158:161], v[192:195], v[26:29]
	v_mfma_f32_16x16x32_bf16 v[54:57], v[150:153], v[200:203], v[54:57]
	v_mfma_f32_16x16x32_bf16 v[22:25], v[158:161], v[200:203], v[22:25]
	v_mfma_f32_16x16x32_bf16 v[50:53], v[150:153], v[208:211], v[50:53]
	v_mfma_f32_16x16x32_bf16 v[18:21], v[158:161], v[208:211], v[18:21]
	s_setprio 0
	s_barrier
	s_add_i32 s4, s59, s21
	s_mov_b32 m0, s4
	ds_read_b128 v[180:183], v219 offset:16384
	ds_read_b128 v[184:187], v219 offset:17408
	ds_read_b128 v[188:191], v219 offset:18432
	ds_read_b128 v[192:195], v219 offset:19456
	ds_read_b128 v[196:199], v219 offset:20480
	ds_read_b128 v[200:203], v219 offset:21504
	ds_read_b128 v[204:207], v219 offset:22528
	ds_read_b128 v[208:211], v219 offset:23552
	global_load_lds_dwordx4 v164, s[36:37]
	s_add_i32 m0, s4, 0x2000
	s_add_u32 s4, s36, 0x100000
	s_addc_u32 s5, s37, 0
	s_add_i32 s65, s60, s21
	global_load_lds_dwordx4 v168, s[36:37]
	s_mov_b32 m0, s65
	s_nop 0
	global_load_lds_dwordx4 v164, s[4:5]
	s_add_i32 m0, s65, 0x2000
	s_nop 0
	global_load_lds_dwordx4 v168, s[4:5]
	s_mov_b32 m0, s40
	s_nop 0
	global_load_lds_dwordx4 v162, s[38:39]
	s_mov_b32 m0, s41
	s_nop 0
	global_load_lds_dwordx4 v166, s[38:39]
	s_waitcnt vmcnt(8)
	s_waitcnt lgkmcnt(0)
	s_barrier
	s_setprio 1
	s_waitcnt lgkmcnt(0)
	v_mfma_f32_16x16x32_bf16 v[110:113], v[130:133], v[180:183], v[110:113]
	v_mfma_f32_16x16x32_bf16 v[78:81], v[138:141], v[180:183], v[78:81]
	v_mfma_f32_16x16x32_bf16 v[106:109], v[130:133], v[188:191], v[106:109]
	v_mfma_f32_16x16x32_bf16 v[74:77], v[138:141], v[188:191], v[74:77]
	v_mfma_f32_16x16x32_bf16 v[102:105], v[130:133], v[196:199], v[102:105]
	v_mfma_f32_16x16x32_bf16 v[70:73], v[138:141], v[196:199], v[70:73]
	v_mfma_f32_16x16x32_bf16 v[98:101], v[130:133], v[204:207], v[98:101]
	v_mfma_f32_16x16x32_bf16 v[66:69], v[138:141], v[204:207], v[66:69]
	v_mfma_f32_16x16x32_bf16 v[110:113], v[134:137], v[184:187], v[110:113]
	v_mfma_f32_16x16x32_bf16 v[78:81], v[142:145], v[184:187], v[78:81]
	v_mfma_f32_16x16x32_bf16 v[106:109], v[134:137], v[192:195], v[106:109]
	v_mfma_f32_16x16x32_bf16 v[74:77], v[142:145], v[192:195], v[74:77]
	v_mfma_f32_16x16x32_bf16 v[102:105], v[134:137], v[200:203], v[102:105]
	v_mfma_f32_16x16x32_bf16 v[70:73], v[142:145], v[200:203], v[70:73]
	v_mfma_f32_16x16x32_bf16 v[98:101], v[134:137], v[208:211], v[98:101]
	v_mfma_f32_16x16x32_bf16 v[66:69], v[142:145], v[208:211], v[66:69]
	s_setprio 0
	s_setprio 1
	v_mfma_f32_16x16x32_bf16 v[46:49], v[146:149], v[180:183], v[46:49]
	v_mfma_f32_16x16x32_bf16 v[14:17], v[154:157], v[180:183], v[14:17]
	v_mfma_f32_16x16x32_bf16 v[42:45], v[146:149], v[188:191], v[42:45]
	v_mfma_f32_16x16x32_bf16 v[10:13], v[154:157], v[188:191], v[10:13]
	v_mfma_f32_16x16x32_bf16 v[38:41], v[146:149], v[196:199], v[38:41]
	v_mfma_f32_16x16x32_bf16 v[6:9], v[154:157], v[196:199], v[6:9]
	v_mfma_f32_16x16x32_bf16 v[34:37], v[146:149], v[204:207], v[34:37]
	v_mfma_f32_16x16x32_bf16 v[2:5], v[154:157], v[204:207], v[2:5]
	v_mfma_f32_16x16x32_bf16 v[46:49], v[150:153], v[184:187], v[46:49]
	v_mfma_f32_16x16x32_bf16 v[14:17], v[158:161], v[184:187], v[14:17]
	v_mfma_f32_16x16x32_bf16 v[42:45], v[150:153], v[192:195], v[42:45]
	v_mfma_f32_16x16x32_bf16 v[10:13], v[158:161], v[192:195], v[10:13]
	v_mfma_f32_16x16x32_bf16 v[38:41], v[150:153], v[200:203], v[38:41]
	v_mfma_f32_16x16x32_bf16 v[6:9], v[158:161], v[200:203], v[6:9]
	v_mfma_f32_16x16x32_bf16 v[34:37], v[150:153], v[208:211], v[34:37]
	v_mfma_f32_16x16x32_bf16 v[2:5], v[158:161], v[208:211], v[2:5]
	s_setprio 0
	s_barrier
; #define PG8_STAGE(bufoff, gbase, voff) do { _Pragma("unroll") for (int _i = 0; _i < 2; ++_i) \
;         __builtin_amdgcn_global_load_lds((const unsigned*)((const char*)(gbase) + (voff)[_i]), (LAS unsigned*)(lds + (bufoff) + ldsw + _i * 8192), 16, 0, 0); } while (0)
; #define PG8_LDA(dst, b, h) do { _Pragma("unroll") for (int m = 0; m < 4; ++m) _Pragma("unroll") for (int k = 0; k < 2; ++k) dst[m][k] = *(const LAS bf16x8*)(lds + PG8_SA(b, h) + aoff + m * 2048 + k * 1024); } while (0)
; #define PG8_LDB(dst, b, h) do { _Pragma("unroll") for (int n = 0; n < 2; ++n) _Pragma("unroll") for (int k = 0; k < 2; ++k) dst[n][k] = *(const LAS bf16x8*)(lds + PG8_SB(b, h) + boff + n * 2048 + k * 1024); } while (0)
; #define PG8_MMA(ai, bj, At, Bt) do { __builtin_amdgcn_s_setprio(1); _Pragma("unroll") for (int m = 0; m < 4; ++m) _Pragma("unroll") for (int n = 0; n < 2; ++n) _Pragma("unroll") for (int k = 0; k < 2; ++k) \
;         acc[ai][bj][m][n] = __builtin_amdgcn_mfma_f32_16x16x32_bf16(Bt[n][k], At[m][k], acc[ai][bj][m][n], 0, 0, 0); __builtin_amdgcn_s_setprio(0); } while (0)
; template <class Epi, class Sched, bool ALIGN_EPI, class Hook = NoHook>
; __device__ __forceinline__ void gemm_phase(LAS unsigned char* lds, const Gemm g, const Sched& S, const Epi& E, const Hook& H = Hook()) {
;     ...
;             PG8_LDB(B0, 0, 0); PG8_LDB(B1, 0, 1); PG8_SCHED; PG8_LDA(At, 0, 0); PG8_STAGE(PG8_SA(1, 1), a1 + hA, voffA);
;             PG8_WAIT_V(8); PG8_WAIT_L(0); PG8_BAR; PG8_MMA(0, 0, At, B0); PG8_MMA(0, 1, At, B1); PG8_BAR; PG8_SCHED;
;             PG8_LDA(At, 0, 1); PG8_STAGE(PG8_SB(0, 0), b2, voffB); PG8_STAGE(PG8_SB(0, 1), b2 + hB, voffB); PG8_STAGE(PG8_SA(0, 0), a2, voffA);
;             PG8_WAIT_V(8); PG8_WAIT_L(0); PG8_BAR; PG8_MMA(1, 0, At, B0); PG8_MMA(1, 1, At, B1); PG8_BAR; PG8_SCHED;
;             PG8_LDB(B0, 1, 0); PG8_LDB(B1, 1, 1); PG8_SCHED; PG8_LDA(At, 1, 0); PG8_STAGE(PG8_SA(0, 1), a2 + hA, voffA);
;             PG8_WAIT_V(8); PG8_WAIT_L(0); PG8_BAR; PG8_MMA(0, 0, At, B0); PG8_MMA(0, 1, At, B1); PG8_BAR; PG8_SCHED;
;             PG8_LDA(At, 1, 1); PG8_STAGE(PG8_SB(1, 0), b3, voffB); PG8_STAGE(PG8_SB(1, 1), b3 + hB, voffB); PG8_STAGE(PG8_SA(1, 0), a3, voffA);
;             PG8_WAIT_V(8); PG8_WAIT_L(0); PG8_BAR; PG8_MMA(1, 0, At, B0); PG8_MMA(1, 1, At, B1); PG8_BAR; PG8_SCHED;
;     ...
;         if constexpr (ALIGN_EPI) { if (wr == 0) PG8_BAR; }
	s_add_i32 s65, 0, 0x18000
	s_add_i32 s66, 0, 0x1c000
	v_add_u32_e32 v142, s65, v213
	v_add_u32_e32 v158, s66, v213
	ds_read_b128 v[130:133], v142
	ds_read_b128 v[134:137], v142 offset:1024
	ds_read_b128 v[138:141], v142 offset:2048
	ds_read_b128 v[142:145], v142 offset:3072
	ds_read_b128 v[146:149], v158
	ds_read_b128 v[150:153], v158 offset:1024
	ds_read_b128 v[154:157], v158 offset:2048
	ds_read_b128 v[158:161], v158 offset:3072
	s_add_u32 s4, s38, 0x8000
	s_addc_u32 s5, s39, 0
	s_mov_b32 m0, s42
	ds_read_b128 v[180:183], v219 offset:32768
	ds_read_b128 v[184:187], v219 offset:33792
	ds_read_b128 v[188:191], v219 offset:34816
	ds_read_b128 v[192:195], v219 offset:35840
	ds_read_b128 v[196:199], v219 offset:36864
	ds_read_b128 v[200:203], v219 offset:37888
	ds_read_b128 v[204:207], v219 offset:38912
	ds_read_b128 v[208:211], v219 offset:39936
	global_load_lds_dwordx4 v162, s[4:5]
	s_mov_b32 m0, s43
	s_nop 0
	global_load_lds_dwordx4 v166, s[4:5]
	s_waitcnt vmcnt(8)
	s_waitcnt lgkmcnt(0)
	s_barrier
	s_setprio 1
	s_waitcnt lgkmcnt(0)
	v_mfma_f32_16x16x32_bf16 v[126:129], v[130:133], v[180:183], v[126:129]
	v_mfma_f32_16x16x32_bf16 v[94:97], v[138:141], v[180:183], v[94:97]
	v_mfma_f32_16x16x32_bf16 v[122:125], v[130:133], v[188:191], v[122:125]
	v_mfma_f32_16x16x32_bf16 v[90:93], v[138:141], v[188:191], v[90:93]
	v_mfma_f32_16x16x32_bf16 v[118:121], v[130:133], v[196:199], v[118:121]
	v_mfma_f32_16x16x32_bf16 v[86:89], v[138:141], v[196:199], v[86:89]
	v_mfma_f32_16x16x32_bf16 v[114:117], v[130:133], v[204:207], v[114:117]
	v_mfma_f32_16x16x32_bf16 v[82:85], v[138:141], v[204:207], v[82:85]
	v_mfma_f32_16x16x32_bf16 v[126:129], v[134:137], v[184:187], v[126:129]
	v_mfma_f32_16x16x32_bf16 v[94:97], v[142:145], v[184:187], v[94:97]
	v_mfma_f32_16x16x32_bf16 v[122:125], v[134:137], v[192:195], v[122:125]
	v_mfma_f32_16x16x32_bf16 v[90:93], v[142:145], v[192:195], v[90:93]
	v_mfma_f32_16x16x32_bf16 v[118:121], v[134:137], v[200:203], v[118:121]
	v_mfma_f32_16x16x32_bf16 v[86:89], v[142:145], v[200:203], v[86:89]
	v_mfma_f32_16x16x32_bf16 v[114:117], v[134:137], v[208:211], v[114:117]
	v_mfma_f32_16x16x32_bf16 v[82:85], v[142:145], v[208:211], v[82:85]
	s_setprio 0
	s_setprio 1
	v_mfma_f32_16x16x32_bf16 v[62:65], v[146:149], v[180:183], v[62:65]
	v_mfma_f32_16x16x32_bf16 v[30:33], v[154:157], v[180:183], v[30:33]
	v_mfma_f32_16x16x32_bf16 v[58:61], v[146:149], v[188:191], v[58:61]
	v_mfma_f32_16x16x32_bf16 v[26:29], v[154:157], v[188:191], v[26:29]
	v_mfma_f32_16x16x32_bf16 v[54:57], v[146:149], v[196:199], v[54:57]
	v_mfma_f32_16x16x32_bf16 v[22:25], v[154:157], v[196:199], v[22:25]
	v_mfma_f32_16x16x32_bf16 v[50:53], v[146:149], v[204:207], v[50:53]
	v_mfma_f32_16x16x32_bf16 v[18:21], v[154:157], v[204:207], v[18:21]
	v_mfma_f32_16x16x32_bf16 v[62:65], v[150:153], v[184:187], v[62:65]
	v_mfma_f32_16x16x32_bf16 v[30:33], v[158:161], v[184:187], v[30:33]
	v_mfma_f32_16x16x32_bf16 v[58:61], v[150:153], v[192:195], v[58:61]
	v_mfma_f32_16x16x32_bf16 v[26:29], v[158:161], v[192:195], v[26:29]
	v_mfma_f32_16x16x32_bf16 v[54:57], v[150:153], v[200:203], v[54:57]
	v_mfma_f32_16x16x32_bf16 v[22:25], v[158:161], v[200:203], v[22:25]
	v_mfma_f32_16x16x32_bf16 v[50:53], v[150:153], v[208:211], v[50:53]
	v_mfma_f32_16x16x32_bf16 v[18:21], v[158:161], v[208:211], v[18:21]
	s_setprio 0
	s_barrier
	s_add_i32 s4, s65, s21
	s_add_u32 s68, s36, s14
	s_addc_u32 s69, s37, s15
	s_mov_b32 m0, s4
	ds_read_b128 v[180:183], v219 offset:49152
	ds_read_b128 v[184:187], v219 offset:50176
	ds_read_b128 v[188:191], v219 offset:51200
	ds_read_b128 v[192:195], v219 offset:52224
	ds_read_b128 v[196:199], v219 offset:53248
	ds_read_b128 v[200:203], v219 offset:54272
	ds_read_b128 v[204:207], v219 offset:55296
	ds_read_b128 v[208:211], v219 offset:56320
	global_load_lds_dwordx4 v164, s[68:69]
	s_add_i32 m0, s4, 0x2000
	s_add_u32 s4, s36, 0x100080
	s_addc_u32 s5, s37, 0
	s_add_i32 s36, s66, s21
	global_load_lds_dwordx4 v168, s[68:69]
	s_mov_b32 m0, s36
	s_nop 0
	global_load_lds_dwordx4 v164, s[4:5]
	s_add_i32 m0, s36, 0x2000
	s_nop 0
	global_load_lds_dwordx4 v168, s[4:5]
	s_add_u32 s70, s38, s14
	s_addc_u32 s71, s39, s15
	s_mov_b32 m0, s51
	s_nop 0
	global_load_lds_dwordx4 v162, s[70:71]
	s_mov_b32 m0, s52
	s_nop 0
	global_load_lds_dwordx4 v166, s[70:71]
	s_waitcnt vmcnt(8)
	s_waitcnt lgkmcnt(0)
	s_barrier
	s_setprio 1
	s_waitcnt lgkmcnt(0)
	v_mfma_f32_16x16x32_bf16 v[110:113], v[130:133], v[180:183], v[110:113]
	v_mfma_f32_16x16x32_bf16 v[78:81], v[138:141], v[180:183], v[78:81]
	v_mfma_f32_16x16x32_bf16 v[106:109], v[130:133], v[188:191], v[106:109]
	v_mfma_f32_16x16x32_bf16 v[74:77], v[138:141], v[188:191], v[74:77]
	v_mfma_f32_16x16x32_bf16 v[102:105], v[130:133], v[196:199], v[102:105]
	v_mfma_f32_16x16x32_bf16 v[70:73], v[138:141], v[196:199], v[70:73]
	v_mfma_f32_16x16x32_bf16 v[98:101], v[130:133], v[204:207], v[98:101]
	v_mfma_f32_16x16x32_bf16 v[66:69], v[138:141], v[204:207], v[66:69]
	v_mfma_f32_16x16x32_bf16 v[110:113], v[134:137], v[184:187], v[110:113]
	v_mfma_f32_16x16x32_bf16 v[78:81], v[142:145], v[184:187], v[78:81]
	v_mfma_f32_16x16x32_bf16 v[106:109], v[134:137], v[192:195], v[106:109]
	v_mfma_f32_16x16x32_bf16 v[74:77], v[142:145], v[192:195], v[74:77]
	v_mfma_f32_16x16x32_bf16 v[102:105], v[134:137], v[200:203], v[102:105]
	v_mfma_f32_16x16x32_bf16 v[70:73], v[142:145], v[200:203], v[70:73]
	v_mfma_f32_16x16x32_bf16 v[98:101], v[134:137], v[208:211], v[98:101]
	v_mfma_f32_16x16x32_bf16 v[66:69], v[142:145], v[208:211], v[66:69]
	s_setprio 0
	s_setprio 1
	v_mfma_f32_16x16x32_bf16 v[46:49], v[146:149], v[180:183], v[46:49]
	v_mfma_f32_16x16x32_bf16 v[14:17], v[154:157], v[180:183], v[14:17]
	v_mfma_f32_16x16x32_bf16 v[42:45], v[146:149], v[188:191], v[42:45]
	v_mfma_f32_16x16x32_bf16 v[10:13], v[154:157], v[188:191], v[10:13]
	v_mfma_f32_16x16x32_bf16 v[38:41], v[146:149], v[196:199], v[38:41]
	v_mfma_f32_16x16x32_bf16 v[6:9], v[154:157], v[196:199], v[6:9]
	v_mfma_f32_16x16x32_bf16 v[34:37], v[146:149], v[204:207], v[34:37]
	v_mfma_f32_16x16x32_bf16 v[2:5], v[154:157], v[204:207], v[2:5]
	v_mfma_f32_16x16x32_bf16 v[46:49], v[150:153], v[184:187], v[46:49]
	v_mfma_f32_16x16x32_bf16 v[14:17], v[158:161], v[184:187], v[14:17]
	v_mfma_f32_16x16x32_bf16 v[42:45], v[150:153], v[192:195], v[42:45]
	v_mfma_f32_16x16x32_bf16 v[10:13], v[158:161], v[192:195], v[10:13]
	v_mfma_f32_16x16x32_bf16 v[38:41], v[150:153], v[200:203], v[38:41]
	v_mfma_f32_16x16x32_bf16 v[6:9], v[158:161], v[200:203], v[6:9]
	v_mfma_f32_16x16x32_bf16 v[34:37], v[150:153], v[208:211], v[34:37]
	v_mfma_f32_16x16x32_bf16 v[2:5], v[158:161], v[208:211], v[2:5]
	s_setprio 0
	s_barrier
	s_add_i32 s64, s64, 2
	s_add_u32 s31, s31, 0x100
	s_addc_u32 s63, s63, 0
	s_cmp_gt_u32 s64, 61
	s_mov_b64 s[4:5], s[34:35]
	s_cbranch_scc0 .LBB0_199
	s_and_b64 vcc, exec, s[18:19]
	s_cbranch_vccz .LBB0_203
	s_barrier
	s_sub_i32 s4, s6, 32
	s_cmp_gt_u32 s4, 39
	s_mov_b64 s[4:5], -1
	s_cbranch_scc1 .LBB0_204

; #define PG8_STAGE(bufoff, gbase, voff) do { _Pragma("unroll") for (int _i = 0; _i < 2; ++_i) \
;         __builtin_amdgcn_global_load_lds((const unsigned*)((const char*)(gbase) + (voff)[_i]), (LAS unsigned*)(lds + (bufoff) + ldsw + _i * 8192), 16, 0, 0); } while (0)
; #define PG8_LDA(dst, b, h) do { _Pragma("unroll") for (int m = 0; m < 4; ++m) _Pragma("unroll") for (int k = 0; k < 2; ++k) dst[m][k] = *(const LAS bf16x8*)(lds + PG8_SA(b, h) + aoff + m * 2048 + k * 1024); } while (0)
; #define PG8_LDB(dst, b, h) do { _Pragma("unroll") for (int n = 0; n < 2; ++n) _Pragma("unroll") for (int k = 0; k < 2; ++k) dst[n][k] = *(const LAS bf16x8*)(lds + PG8_SB(b, h) + boff + n * 2048 + k * 1024); } while (0)
; #define PG8_MMA(ai, bj, At, Bt) do { __builtin_amdgcn_s_setprio(1); _Pragma("unroll") for (int m = 0; m < 4; ++m) _Pragma("unroll") for (int n = 0; n < 2; ++n) _Pragma("unroll") for (int k = 0; k < 2; ++k) \
;         acc[ai][bj][m][n] = __builtin_amdgcn_mfma_f32_16x16x32_bf16(Bt[n][k], At[m][k], acc[ai][bj][m][n], 0, 0, 0); __builtin_amdgcn_s_setprio(0); } while (0)
; #define PG8_WAIT_V(n) asm volatile("s_waitcnt vmcnt(" #n ")" ::: "memory")
; #define PG8_WAIT_L(n) asm volatile("s_waitcnt lgkmcnt(" #n ")" ::: "memory")
; #define PG8_BAR __builtin_amdgcn_s_barrier()
; #define PG8_SCHED __builtin_amdgcn_sched_barrier(0)
; template <class Epi, class Sched, bool ALIGN_EPI, class Hook = NoHook>
; __device__ __forceinline__ void gemm_phase(LAS unsigned char* lds, const Gemm g, const Sched& S, const Epi& E, const Hook& H = Hook()) {
;     ...
;             PG8_LDB(B0, 0, 0); PG8_LDB(B1, 0, 1); PG8_SCHED; PG8_LDA(At, 0, 0); PG8_STAGE(PG8_SA(1, 1), a1 + hA, voffA);
;             PG8_WAIT_V(8); PG8_WAIT_L(0); PG8_BAR; PG8_MMA(0, 0, At, B0); PG8_MMA(0, 1, At, B1); PG8_BAR; PG8_SCHED;
;             PG8_LDA(At, 0, 1); PG8_STAGE(PG8_SB(0, 0), b2, voffB); PG8_STAGE(PG8_SB(0, 1), b2 + hB, voffB); PG8_STAGE(PG8_SA(0, 0), a2, voffA);
;             PG8_WAIT_V(8); PG8_WAIT_L(0); PG8_BAR; PG8_MMA(1, 0, At, B0); PG8_MMA(1, 1, At, B1); PG8_BAR; PG8_SCHED;
.LBB0_262:
	ds_read_b128 v[148:151], v145
	ds_read_b128 v[152:155], v145 offset:1024
	ds_read_b128 v[156:159], v145 offset:2048
	ds_read_b128 v[160:163], v145 offset:3072
	ds_read_b128 v[164:167], v146
	ds_read_b128 v[168:171], v146 offset:1024
	ds_read_b128 v[172:175], v146 offset:2048
	ds_read_b128 v[176:179], v146 offset:3072
	s_add_u32 s22, s20, 0xfff00080
	s_addc_u32 s23, s21, -1
	s_cmp_eq_u32 s50, 4
	s_cselect_b32 s25, s11, s23
	s_cselect_b32 s24, s13, s22
	s_cselect_b32 s23, s40, s43
	s_cselect_b32 s22, s41, s42
	s_add_i32 m0, s5, 0xc000
	ds_read_b128 v[180:183], v147
	ds_read_b128 v[184:187], v147 offset:1024
	ds_read_b128 v[188:191], v147 offset:2048
	ds_read_b128 v[192:195], v147 offset:3072
	ds_read_b128 v[196:199], v147 offset:4096
	ds_read_b128 v[200:203], v147 offset:5120
	ds_read_b128 v[204:207], v147 offset:6144
	ds_read_b128 v[208:211], v147 offset:7168
	global_load_lds_dwordx4 v136, s[20:21]
	s_add_i32 m0, s5, 0xe000
	s_nop 0
	global_load_lds_dwordx4 v138, s[20:21]
	s_waitcnt vmcnt(8)
	s_waitcnt lgkmcnt(0)
	s_barrier
	s_setprio 1
	s_waitcnt lgkmcnt(0)
	v_mfma_f32_16x16x32_bf16 v[126:129], v[148:151], v[180:183], v[126:129]
	v_mfma_f32_16x16x32_bf16 v[122:125], v[156:159], v[180:183], v[122:125]
	v_mfma_f32_16x16x32_bf16 v[118:121], v[148:151], v[188:191], v[118:121]
	v_mfma_f32_16x16x32_bf16 v[114:117], v[156:159], v[188:191], v[114:117]
	v_mfma_f32_16x16x32_bf16 v[106:109], v[148:151], v[196:199], v[106:109]
	v_mfma_f32_16x16x32_bf16 v[98:101], v[156:159], v[196:199], v[98:101]
	v_mfma_f32_16x16x32_bf16 v[90:93], v[148:151], v[204:207], v[90:93]
	v_mfma_f32_16x16x32_bf16 v[82:85], v[156:159], v[204:207], v[82:85]
	v_mfma_f32_16x16x32_bf16 v[126:129], v[152:155], v[184:187], v[126:129]
	v_mfma_f32_16x16x32_bf16 v[122:125], v[160:163], v[184:187], v[122:125]
	v_mfma_f32_16x16x32_bf16 v[118:121], v[152:155], v[192:195], v[118:121]
	v_mfma_f32_16x16x32_bf16 v[114:117], v[160:163], v[192:195], v[114:117]
	v_mfma_f32_16x16x32_bf16 v[106:109], v[152:155], v[200:203], v[106:109]
	v_mfma_f32_16x16x32_bf16 v[98:101], v[160:163], v[200:203], v[98:101]
	v_mfma_f32_16x16x32_bf16 v[90:93], v[152:155], v[208:211], v[90:93]
	v_mfma_f32_16x16x32_bf16 v[82:85], v[160:163], v[208:211], v[82:85]
	s_setprio 0
	s_setprio 1
	v_mfma_f32_16x16x32_bf16 v[110:113], v[164:167], v[180:183], v[110:113]
	v_mfma_f32_16x16x32_bf16 v[102:105], v[172:175], v[180:183], v[102:105]
	v_mfma_f32_16x16x32_bf16 v[94:97], v[164:167], v[188:191], v[94:97]
	v_mfma_f32_16x16x32_bf16 v[86:89], v[172:175], v[188:191], v[86:89]
	v_mfma_f32_16x16x32_bf16 v[78:81], v[164:167], v[196:199], v[78:81]
	v_mfma_f32_16x16x32_bf16 v[74:77], v[172:175], v[196:199], v[74:77]
	v_mfma_f32_16x16x32_bf16 v[70:73], v[164:167], v[204:207], v[70:73]
	v_mfma_f32_16x16x32_bf16 v[66:69], v[172:175], v[204:207], v[66:69]
	v_mfma_f32_16x16x32_bf16 v[110:113], v[168:171], v[184:187], v[110:113]
	v_mfma_f32_16x16x32_bf16 v[102:105], v[176:179], v[184:187], v[102:105]
	v_mfma_f32_16x16x32_bf16 v[94:97], v[168:171], v[192:195], v[94:97]
	v_mfma_f32_16x16x32_bf16 v[86:89], v[176:179], v[192:195], v[86:89]
	v_mfma_f32_16x16x32_bf16 v[78:81], v[168:171], v[200:203], v[78:81]
	v_mfma_f32_16x16x32_bf16 v[74:77], v[176:179], v[200:203], v[74:77]
	v_mfma_f32_16x16x32_bf16 v[70:73], v[168:171], v[208:211], v[70:73]
	v_mfma_f32_16x16x32_bf16 v[66:69], v[176:179], v[208:211], v[66:69]
	s_setprio 0
	s_barrier
	s_add_i32 s51, s38, s29
	s_mov_b32 m0, s51
	ds_read_b128 v[180:183], v147 offset:16384
	ds_read_b128 v[184:187], v147 offset:17408
	ds_read_b128 v[188:191], v147 offset:18432
	ds_read_b128 v[192:195], v147 offset:19456
	ds_read_b128 v[196:199], v147 offset:20480
	ds_read_b128 v[200:203], v147 offset:21504
	ds_read_b128 v[204:207], v147 offset:22528
	ds_read_b128 v[208:211], v147 offset:23552
	global_load_lds_dwordx4 v132, s[22:23]
	s_add_i32 m0, s51, 0x2000
	s_add_u32 s52, s22, 0x100000
	s_addc_u32 s53, s23, 0
	s_add_i32 s51, s39, s29
	global_load_lds_dwordx4 v130, s[22:23]
	s_mov_b32 m0, s51
	v_lshl_add_u64 v[220:221], s[24:25], 0, v[130:131]
	global_load_lds_dwordx4 v132, s[52:53]
	s_add_i32 m0, s51, 0x2000
	s_nop 0
	global_load_lds_dwordx4 v130, s[52:53]
	v_lshl_add_u64 v[218:219], s[24:25], 0, v[132:133]
	s_mov_b32 m0, s5
	s_nop 0
	global_load_lds_dwordx4 v132, s[24:25]
	s_mov_b32 m0, s7
	s_nop 0
	global_load_lds_dwordx4 v130, s[24:25]
	s_waitcnt vmcnt(8)
	s_waitcnt lgkmcnt(0)
	s_barrier
	s_setprio 1
	s_waitcnt lgkmcnt(0)
	v_mfma_f32_16x16x32_bf16 v[62:65], v[148:151], v[180:183], v[62:65]
	v_mfma_f32_16x16x32_bf16 v[58:61], v[156:159], v[180:183], v[58:61]
	v_mfma_f32_16x16x32_bf16 v[54:57], v[148:151], v[188:191], v[54:57]
	v_mfma_f32_16x16x32_bf16 v[50:53], v[156:159], v[188:191], v[50:53]
	v_mfma_f32_16x16x32_bf16 v[38:41], v[148:151], v[196:199], v[38:41]
	v_mfma_f32_16x16x32_bf16 v[34:37], v[156:159], v[196:199], v[34:37]
	v_mfma_f32_16x16x32_bf16 v[22:25], v[148:151], v[204:207], v[22:25]
	v_mfma_f32_16x16x32_bf16 v[18:21], v[156:159], v[204:207], v[18:21]
	v_mfma_f32_16x16x32_bf16 v[62:65], v[152:155], v[184:187], v[62:65]
	v_mfma_f32_16x16x32_bf16 v[58:61], v[160:163], v[184:187], v[58:61]
	v_mfma_f32_16x16x32_bf16 v[54:57], v[152:155], v[192:195], v[54:57]
	v_mfma_f32_16x16x32_bf16 v[50:53], v[160:163], v[192:195], v[50:53]
	v_mfma_f32_16x16x32_bf16 v[38:41], v[152:155], v[200:203], v[38:41]
	v_mfma_f32_16x16x32_bf16 v[34:37], v[160:163], v[200:203], v[34:37]
	v_mfma_f32_16x16x32_bf16 v[22:25], v[152:155], v[208:211], v[22:25]
	v_mfma_f32_16x16x32_bf16 v[18:21], v[160:163], v[208:211], v[18:21]
	s_setprio 0
	s_setprio 1
	v_mfma_f32_16x16x32_bf16 v[46:49], v[164:167], v[180:183], v[46:49]
	v_mfma_f32_16x16x32_bf16 v[42:45], v[172:175], v[180:183], v[42:45]
	v_mfma_f32_16x16x32_bf16 v[30:33], v[164:167], v[188:191], v[30:33]
	v_mfma_f32_16x16x32_bf16 v[26:29], v[172:175], v[188:191], v[26:29]
	v_mfma_f32_16x16x32_bf16 v[14:17], v[164:167], v[196:199], v[14:17]
	v_mfma_f32_16x16x32_bf16 v[10:13], v[172:175], v[196:199], v[10:13]
	v_mfma_f32_16x16x32_bf16 v[6:9], v[164:167], v[204:207], v[6:9]
	v_mfma_f32_16x16x32_bf16 v[2:5], v[172:175], v[204:207], v[2:5]
	v_mfma_f32_16x16x32_bf16 v[46:49], v[168:171], v[184:187], v[46:49]
	v_mfma_f32_16x16x32_bf16 v[42:45], v[176:179], v[184:187], v[42:45]
	v_mfma_f32_16x16x32_bf16 v[30:33], v[168:171], v[192:195], v[30:33]
	v_mfma_f32_16x16x32_bf16 v[26:29], v[176:179], v[192:195], v[26:29]
	v_mfma_f32_16x16x32_bf16 v[14:17], v[168:171], v[200:203], v[14:17]
	v_mfma_f32_16x16x32_bf16 v[10:13], v[176:179], v[200:203], v[10:13]
	v_mfma_f32_16x16x32_bf16 v[6:9], v[168:171], v[208:211], v[6:9]
	v_mfma_f32_16x16x32_bf16 v[2:5], v[176:179], v[208:211], v[2:5]
	s_setprio 0
	s_barrier
; #define PG8_STAGE(bufoff, gbase, voff) do { _Pragma("unroll") for (int _i = 0; _i < 2; ++_i) \
;         __builtin_amdgcn_global_load_lds((const unsigned*)((const char*)(gbase) + (voff)[_i]), (LAS unsigned*)(lds + (bufoff) + ldsw + _i * 8192), 16, 0, 0); } while (0)
; #define PG8_LDA(dst, b, h) do { _Pragma("unroll") for (int m = 0; m < 4; ++m) _Pragma("unroll") for (int k = 0; k < 2; ++k) dst[m][k] = *(const LAS bf16x8*)(lds + PG8_SA(b, h) + aoff + m * 2048 + k * 1024); } while (0)
; #define PG8_LDB(dst, b, h) do { _Pragma("unroll") for (int n = 0; n < 2; ++n) _Pragma("unroll") for (int k = 0; k < 2; ++k) dst[n][k] = *(const LAS bf16x8*)(lds + PG8_SB(b, h) + boff + n * 2048 + k * 1024); } while (0)
; #define PG8_MMA(ai, bj, At, Bt) do { __builtin_amdgcn_s_setprio(1); _Pragma("unroll") for (int m = 0; m < 4; ++m) _Pragma("unroll") for (int n = 0; n < 2; ++n) _Pragma("unroll") for (int k = 0; k < 2; ++k) \
;         acc[ai][bj][m][n] = __builtin_amdgcn_mfma_f32_16x16x32_bf16(Bt[n][k], At[m][k], acc[ai][bj][m][n], 0, 0, 0); __builtin_amdgcn_s_setprio(0); } while (0)
; #define PG8_WAIT_V(n) asm volatile("s_waitcnt vmcnt(" #n ")" ::: "memory")
; #define PG8_WAIT_L(n) asm volatile("s_waitcnt lgkmcnt(" #n ")" ::: "memory")
; #define PG8_BAR __builtin_amdgcn_s_barrier()
; #define PG8_SCHED __builtin_amdgcn_sched_barrier(0)
; template <class Epi, class Sched, bool ALIGN_EPI, class Hook = NoHook>
; __device__ __forceinline__ void gemm_phase(LAS unsigned char* lds, const Gemm g, const Sched& S, const Epi& E, const Hook& H = Hook()) {
;     ...
;             PG8_LDB(B0, 1, 0); PG8_LDB(B1, 1, 1); PG8_SCHED; PG8_LDA(At, 1, 0); PG8_STAGE(PG8_SA(0, 1), a2 + hA, voffA);
;             PG8_WAIT_V(8); PG8_WAIT_L(0); PG8_BAR; PG8_MMA(0, 0, At, B0); PG8_MMA(0, 1, At, B1); PG8_BAR; PG8_SCHED;
;             PG8_LDA(At, 1, 1); PG8_STAGE(PG8_SB(1, 0), b3, voffB); PG8_STAGE(PG8_SB(1, 1), b3 + hB, voffB); PG8_STAGE(PG8_SA(1, 0), a3, voffA);
;             PG8_WAIT_V(8); PG8_WAIT_L(0); PG8_BAR; PG8_MMA(1, 0, At, B0); PG8_MMA(1, 1, At, B1); PG8_BAR; PG8_SCHED;
	s_add_i32 s51, 0, 0x18000
	s_add_i32 s52, 0, 0x1c000
	v_add_u32_e32 v160, s51, v144
	v_add_u32_e32 v176, s52, v144
	ds_read_b128 v[148:151], v160
	ds_read_b128 v[152:155], v160 offset:1024
	ds_read_b128 v[156:159], v160 offset:2048
	ds_read_b128 v[160:163], v160 offset:3072
	ds_read_b128 v[164:167], v176
	ds_read_b128 v[168:171], v176 offset:1024
	ds_read_b128 v[172:175], v176 offset:2048
	ds_read_b128 v[176:179], v176 offset:3072
	s_add_u32 s24, s24, 0x100000
	s_addc_u32 s25, s25, 0
	s_mov_b32 m0, s30
	ds_read_b128 v[180:183], v147 offset:32768
	ds_read_b128 v[184:187], v147 offset:33792
	ds_read_b128 v[188:191], v147 offset:34816
	ds_read_b128 v[192:195], v147 offset:35840
	ds_read_b128 v[196:199], v147 offset:36864
	ds_read_b128 v[200:203], v147 offset:37888
	ds_read_b128 v[204:207], v147 offset:38912
	ds_read_b128 v[208:211], v147 offset:39936
	global_load_lds_dwordx4 v132, s[24:25]
	s_mov_b32 m0, s31
	s_nop 0
	global_load_lds_dwordx4 v130, s[24:25]
	s_waitcnt vmcnt(8)
	s_waitcnt lgkmcnt(0)
	s_barrier
	s_setprio 1
	s_waitcnt lgkmcnt(0)
	v_mfma_f32_16x16x32_bf16 v[126:129], v[148:151], v[180:183], v[126:129]
	v_mfma_f32_16x16x32_bf16 v[122:125], v[156:159], v[180:183], v[122:125]
	v_mfma_f32_16x16x32_bf16 v[118:121], v[148:151], v[188:191], v[118:121]
	v_mfma_f32_16x16x32_bf16 v[114:117], v[156:159], v[188:191], v[114:117]
	v_mfma_f32_16x16x32_bf16 v[106:109], v[148:151], v[196:199], v[106:109]
	v_mfma_f32_16x16x32_bf16 v[98:101], v[156:159], v[196:199], v[98:101]
	v_mfma_f32_16x16x32_bf16 v[90:93], v[148:151], v[204:207], v[90:93]
	v_mfma_f32_16x16x32_bf16 v[82:85], v[156:159], v[204:207], v[82:85]
	v_mfma_f32_16x16x32_bf16 v[126:129], v[152:155], v[184:187], v[126:129]
	v_mfma_f32_16x16x32_bf16 v[122:125], v[160:163], v[184:187], v[122:125]
	v_mfma_f32_16x16x32_bf16 v[118:121], v[152:155], v[192:195], v[118:121]
	v_mfma_f32_16x16x32_bf16 v[114:117], v[160:163], v[192:195], v[114:117]
	v_mfma_f32_16x16x32_bf16 v[106:109], v[152:155], v[200:203], v[106:109]
	v_mfma_f32_16x16x32_bf16 v[98:101], v[160:163], v[200:203], v[98:101]
	v_mfma_f32_16x16x32_bf16 v[90:93], v[152:155], v[208:211], v[90:93]
	v_mfma_f32_16x16x32_bf16 v[82:85], v[160:163], v[208:211], v[82:85]
	s_setprio 0
	s_setprio 1
	v_mfma_f32_16x16x32_bf16 v[110:113], v[164:167], v[180:183], v[110:113]
	v_mfma_f32_16x16x32_bf16 v[102:105], v[172:175], v[180:183], v[102:105]
	v_mfma_f32_16x16x32_bf16 v[94:97], v[164:167], v[188:191], v[94:97]
	v_mfma_f32_16x16x32_bf16 v[86:89], v[172:175], v[188:191], v[86:89]
	v_mfma_f32_16x16x32_bf16 v[78:81], v[164:167], v[196:199], v[78:81]
	v_mfma_f32_16x16x32_bf16 v[74:77], v[172:175], v[196:199], v[74:77]
	v_mfma_f32_16x16x32_bf16 v[70:73], v[164:167], v[204:207], v[70:73]
	v_mfma_f32_16x16x32_bf16 v[66:69], v[172:175], v[204:207], v[66:69]
	v_mfma_f32_16x16x32_bf16 v[110:113], v[168:171], v[184:187], v[110:113]
	v_mfma_f32_16x16x32_bf16 v[102:105], v[176:179], v[184:187], v[102:105]
	v_mfma_f32_16x16x32_bf16 v[94:97], v[168:171], v[192:195], v[94:97]
	v_mfma_f32_16x16x32_bf16 v[86:89], v[176:179], v[192:195], v[86:89]
	v_mfma_f32_16x16x32_bf16 v[78:81], v[168:171], v[200:203], v[78:81]
	v_mfma_f32_16x16x32_bf16 v[74:77], v[176:179], v[200:203], v[74:77]
	v_mfma_f32_16x16x32_bf16 v[70:73], v[168:171], v[208:211], v[70:73]
	v_mfma_f32_16x16x32_bf16 v[66:69], v[176:179], v[208:211], v[66:69]
	s_setprio 0
	s_barrier
	s_add_i32 s24, s51, s29
	s_add_u32 s54, s22, s8
	s_addc_u32 s55, s23, s9
	s_mov_b32 m0, s24
	ds_read_b128 v[180:183], v147 offset:49152
	ds_read_b128 v[184:187], v147 offset:50176
	ds_read_b128 v[188:191], v147 offset:51200
	ds_read_b128 v[192:195], v147 offset:52224
	ds_read_b128 v[196:199], v147 offset:53248
	ds_read_b128 v[200:203], v147 offset:54272
	ds_read_b128 v[204:207], v147 offset:55296
	ds_read_b128 v[208:211], v147 offset:56320
	global_load_lds_dwordx4 v132, s[54:55]
	s_add_i32 m0, s24, 0x2000
	s_add_u32 s22, s22, 0x100080
	s_addc_u32 s23, s23, 0
	s_add_i32 s24, s52, s29
	global_load_lds_dwordx4 v130, s[54:55]
	s_mov_b32 m0, s24
	s_nop 0
	global_load_lds_dwordx4 v132, s[22:23]
	s_add_i32 m0, s24, 0x2000
	s_nop 0
	global_load_lds_dwordx4 v130, s[22:23]
	v_lshl_add_u64 v[212:213], v[218:219], 0, s[8:9]
	s_mov_b32 m0, s35
	s_nop 0
	global_load_lds_dwordx4 v[212:213], off
	v_lshl_add_u64 v[212:213], v[220:221], 0, s[8:9]
	s_mov_b32 m0, s36
	s_nop 0
	global_load_lds_dwordx4 v[212:213], off
	s_waitcnt vmcnt(8)
	s_waitcnt lgkmcnt(0)
	s_barrier
; #define PG8_MMA(ai, bj, At, Bt) do { __builtin_amdgcn_s_setprio(1); _Pragma("unroll") for (int m = 0; m < 4; ++m) _Pragma("unroll") for (int n = 0; n < 2; ++n) _Pragma("unroll") for (int k = 0; k < 2; ++k) \
;         acc[ai][bj][m][n] = __builtin_amdgcn_mfma_f32_16x16x32_bf16(Bt[n][k], At[m][k], acc[ai][bj][m][n], 0, 0, 0); __builtin_amdgcn_s_setprio(0); } while (0)
; #define PG8_WAIT_V(n) asm volatile("s_waitcnt vmcnt(" #n ")" ::: "memory")
; #define PG8_WAIT_L(n) asm volatile("s_waitcnt lgkmcnt(" #n ")" ::: "memory")
; #define PG8_BAR __builtin_amdgcn_s_barrier()
; #define PG8_SCHED __builtin_amdgcn_sched_barrier(0)
;     __device__ __forceinline__ void operator()(const f32x4 (&acc)[2][2][4][2], const Unit& u, int wr, int wc, int fr, int fq) const {
;         float* base = C + (size_t)(u.ka / kslab) * slab_stride;
;         const int row0 = u.pm * BM + wr * 64 + fr, col0 = wc * 32 + 4 * fq;
; #pragma unroll
;         for (int ai = 0; ai < 2; ++ai)
; #pragma unroll
;             for (int m = 0; m < 4; ++m) { float* rowp = base + (size_t)(row0 + ai * HALF + m * 16) * 256 + col0;
; #pragma unroll
;                 for (int bj = 0; bj < 2; ++bj)
; #pragma unroll
;                     for (int n = 0; n < 2; ++n) *(f32x4*)(rowp + bj * HALF + n * 16) = acc[ai][bj][m][n]; }
;     }
; template <class Epi, class Sched, bool ALIGN_EPI, class Hook = NoHook>
; __device__ __forceinline__ void gemm_phase(LAS unsigned char* lds, const Gemm g, const Sched& S, const Epi& E, const Hook& H = Hook()) {
;     ...
;             PG8_WAIT_V(8); PG8_WAIT_L(0); PG8_BAR; PG8_MMA(1, 0, At, B0); PG8_MMA(1, 1, At, B1); PG8_BAR; PG8_SCHED;
;     ...
;     PG8_WAIT_V(0);
;     if constexpr (!ALIGN_EPI) { if (wr == 0) PG8_BAR; }
	s_setprio 1
	s_waitcnt lgkmcnt(0)
	v_mfma_f32_16x16x32_bf16 v[62:65], v[148:151], v[180:183], v[62:65]
	v_mfma_f32_16x16x32_bf16 v[58:61], v[156:159], v[180:183], v[58:61]
	v_mfma_f32_16x16x32_bf16 v[54:57], v[148:151], v[188:191], v[54:57]
	v_mfma_f32_16x16x32_bf16 v[50:53], v[156:159], v[188:191], v[50:53]
	v_mfma_f32_16x16x32_bf16 v[38:41], v[148:151], v[196:199], v[38:41]
	v_mfma_f32_16x16x32_bf16 v[34:37], v[156:159], v[196:199], v[34:37]
	v_mfma_f32_16x16x32_bf16 v[22:25], v[148:151], v[204:207], v[22:25]
	v_mfma_f32_16x16x32_bf16 v[18:21], v[156:159], v[204:207], v[18:21]
	v_mfma_f32_16x16x32_bf16 v[62:65], v[152:155], v[184:187], v[62:65]
	v_mfma_f32_16x16x32_bf16 v[58:61], v[160:163], v[184:187], v[58:61]
	v_mfma_f32_16x16x32_bf16 v[54:57], v[152:155], v[192:195], v[54:57]
	v_mfma_f32_16x16x32_bf16 v[50:53], v[160:163], v[192:195], v[50:53]
	v_mfma_f32_16x16x32_bf16 v[38:41], v[152:155], v[200:203], v[38:41]
	v_mfma_f32_16x16x32_bf16 v[34:37], v[160:163], v[200:203], v[34:37]
	v_mfma_f32_16x16x32_bf16 v[22:25], v[152:155], v[208:211], v[22:25]
	v_mfma_f32_16x16x32_bf16 v[18:21], v[160:163], v[208:211], v[18:21]
	s_setprio 0
	s_setprio 1
	v_mfma_f32_16x16x32_bf16 v[46:49], v[164:167], v[180:183], v[46:49]
	v_mfma_f32_16x16x32_bf16 v[42:45], v[172:175], v[180:183], v[42:45]
	v_mfma_f32_16x16x32_bf16 v[30:33], v[164:167], v[188:191], v[30:33]
	v_mfma_f32_16x16x32_bf16 v[26:29], v[172:175], v[188:191], v[26:29]
	v_mfma_f32_16x16x32_bf16 v[14:17], v[164:167], v[196:199], v[14:17]
	v_mfma_f32_16x16x32_bf16 v[10:13], v[172:175], v[196:199], v[10:13]
	v_mfma_f32_16x16x32_bf16 v[6:9], v[164:167], v[204:207], v[6:9]
	v_mfma_f32_16x16x32_bf16 v[2:5], v[172:175], v[204:207], v[2:5]
	v_mfma_f32_16x16x32_bf16 v[46:49], v[168:171], v[184:187], v[46:49]
	v_mfma_f32_16x16x32_bf16 v[42:45], v[176:179], v[184:187], v[42:45]
	v_mfma_f32_16x16x32_bf16 v[30:33], v[168:171], v[192:195], v[30:33]
	v_mfma_f32_16x16x32_bf16 v[26:29], v[176:179], v[192:195], v[26:29]
	v_mfma_f32_16x16x32_bf16 v[14:17], v[168:171], v[200:203], v[14:17]
	v_mfma_f32_16x16x32_bf16 v[10:13], v[176:179], v[200:203], v[10:13]
	v_mfma_f32_16x16x32_bf16 v[6:9], v[168:171], v[208:211], v[6:9]
	v_mfma_f32_16x16x32_bf16 v[2:5], v[176:179], v[208:211], v[2:5]
	s_setprio 0
	s_barrier
	s_add_i32 s50, s50, 2
	s_add_u32 s20, s20, 0x100
	s_addc_u32 s21, s21, 0
	s_add_u32 s42, s42, 0x100
	s_addc_u32 s43, s43, 0
	s_cmp_gt_u32 s50, 5
	s_cbranch_scc0 .LBB0_262
	s_ashr_i32 s11, s6, 31
	s_lshr_b32 s11, s11, 23
	s_add_i32 s6, s6, s11
	s_ashr_i32 s20, s6, 9
	s_ashr_i32 s21, s20, 31
	v_lshl_add_u32 v148, s4, 8, v1
	s_lshl_b64 s[20:21], s[20:21], 23
	v_ashrrev_i32_e32 v149, 31, v148
	v_lshl_add_u64 v[150:151], v[134:135], 0, s[20:21]
	v_lshlrev_b64 v[152:153], 10, v[148:149]
	v_lshl_add_u64 v[152:153], v[150:151], 0, v[152:153]
	global_store_dwordx4 v[152:153], v[126:129], off
	global_store_dwordx4 v[152:153], v[122:125], off offset:64
	global_store_dwordx4 v[152:153], v[110:113], off offset:512
	global_store_dwordx4 v[152:153], v[102:105], off offset:576
	s_mov_b32 s4, 0x20000
	s_mov_b64 s[20:21], 0x20000
	v_or_b32_e32 v102, 16, v148
	v_ashrrev_i32_e32 v103, 31, v102
	v_lshlrev_b64 v[102:103], 10, v[102:103]
	v_lshl_add_u64 v[102:103], v[150:151], 0, v[102:103]
	global_store_dwordx4 v[102:103], v[118:121], off
	global_store_dwordx4 v[102:103], v[114:117], off offset:64
	global_store_dwordx4 v[102:103], v[94:97], off offset:512
	global_store_dwordx4 v[102:103], v[86:89], off offset:576
	s_mov_b32 s6, s12
	s_mov_b64 s[22:23], s[18:19]
	v_or_b32_e32 v86, 32, v148
	v_ashrrev_i32_e32 v87, 31, v86
	v_lshlrev_b64 v[86:87], 10, v[86:87]
	v_lshl_add_u64 v[86:87], v[150:151], 0, v[86:87]
	global_store_dwordx4 v[86:87], v[106:109], off
	global_store_dwordx4 v[86:87], v[98:101], off offset:64
	global_store_dwordx4 v[86:87], v[78:81], off offset:512
	global_store_dwordx4 v[86:87], v[74:77], off offset:576
	s_nop 1
	v_or_b32_e32 v74, 48, v148
	v_ashrrev_i32_e32 v75, 31, v74
	v_lshlrev_b64 v[74:75], 10, v[74:75]
	v_lshl_add_u64 v[74:75], v[150:151], 0, v[74:75]
	global_store_dwordx4 v[74:75], v[90:93], off
	global_store_dwordx4 v[74:75], v[82:85], off offset:64
	global_store_dwordx4 v[74:75], v[70:73], off offset:512
	global_store_dwordx4 v[74:75], v[66:69], off offset:576
	s_nop 1
	v_add_co_u32_e32 v68, vcc, s4, v152
	s_mov_b32 s4, 0x24000
	s_nop 0
	v_addc_co_u32_e32 v69, vcc, 0, v153, vcc
	v_lshl_add_u64 v[66:67], v[152:153], 0, s[20:21]
	global_store_dwordx4 v[68:69], v[62:65], off
	global_store_dwordx4 v[66:67], v[58:61], off offset:64
	global_store_dwordx4 v[66:67], v[46:49], off offset:512
	global_store_dwordx4 v[66:67], v[42:45], off offset:576
	s_mov_b64 s[20:21], 0x24000
	s_nop 0
	v_add_co_u32_e32 v44, vcc, s4, v152
	s_mov_b32 s4, 0x28000
	s_nop 0
	v_addc_co_u32_e32 v45, vcc, 0, v153, vcc
	v_lshl_add_u64 v[42:43], v[152:153], 0, s[20:21]
	global_store_dwordx4 v[44:45], v[54:57], off
	global_store_dwordx4 v[42:43], v[50:53], off offset:64
	global_store_dwordx4 v[42:43], v[30:33], off offset:512
	global_store_dwordx4 v[42:43], v[26:29], off offset:576
	s_mov_b64 s[20:21], 0x28000
	s_nop 0
	v_add_co_u32_e32 v28, vcc, s4, v152
	v_lshl_add_u64 v[26:27], v[152:153], 0, s[20:21]
	s_nop 0
	v_addc_co_u32_e32 v29, vcc, 0, v153, vcc
	global_store_dwordx4 v[28:29], v[38:41], off
	global_store_dwordx4 v[26:27], v[34:37], off offset:64
	global_store_dwordx4 v[26:27], v[14:17], off offset:512
	global_store_dwordx4 v[26:27], v[10:13], off offset:576
	s_mov_b64 s[20:21], 0x2c000
	s_mov_b32 s4, s10
	v_add_co_u32_e32 v12, vcc, 0x2c000, v152
	v_lshl_add_u64 v[10:11], v[152:153], 0, s[20:21]
	s_nop 0
	v_addc_co_u32_e32 v13, vcc, 0, v153, vcc
	s_and_b64 vcc, exec, s[2:3]
	s_mov_b64 s[20:21], s[14:15]
	global_store_dwordx4 v[12:13], v[22:25], off
	global_store_dwordx4 v[10:11], v[18:21], off offset:64
	global_store_dwordx4 v[10:11], v[6:9], off offset:512
	global_store_dwordx4 v[10:11], v[2:5], off offset:576
	s_cbranch_vccz .LBB0_259
	s_waitcnt vmcnt(0)
	s_cmpk_gt_u32 s26, 0xff
	s_cbranch_scc1 .LBB0_266
	s_barrier

; #define PG8_STAGE(bufoff, gbase, voff) do { _Pragma("unroll") for (int _i = 0; _i < 2; ++_i) \
;         __builtin_amdgcn_global_load_lds((const unsigned*)((const char*)(gbase) + (voff)[_i]), (LAS unsigned*)(lds + (bufoff) + ldsw + _i * 8192), 16, 0, 0); } while (0)
; #define PG8_LDA(dst, b, h) do { _Pragma("unroll") for (int m = 0; m < 4; ++m) _Pragma("unroll") for (int k = 0; k < 2; ++k) dst[m][k] = *(const LAS bf16x8*)(lds + PG8_SA(b, h) + aoff + m * 2048 + k * 1024); } while (0)
; #define PG8_LDB(dst, b, h) do { _Pragma("unroll") for (int n = 0; n < 2; ++n) _Pragma("unroll") for (int k = 0; k < 2; ++k) dst[n][k] = *(const LAS bf16x8*)(lds + PG8_SB(b, h) + boff + n * 2048 + k * 1024); } while (0)
; #define PG8_MMA(ai, bj, At, Bt) do { __builtin_amdgcn_s_setprio(1); _Pragma("unroll") for (int m = 0; m < 4; ++m) _Pragma("unroll") for (int n = 0; n < 2; ++n) _Pragma("unroll") for (int k = 0; k < 2; ++k) \
;         acc[ai][bj][m][n] = __builtin_amdgcn_mfma_f32_16x16x32_bf16(Bt[n][k], At[m][k], acc[ai][bj][m][n], 0, 0, 0); __builtin_amdgcn_s_setprio(0); } while (0)
; #define PG8_WAIT_V(n) asm volatile("s_waitcnt vmcnt(" #n ")" ::: "memory")
; #define PG8_WAIT_L(n) asm volatile("s_waitcnt lgkmcnt(" #n ")" ::: "memory")
; #define PG8_BAR __builtin_amdgcn_s_barrier()
; #define PG8_SCHED __builtin_amdgcn_sched_barrier(0)
; template <class Epi, class Sched, bool ALIGN_EPI, class Hook = NoHook>
; __device__ __forceinline__ void gemm_phase(LAS unsigned char* lds, const Gemm g, const Sched& S, const Epi& E, const Hook& H = Hook()) {
;     ...
;             PG8_LDB(B0, 0, 0); PG8_LDB(B1, 0, 1); PG8_SCHED; PG8_LDA(At, 0, 0); PG8_STAGE(PG8_SA(1, 1), a1 + hA, voffA);
;             PG8_WAIT_V(8); PG8_WAIT_L(0); PG8_BAR; PG8_MMA(0, 0, At, B0); PG8_MMA(0, 1, At, B1); PG8_BAR; PG8_SCHED;
;             PG8_LDA(At, 0, 1); PG8_STAGE(PG8_SB(0, 0), b2, voffB); PG8_STAGE(PG8_SB(0, 1), b2 + hB, voffB); PG8_STAGE(PG8_SA(0, 0), a2, voffA);
;             PG8_WAIT_V(8); PG8_WAIT_L(0); PG8_BAR; PG8_MMA(1, 0, At, B0); PG8_MMA(1, 1, At, B1); PG8_BAR; PG8_SCHED;
.LBB0_783:
	v_add_u32_e32 v3, s56, v222
	s_add_i32 s67, s67, 2
	ds_read_b128 v[126:129], v3
	ds_read_b128 v[130:133], v3 offset:1024
	ds_read_b128 v[142:145], v3 offset:2048
	ds_read_b128 v[146:149], v3 offset:3072
	v_add_u32_e32 v3, s57, v222
	s_add_u32 s28, s22, s26
	ds_read_b128 v[150:153], v3
	ds_read_b128 v[154:157], v3 offset:1024
	ds_read_b128 v[158:161], v3 offset:2048
	ds_read_b128 v[162:165], v3 offset:3072
	s_addc_u32 s29, s23, s27
	s_add_u32 s28, s28, 0x100
	s_addc_u32 s29, s29, 0
	s_add_u32 s68, s63, s26
	s_addc_u32 s69, s64, s27
	s_cmpk_eq_i32 s26, 0x5f00
	s_cselect_b32 s31, s5, s29
	s_cselect_b32 s30, s4, s28
	s_cselect_b32 s29, s21, s69
	s_cselect_b32 s28, s20, s68
	v_lshl_add_u64 v[4:5], v[182:183], 0, s[26:27]
	s_add_i32 m0, s37, 0xc000
	ds_read_b128 v[186:189], v224
	ds_read_b128 v[190:193], v224 offset:1024
	ds_read_b128 v[194:197], v224 offset:2048
	ds_read_b128 v[198:201], v224 offset:3072
	ds_read_b128 v[202:205], v224 offset:4096
	ds_read_b128 v[206:209], v224 offset:5120
	ds_read_b128 v[210:213], v224 offset:6144
	ds_read_b128 v[214:217], v224 offset:7168
	global_load_lds_dwordx4 v[4:5], off
	v_lshl_add_u64 v[4:5], v[184:185], 0, s[26:27]
	s_add_i32 m0, s37, 0xe000
	s_nop 0
	global_load_lds_dwordx4 v[4:5], off
	s_waitcnt vmcnt(8)
	s_waitcnt lgkmcnt(0)
	s_barrier
	s_setprio 1
	s_waitcnt lgkmcnt(0)
	v_mfma_f32_16x16x32_bf16 v[138:141], v[126:129], v[186:189], v[138:141]
	v_mfma_f32_16x16x32_bf16 v[134:137], v[142:145], v[186:189], v[134:137]
	v_mfma_f32_16x16x32_bf16 v[122:125], v[126:129], v[194:197], v[122:125]
	v_mfma_f32_16x16x32_bf16 v[118:121], v[142:145], v[194:197], v[118:121]
	v_mfma_f32_16x16x32_bf16 v[114:117], v[126:129], v[202:205], v[114:117]
	v_mfma_f32_16x16x32_bf16 v[110:113], v[142:145], v[202:205], v[110:113]
	v_mfma_f32_16x16x32_bf16 v[106:109], v[126:129], v[210:213], v[106:109]
	v_mfma_f32_16x16x32_bf16 v[102:105], v[142:145], v[210:213], v[102:105]
	v_mfma_f32_16x16x32_bf16 v[138:141], v[130:133], v[190:193], v[138:141]
	v_mfma_f32_16x16x32_bf16 v[134:137], v[146:149], v[190:193], v[134:137]
	v_mfma_f32_16x16x32_bf16 v[122:125], v[130:133], v[198:201], v[122:125]
	v_mfma_f32_16x16x32_bf16 v[118:121], v[146:149], v[198:201], v[118:121]
	v_mfma_f32_16x16x32_bf16 v[114:117], v[130:133], v[206:209], v[114:117]
	v_mfma_f32_16x16x32_bf16 v[110:113], v[146:149], v[206:209], v[110:113]
	v_mfma_f32_16x16x32_bf16 v[106:109], v[130:133], v[214:217], v[106:109]
	v_mfma_f32_16x16x32_bf16 v[102:105], v[146:149], v[214:217], v[102:105]
	s_setprio 0
	s_setprio 1
	v_mfma_f32_16x16x32_bf16 v[66:69], v[150:153], v[186:189], v[66:69]
	v_mfma_f32_16x16x32_bf16 v[62:65], v[158:161], v[186:189], v[62:65]
	v_mfma_f32_16x16x32_bf16 v[58:61], v[150:153], v[194:197], v[58:61]
	v_mfma_f32_16x16x32_bf16 v[54:57], v[158:161], v[194:197], v[54:57]
	v_mfma_f32_16x16x32_bf16 v[50:53], v[150:153], v[202:205], v[50:53]
	v_mfma_f32_16x16x32_bf16 v[46:49], v[158:161], v[202:205], v[46:49]
	v_mfma_f32_16x16x32_bf16 v[42:45], v[150:153], v[210:213], v[42:45]
	v_mfma_f32_16x16x32_bf16 v[38:41], v[158:161], v[210:213], v[38:41]
	v_mfma_f32_16x16x32_bf16 v[66:69], v[154:157], v[190:193], v[66:69]
	v_mfma_f32_16x16x32_bf16 v[62:65], v[162:165], v[190:193], v[62:65]
	v_mfma_f32_16x16x32_bf16 v[58:61], v[154:157], v[198:201], v[58:61]
	v_mfma_f32_16x16x32_bf16 v[54:57], v[162:165], v[198:201], v[54:57]
	v_mfma_f32_16x16x32_bf16 v[50:53], v[154:157], v[206:209], v[50:53]
	v_mfma_f32_16x16x32_bf16 v[46:49], v[162:165], v[206:209], v[46:49]
	v_mfma_f32_16x16x32_bf16 v[42:45], v[154:157], v[214:217], v[42:45]
	v_mfma_f32_16x16x32_bf16 v[38:41], v[162:165], v[214:217], v[38:41]
	s_setprio 0
	s_barrier
	s_add_i32 s68, s56, s35
	s_mov_b32 m0, s68
	ds_read_b128 v[186:189], v224 offset:16384
	ds_read_b128 v[190:193], v224 offset:17408
	ds_read_b128 v[194:197], v224 offset:18432
	ds_read_b128 v[198:201], v224 offset:19456
	ds_read_b128 v[202:205], v224 offset:20480
	ds_read_b128 v[206:209], v224 offset:21504
	ds_read_b128 v[210:213], v224 offset:22528
	ds_read_b128 v[214:217], v224 offset:23552
	global_load_lds_dwordx4 v168, s[28:29]
	s_add_i32 m0, s68, 0x2000
	s_add_u32 s68, s28, 0x300000
	s_addc_u32 s69, s29, 0
	s_add_i32 s70, s57, s35
	global_load_lds_dwordx4 v172, s[28:29]
	s_mov_b32 m0, s70
	v_lshl_add_u64 v[230:231], s[30:31], 0, v[166:167]
	global_load_lds_dwordx4 v168, s[68:69]
	s_add_i32 m0, s70, 0x2000
	v_lshl_add_u64 v[232:233], s[30:31], 0, v[170:171]
	global_load_lds_dwordx4 v172, s[68:69]
	s_mov_b32 m0, s37
	s_nop 0
	global_load_lds_dwordx4 v166, s[30:31]
	s_mov_b32 m0, s38
	s_nop 0
	global_load_lds_dwordx4 v170, s[30:31]
	s_waitcnt vmcnt(8)
	s_waitcnt lgkmcnt(0)
	s_barrier
; #define PG8_STAGE(bufoff, gbase, voff) do { _Pragma("unroll") for (int _i = 0; _i < 2; ++_i) \
;         __builtin_amdgcn_global_load_lds((const unsigned*)((const char*)(gbase) + (voff)[_i]), (LAS unsigned*)(lds + (bufoff) + ldsw + _i * 8192), 16, 0, 0); } while (0)
; #define PG8_LDA(dst, b, h) do { _Pragma("unroll") for (int m = 0; m < 4; ++m) _Pragma("unroll") for (int k = 0; k < 2; ++k) dst[m][k] = *(const LAS bf16x8*)(lds + PG8_SA(b, h) + aoff + m * 2048 + k * 1024); } while (0)
; #define PG8_LDB(dst, b, h) do { _Pragma("unroll") for (int n = 0; n < 2; ++n) _Pragma("unroll") for (int k = 0; k < 2; ++k) dst[n][k] = *(const LAS bf16x8*)(lds + PG8_SB(b, h) + boff + n * 2048 + k * 1024); } while (0)
; #define PG8_MMA(ai, bj, At, Bt) do { __builtin_amdgcn_s_setprio(1); _Pragma("unroll") for (int m = 0; m < 4; ++m) _Pragma("unroll") for (int n = 0; n < 2; ++n) _Pragma("unroll") for (int k = 0; k < 2; ++k) \
;         acc[ai][bj][m][n] = __builtin_amdgcn_mfma_f32_16x16x32_bf16(Bt[n][k], At[m][k], acc[ai][bj][m][n], 0, 0, 0); __builtin_amdgcn_s_setprio(0); } while (0)
; #define PG8_WAIT_V(n) asm volatile("s_waitcnt vmcnt(" #n ")" ::: "memory")
; #define PG8_WAIT_L(n) asm volatile("s_waitcnt lgkmcnt(" #n ")" ::: "memory")
; #define PG8_BAR __builtin_amdgcn_s_barrier()
; #define PG8_SCHED __builtin_amdgcn_sched_barrier(0)
; template <class Epi, class Sched, bool ALIGN_EPI, class Hook = NoHook>
; __device__ __forceinline__ void gemm_phase(LAS unsigned char* lds, const Gemm g, const Sched& S, const Epi& E, const Hook& H = Hook()) {
;     ...
;             PG8_LDB(B0, 1, 0); PG8_LDB(B1, 1, 1); PG8_SCHED; PG8_LDA(At, 1, 0); PG8_STAGE(PG8_SA(0, 1), a2 + hA, voffA);
;             PG8_WAIT_V(8); PG8_WAIT_L(0); PG8_BAR; PG8_MMA(0, 0, At, B0); PG8_MMA(0, 1, At, B1); PG8_BAR; PG8_SCHED;
	s_setprio 1
	s_waitcnt lgkmcnt(0)
	v_mfma_f32_16x16x32_bf16 v[98:101], v[126:129], v[186:189], v[98:101]
	v_mfma_f32_16x16x32_bf16 v[94:97], v[142:145], v[186:189], v[94:97]
	v_mfma_f32_16x16x32_bf16 v[90:93], v[126:129], v[194:197], v[90:93]
	v_mfma_f32_16x16x32_bf16 v[86:89], v[142:145], v[194:197], v[86:89]
	v_mfma_f32_16x16x32_bf16 v[82:85], v[126:129], v[202:205], v[82:85]
	v_mfma_f32_16x16x32_bf16 v[78:81], v[142:145], v[202:205], v[78:81]
	v_mfma_f32_16x16x32_bf16 v[74:77], v[126:129], v[210:213], v[74:77]
	v_mfma_f32_16x16x32_bf16 v[70:73], v[142:145], v[210:213], v[70:73]
	v_mfma_f32_16x16x32_bf16 v[98:101], v[130:133], v[190:193], v[98:101]
	v_mfma_f32_16x16x32_bf16 v[94:97], v[146:149], v[190:193], v[94:97]
	v_mfma_f32_16x16x32_bf16 v[90:93], v[130:133], v[198:201], v[90:93]
	v_mfma_f32_16x16x32_bf16 v[86:89], v[146:149], v[198:201], v[86:89]
	v_mfma_f32_16x16x32_bf16 v[82:85], v[130:133], v[206:209], v[82:85]
	v_mfma_f32_16x16x32_bf16 v[78:81], v[146:149], v[206:209], v[78:81]
	v_mfma_f32_16x16x32_bf16 v[74:77], v[130:133], v[214:217], v[74:77]
	v_mfma_f32_16x16x32_bf16 v[70:73], v[146:149], v[214:217], v[70:73]
	s_setprio 0
	s_setprio 1
	v_mfma_f32_16x16x32_bf16 v[34:37], v[150:153], v[186:189], v[34:37]
	v_mfma_f32_16x16x32_bf16 v[30:33], v[158:161], v[186:189], v[30:33]
	v_mfma_f32_16x16x32_bf16 v[26:29], v[150:153], v[194:197], v[26:29]
	v_mfma_f32_16x16x32_bf16 v[22:25], v[158:161], v[194:197], v[22:25]
	v_mfma_f32_16x16x32_bf16 v[18:21], v[150:153], v[202:205], v[18:21]
	v_mfma_f32_16x16x32_bf16 v[14:17], v[158:161], v[202:205], v[14:17]
	v_mfma_f32_16x16x32_bf16 v[10:13], v[150:153], v[210:213], v[10:13]
	v_mfma_f32_16x16x32_bf16 v[4:7], v[158:161], v[210:213], v[6:9]
	v_mfma_f32_16x16x32_bf16 v[34:37], v[154:157], v[190:193], v[34:37]
	v_mfma_f32_16x16x32_bf16 v[30:33], v[162:165], v[190:193], v[30:33]
	v_mfma_f32_16x16x32_bf16 v[26:29], v[154:157], v[198:201], v[26:29]
	v_mfma_f32_16x16x32_bf16 v[22:25], v[162:165], v[198:201], v[22:25]
	v_mfma_f32_16x16x32_bf16 v[18:21], v[154:157], v[206:209], v[18:21]
	v_mfma_f32_16x16x32_bf16 v[14:17], v[162:165], v[206:209], v[14:17]
	v_mfma_f32_16x16x32_bf16 v[10:13], v[154:157], v[214:217], v[10:13]
	v_mfma_f32_16x16x32_bf16 v[4:7], v[162:165], v[214:217], v[4:7]
	s_setprio 0
	s_barrier
	s_add_i32 s68, 0, 0x18000
	v_add_u32_e32 v3, s68, v222
	s_add_i32 s69, 0, 0x1c000
	ds_read_b128 v[126:129], v3
	ds_read_b128 v[130:133], v3 offset:1024
	ds_read_b128 v[142:145], v3 offset:2048
	ds_read_b128 v[146:149], v3 offset:3072
	v_add_u32_e32 v3, s69, v222
	ds_read_b128 v[150:153], v3
	ds_read_b128 v[154:157], v3 offset:1024
	ds_read_b128 v[158:161], v3 offset:2048
	ds_read_b128 v[162:165], v3 offset:3072
	s_add_u32 s30, s30, 0x300000
	s_addc_u32 s31, s31, 0
	s_mov_b32 m0, s39
	ds_read_b128 v[186:189], v224 offset:32768
	ds_read_b128 v[190:193], v224 offset:33792
	ds_read_b128 v[194:197], v224 offset:34816
	ds_read_b128 v[198:201], v224 offset:35840
	ds_read_b128 v[202:205], v224 offset:36864
	ds_read_b128 v[206:209], v224 offset:37888
	ds_read_b128 v[210:213], v224 offset:38912
	ds_read_b128 v[214:217], v224 offset:39936
	global_load_lds_dwordx4 v166, s[30:31]
	s_mov_b32 m0, s40
	s_nop 0
	global_load_lds_dwordx4 v170, s[30:31]
	s_waitcnt vmcnt(8)
	s_waitcnt lgkmcnt(0)
	s_barrier
	s_setprio 1
	s_waitcnt lgkmcnt(0)
	v_mfma_f32_16x16x32_bf16 v[138:141], v[126:129], v[186:189], v[138:141]
	v_mfma_f32_16x16x32_bf16 v[134:137], v[142:145], v[186:189], v[134:137]
	v_mfma_f32_16x16x32_bf16 v[122:125], v[126:129], v[194:197], v[122:125]
	v_mfma_f32_16x16x32_bf16 v[118:121], v[142:145], v[194:197], v[118:121]
	v_mfma_f32_16x16x32_bf16 v[114:117], v[126:129], v[202:205], v[114:117]
	v_mfma_f32_16x16x32_bf16 v[110:113], v[142:145], v[202:205], v[110:113]
	v_mfma_f32_16x16x32_bf16 v[106:109], v[126:129], v[210:213], v[106:109]
	v_mfma_f32_16x16x32_bf16 v[102:105], v[142:145], v[210:213], v[102:105]
	v_mfma_f32_16x16x32_bf16 v[138:141], v[130:133], v[190:193], v[138:141]
	v_mfma_f32_16x16x32_bf16 v[134:137], v[146:149], v[190:193], v[134:137]
	v_mfma_f32_16x16x32_bf16 v[122:125], v[130:133], v[198:201], v[122:125]
	v_mfma_f32_16x16x32_bf16 v[118:121], v[146:149], v[198:201], v[118:121]
	v_mfma_f32_16x16x32_bf16 v[114:117], v[130:133], v[206:209], v[114:117]
	v_mfma_f32_16x16x32_bf16 v[110:113], v[146:149], v[206:209], v[110:113]
	v_mfma_f32_16x16x32_bf16 v[106:109], v[130:133], v[214:217], v[106:109]
	v_mfma_f32_16x16x32_bf16 v[102:105], v[146:149], v[214:217], v[102:105]
	s_setprio 0
	s_setprio 1
	v_mfma_f32_16x16x32_bf16 v[66:69], v[150:153], v[186:189], v[66:69]
	v_mfma_f32_16x16x32_bf16 v[62:65], v[158:161], v[186:189], v[62:65]
	v_mfma_f32_16x16x32_bf16 v[58:61], v[150:153], v[194:197], v[58:61]
	v_mfma_f32_16x16x32_bf16 v[54:57], v[158:161], v[194:197], v[54:57]
	v_mfma_f32_16x16x32_bf16 v[50:53], v[150:153], v[202:205], v[50:53]
	v_mfma_f32_16x16x32_bf16 v[46:49], v[158:161], v[202:205], v[46:49]
	v_mfma_f32_16x16x32_bf16 v[42:45], v[150:153], v[210:213], v[42:45]
	v_mfma_f32_16x16x32_bf16 v[38:41], v[158:161], v[210:213], v[38:41]
	v_mfma_f32_16x16x32_bf16 v[66:69], v[154:157], v[190:193], v[66:69]
	v_mfma_f32_16x16x32_bf16 v[62:65], v[162:165], v[190:193], v[62:65]
	v_mfma_f32_16x16x32_bf16 v[58:61], v[154:157], v[198:201], v[58:61]
	v_mfma_f32_16x16x32_bf16 v[54:57], v[162:165], v[198:201], v[54:57]
	v_mfma_f32_16x16x32_bf16 v[50:53], v[154:157], v[206:209], v[50:53]
	v_mfma_f32_16x16x32_bf16 v[46:49], v[162:165], v[206:209], v[46:49]
	v_mfma_f32_16x16x32_bf16 v[42:45], v[154:157], v[214:217], v[42:45]
	v_mfma_f32_16x16x32_bf16 v[38:41], v[162:165], v[214:217], v[38:41]
	s_setprio 0
	s_barrier
; #define PG8_STAGE(bufoff, gbase, voff) do { _Pragma("unroll") for (int _i = 0; _i < 2; ++_i) \
;         __builtin_amdgcn_global_load_lds((const unsigned*)((const char*)(gbase) + (voff)[_i]), (LAS unsigned*)(lds + (bufoff) + ldsw + _i * 8192), 16, 0, 0); } while (0)
; #define PG8_LDA(dst, b, h) do { _Pragma("unroll") for (int m = 0; m < 4; ++m) _Pragma("unroll") for (int k = 0; k < 2; ++k) dst[m][k] = *(const LAS bf16x8*)(lds + PG8_SA(b, h) + aoff + m * 2048 + k * 1024); } while (0)
; #define PG8_MMA(ai, bj, At, Bt) do { __builtin_amdgcn_s_setprio(1); _Pragma("unroll") for (int m = 0; m < 4; ++m) _Pragma("unroll") for (int n = 0; n < 2; ++n) _Pragma("unroll") for (int k = 0; k < 2; ++k) \
;         acc[ai][bj][m][n] = __builtin_amdgcn_mfma_f32_16x16x32_bf16(Bt[n][k], At[m][k], acc[ai][bj][m][n], 0, 0, 0); __builtin_amdgcn_s_setprio(0); } while (0)
; #define PG8_WAIT_V(n) asm volatile("s_waitcnt vmcnt(" #n ")" ::: "memory")
; #define PG8_WAIT_L(n) asm volatile("s_waitcnt lgkmcnt(" #n ")" ::: "memory")
; #define PG8_BAR __builtin_amdgcn_s_barrier()
; #define PG8_SCHED __builtin_amdgcn_sched_barrier(0)
;     __device__ __forceinline__ void after(int te, f32x4 (&acc)[2][2][4][2], const Unit& u, int wr, int wc, int fr, int fq) const {
;         if (te > D_INNER / BK) return;
;         const int g = (te >> 4) - 1;
;         asm volatile("" : "+v"(fr), "+v"(fq));
; #pragma unroll
;         for (int ai = 0; ai < 2; ++ai)
; #pragma unroll
;             for (int m = 0; m < 4; ++m) { const float f = tab[(ai * HALF + wr * 64 + m * 16 + fr) * 8 + g];
; template <class Epi, class Sched, bool ALIGN_EPI, class Hook = NoHook>
; __device__ __forceinline__ void gemm_phase(LAS unsigned char* lds, const Gemm g, const Sched& S, const Epi& E, const Hook& H = Hook()) {
;     ...
;             PG8_LDA(At, 1, 1); PG8_STAGE(PG8_SB(1, 0), b3, voffB); PG8_STAGE(PG8_SB(1, 1), b3 + hB, voffB); PG8_STAGE(PG8_SA(1, 0), a3, voffA);
;             PG8_WAIT_V(8); PG8_WAIT_L(0); PG8_BAR; PG8_MMA(1, 0, At, B0); PG8_MMA(1, 1, At, B1); PG8_BAR; PG8_SCHED;
;         }
;         if constexpr (Hook::ON) H.after(te, acc, cur, wr, wc, fr, fq);
	s_add_i32 s30, s68, s35
	s_add_u32 s72, s28, s14
	s_addc_u32 s73, s29, s15
	s_mov_b32 m0, s30
	ds_read_b128 v[186:189], v224 offset:49152
	ds_read_b128 v[190:193], v224 offset:50176
	ds_read_b128 v[194:197], v224 offset:51200
	ds_read_b128 v[198:201], v224 offset:52224
	ds_read_b128 v[202:205], v224 offset:53248
	ds_read_b128 v[206:209], v224 offset:54272
	ds_read_b128 v[210:213], v224 offset:55296
	ds_read_b128 v[214:217], v224 offset:56320
	global_load_lds_dwordx4 v168, s[72:73]
	s_add_i32 m0, s30, 0x2000
	s_add_u32 s28, s28, 0x300080
	s_addc_u32 s29, s29, 0
	s_add_i32 s30, s69, s35
	global_load_lds_dwordx4 v172, s[72:73]
	s_mov_b32 m0, s30
	s_nop 0
	global_load_lds_dwordx4 v168, s[28:29]
	s_add_i32 m0, s30, 0x2000
	s_nop 0
	global_load_lds_dwordx4 v172, s[28:29]
	v_lshl_add_u64 v[8:9], v[230:231], 0, s[14:15]
	s_mov_b32 m0, s45
	s_nop 0
	global_load_lds_dwordx4 v[8:9], off
	v_lshl_add_u64 v[8:9], v[232:233], 0, s[14:15]
	s_mov_b32 m0, s46
	s_nop 0
	global_load_lds_dwordx4 v[8:9], off
	s_waitcnt vmcnt(8)
	s_waitcnt lgkmcnt(0)
	s_barrier
	s_setprio 1
	s_waitcnt lgkmcnt(0)
	v_mfma_f32_16x16x32_bf16 v[98:101], v[126:129], v[186:189], v[98:101]
	v_mfma_f32_16x16x32_bf16 v[94:97], v[142:145], v[186:189], v[94:97]
	v_mfma_f32_16x16x32_bf16 v[90:93], v[126:129], v[194:197], v[90:93]
	v_mfma_f32_16x16x32_bf16 v[86:89], v[142:145], v[194:197], v[86:89]
	v_mfma_f32_16x16x32_bf16 v[82:85], v[126:129], v[202:205], v[82:85]
	v_mfma_f32_16x16x32_bf16 v[78:81], v[142:145], v[202:205], v[78:81]
	v_mfma_f32_16x16x32_bf16 v[74:77], v[126:129], v[210:213], v[74:77]
	v_mfma_f32_16x16x32_bf16 v[70:73], v[142:145], v[210:213], v[70:73]
	v_mfma_f32_16x16x32_bf16 v[98:101], v[130:133], v[190:193], v[98:101]
	v_mfma_f32_16x16x32_bf16 v[94:97], v[146:149], v[190:193], v[94:97]
	v_mfma_f32_16x16x32_bf16 v[90:93], v[130:133], v[198:201], v[90:93]
	v_mfma_f32_16x16x32_bf16 v[86:89], v[146:149], v[198:201], v[86:89]
	v_mfma_f32_16x16x32_bf16 v[82:85], v[130:133], v[206:209], v[82:85]
	v_mfma_f32_16x16x32_bf16 v[78:81], v[146:149], v[206:209], v[78:81]
	v_mfma_f32_16x16x32_bf16 v[74:77], v[130:133], v[214:217], v[74:77]
	v_mfma_f32_16x16x32_bf16 v[70:73], v[146:149], v[214:217], v[70:73]
	s_setprio 0
	s_setprio 1
	v_mfma_f32_16x16x32_bf16 v[34:37], v[150:153], v[186:189], v[34:37]
	v_mfma_f32_16x16x32_bf16 v[30:33], v[158:161], v[186:189], v[30:33]
	v_mfma_f32_16x16x32_bf16 v[26:29], v[150:153], v[194:197], v[26:29]
	v_mfma_f32_16x16x32_bf16 v[22:25], v[158:161], v[194:197], v[22:25]
	v_mfma_f32_16x16x32_bf16 v[18:21], v[150:153], v[202:205], v[18:21]
	v_mfma_f32_16x16x32_bf16 v[14:17], v[158:161], v[202:205], v[14:17]
	v_mfma_f32_16x16x32_bf16 v[8:11], v[150:153], v[210:213], v[10:13]
	v_mfma_f32_16x16x32_bf16 v[4:7], v[158:161], v[210:213], v[4:7]
	v_mfma_f32_16x16x32_bf16 v[34:37], v[154:157], v[190:193], v[34:37]
	v_mfma_f32_16x16x32_bf16 v[30:33], v[162:165], v[190:193], v[30:33]
	v_mfma_f32_16x16x32_bf16 v[26:29], v[154:157], v[198:201], v[26:29]
	v_mfma_f32_16x16x32_bf16 v[22:25], v[162:165], v[198:201], v[22:25]
	v_mfma_f32_16x16x32_bf16 v[18:21], v[154:157], v[206:209], v[18:21]
	v_mfma_f32_16x16x32_bf16 v[14:17], v[162:165], v[206:209], v[14:17]
	v_mfma_f32_16x16x32_bf16 v[10:13], v[154:157], v[214:217], v[8:11]
	v_mfma_f32_16x16x32_bf16 v[6:9], v[162:165], v[214:217], v[4:7]
	s_setprio 0
	s_barrier
	s_add_u32 s26, s26, 0x100
	s_addc_u32 s27, s27, 0
	s_cmp_ge_u32 s67, s66
	s_cbranch_scc0 .LBB0_783
	s_cmpk_gt_u32 s65, 0x7f
	s_cbranch_scc1 .LBB0_787
	s_lshr_b32 s26, s66, 4
	s_add_i32 s26, s26, -1
	v_mov_b32_e32 v3, v1
	v_mov_b32_e32 v4, v220
	s_lshl_b32 s27, s26, 2
	s_add_i32 s28, s27, s48
	v_lshlrev_b32_e32 v5, 5, v3
	v_add_u32_e32 v126, s28, v5
	ds_read_b32 v126, v126
	s_add_i32 s28, s27, s49
	s_waitcnt lgkmcnt(0)
	v_pk_mul_f32 v[140:141], v[140:141], v[126:127] op_sel_hi:[1,0]
	v_pk_mul_f32 v[138:139], v[138:139], v[126:127] op_sel_hi:[1,0]
	v_pk_mul_f32 v[136:137], v[136:137], v[126:127] op_sel_hi:[1,0]
	v_pk_mul_f32 v[134:135], v[134:135], v[126:127] op_sel_hi:[1,0]
	v_pk_mul_f32 v[68:69], v[68:69], v[126:127] op_sel_hi:[1,0]
	v_pk_mul_f32 v[66:67], v[66:67], v[126:127] op_sel_hi:[1,0]
	v_pk_mul_f32 v[64:65], v[64:65], v[126:127] op_sel_hi:[1,0]
	v_pk_mul_f32 v[62:63], v[62:63], v[126:127] op_sel_hi:[1,0]
	v_add_u32_e32 v126, s28, v5
	ds_read_b32 v126, v126
	s_add_i32 s28, s27, s50
	s_waitcnt lgkmcnt(0)
	v_pk_mul_f32 v[124:125], v[124:125], v[126:127] op_sel_hi:[1,0]
	v_pk_mul_f32 v[122:123], v[122:123], v[126:127] op_sel_hi:[1,0]
	v_pk_mul_f32 v[120:121], v[120:121], v[126:127] op_sel_hi:[1,0]
	v_pk_mul_f32 v[118:119], v[118:119], v[126:127] op_sel_hi:[1,0]
	v_pk_mul_f32 v[60:61], v[60:61], v[126:127] op_sel_hi:[1,0]
	v_pk_mul_f32 v[58:59], v[58:59], v[126:127] op_sel_hi:[1,0]
	v_pk_mul_f32 v[56:57], v[56:57], v[126:127] op_sel_hi:[1,0]
	v_pk_mul_f32 v[54:55], v[54:55], v[126:127] op_sel_hi:[1,0]
	v_add_u32_e32 v126, s28, v5
	ds_read_b32 v126, v126
	s_add_i32 s28, s27, s51
	s_waitcnt lgkmcnt(0)
	v_pk_mul_f32 v[116:117], v[116:117], v[126:127] op_sel_hi:[1,0]
	v_pk_mul_f32 v[114:115], v[114:115], v[126:127] op_sel_hi:[1,0]
	v_pk_mul_f32 v[112:113], v[112:113], v[126:127] op_sel_hi:[1,0]
	v_pk_mul_f32 v[110:111], v[110:111], v[126:127] op_sel_hi:[1,0]
	v_pk_mul_f32 v[52:53], v[52:53], v[126:127] op_sel_hi:[1,0]
	v_pk_mul_f32 v[50:51], v[50:51], v[126:127] op_sel_hi:[1,0]
	v_pk_mul_f32 v[48:49], v[48:49], v[126:127] op_sel_hi:[1,0]
	v_pk_mul_f32 v[46:47], v[46:47], v[126:127] op_sel_hi:[1,0]
	v_add_u32_e32 v126, s28, v5
	ds_read_b32 v126, v126
	s_add_i32 s28, s27, s52
	s_waitcnt lgkmcnt(0)
;     __device__ __forceinline__ void after(int te, f32x4 (&acc)[2][2][4][2], const Unit& u, int wr, int wc, int fr, int fq) const {
;     ...
;             for (int m = 0; m < 4; ++m) { const float f = tab[(ai * HALF + wr * 64 + m * 16 + fr) * 8 + g];
; #pragma unroll
;                 for (int bj = 0; bj < 2; ++bj)
; #pragma unroll
;                     for (int n = 0; n < 2; ++n) acc[ai][bj][m][n] *= f; }
;         if (g == 7) {
;             const int row0 = u.pm * BM + wr * 64 + fr, col0 = u.pn * BM + wc * 32 + 8 * fq;
; #pragma unroll
;             for (int bj = 0; bj < 2; ++bj) { const int c = col0 + bj * HALF;
;                 const f32x4 s0 = *(const f32x4*)(gb + c), s1 = *(const f32x4*)(gb + c + 4), a0 = *(const f32x4*)(gb + D_MODEL + c), a1 = *(const f32x4*)(gb + D_MODEL + c + 4);
; #pragma unroll
;                 for (int ai = 0; ai < 2; ++ai) {
;                     u32x4 gs[4], ga[4];
; #pragma unroll
;                     for (int m = 0; m < 4; ++m) { const size_t r = (size_t)(row0 + ai * HALF + m * 16); gs[m] = *(const u32x4*)(proj + r * LDP + PGS + c); ga[m] = *(const u32x4*)(proj + r * LDP + PGA + c); }
	v_pk_mul_f32 v[108:109], v[108:109], v[126:127] op_sel_hi:[1,0]
	v_pk_mul_f32 v[106:107], v[106:107], v[126:127] op_sel_hi:[1,0]
	v_pk_mul_f32 v[104:105], v[104:105], v[126:127] op_sel_hi:[1,0]
	v_pk_mul_f32 v[102:103], v[102:103], v[126:127] op_sel_hi:[1,0]
	v_pk_mul_f32 v[44:45], v[44:45], v[126:127] op_sel_hi:[1,0]
	v_pk_mul_f32 v[42:43], v[42:43], v[126:127] op_sel_hi:[1,0]
	v_pk_mul_f32 v[40:41], v[40:41], v[126:127] op_sel_hi:[1,0]
	v_pk_mul_f32 v[38:39], v[38:39], v[126:127] op_sel_hi:[1,0]
	v_add_u32_e32 v126, s28, v5
	ds_read_b32 v126, v126
	s_add_i32 s28, s27, s53
	s_waitcnt lgkmcnt(0)
	v_pk_mul_f32 v[100:101], v[100:101], v[126:127] op_sel_hi:[1,0]
	v_pk_mul_f32 v[98:99], v[98:99], v[126:127] op_sel_hi:[1,0]
	v_pk_mul_f32 v[96:97], v[96:97], v[126:127] op_sel_hi:[1,0]
	v_pk_mul_f32 v[94:95], v[94:95], v[126:127] op_sel_hi:[1,0]
	v_pk_mul_f32 v[36:37], v[36:37], v[126:127] op_sel_hi:[1,0]
	v_pk_mul_f32 v[34:35], v[34:35], v[126:127] op_sel_hi:[1,0]
	v_pk_mul_f32 v[32:33], v[32:33], v[126:127] op_sel_hi:[1,0]
	v_pk_mul_f32 v[30:31], v[30:31], v[126:127] op_sel_hi:[1,0]
	v_add_u32_e32 v126, s28, v5
	ds_read_b32 v126, v126
	s_add_i32 s28, s27, s54
	s_add_i32 s27, s27, s55
	s_cmp_lg_u32 s26, 7
	s_waitcnt lgkmcnt(0)
	v_pk_mul_f32 v[92:93], v[92:93], v[126:127] op_sel_hi:[1,0]
	v_pk_mul_f32 v[90:91], v[90:91], v[126:127] op_sel_hi:[1,0]
	v_pk_mul_f32 v[88:89], v[88:89], v[126:127] op_sel_hi:[1,0]
	v_pk_mul_f32 v[86:87], v[86:87], v[126:127] op_sel_hi:[1,0]
	v_pk_mul_f32 v[28:29], v[28:29], v[126:127] op_sel_hi:[1,0]
	v_pk_mul_f32 v[26:27], v[26:27], v[126:127] op_sel_hi:[1,0]
	v_pk_mul_f32 v[24:25], v[24:25], v[126:127] op_sel_hi:[1,0]
	v_pk_mul_f32 v[22:23], v[22:23], v[126:127] op_sel_hi:[1,0]
	v_add_u32_e32 v126, s28, v5
	ds_read_b32 v126, v126
	v_add_u32_e32 v5, s27, v5
	s_waitcnt lgkmcnt(0)
	v_pk_mul_f32 v[84:85], v[84:85], v[126:127] op_sel_hi:[1,0]
	v_pk_mul_f32 v[82:83], v[82:83], v[126:127] op_sel_hi:[1,0]
	v_pk_mul_f32 v[80:81], v[80:81], v[126:127] op_sel_hi:[1,0]
	v_pk_mul_f32 v[78:79], v[78:79], v[126:127] op_sel_hi:[1,0]
	v_pk_mul_f32 v[20:21], v[20:21], v[126:127] op_sel_hi:[1,0]
	v_pk_mul_f32 v[18:19], v[18:19], v[126:127] op_sel_hi:[1,0]
	v_pk_mul_f32 v[16:17], v[16:17], v[126:127] op_sel_hi:[1,0]
	v_pk_mul_f32 v[14:15], v[14:15], v[126:127] op_sel_hi:[1,0]
	ds_read_b32 v126, v5
	s_waitcnt lgkmcnt(0)
	v_pk_mul_f32 v[76:77], v[76:77], v[126:127] op_sel_hi:[1,0]
	v_pk_mul_f32 v[74:75], v[74:75], v[126:127] op_sel_hi:[1,0]
	v_pk_mul_f32 v[72:73], v[72:73], v[126:127] op_sel_hi:[1,0]
	v_pk_mul_f32 v[70:71], v[70:71], v[126:127] op_sel_hi:[1,0]
	v_pk_mul_f32 v[12:13], v[12:13], v[126:127] op_sel_hi:[1,0]
	v_pk_mul_f32 v[10:11], v[10:11], v[126:127] op_sel_hi:[1,0]
	v_pk_mul_f32 v[8:9], v[8:9], v[126:127] op_sel_hi:[1,0]
	v_pk_mul_f32 v[6:7], v[6:7], v[126:127] op_sel_hi:[1,0]
	s_cbranch_scc1 .LBB0_787
	v_add_u32_e32 v126, s62, v3
	v_ashrrev_i32_e32 v127, 31, v126
	v_lshl_add_u32 v4, v4, 3, s61
	v_lshlrev_b64 v[126:127], 14, v[126:127]
	v_ashrrev_i32_e32 v5, 31, v4
	v_lshl_add_u64 v[126:127], s[76:77], 0, v[126:127]
	v_lshl_add_u64 v[192:193], v[4:5], 1, v[126:127]
	v_readlane_b32 s68, v254, 20
	global_load_dwordx4 v[204:207], v[192:193], off
	v_add_co_u32_e32 v126, vcc, s41, v192
	v_lshlrev_b64 v[4:5], 2, v[4:5]
	v_readlane_b32 s70, v254, 22
	v_readlane_b32 s71, v254, 23
	v_addc_co_u32_e32 v127, vcc, 0, v193, vcc
	s_nop 0
	v_lshl_add_u64 v[196:197], s[70:71], 0, v[4:5]
	global_load_dwordx4 v[208:211], v[126:127], off
	global_load_dwordx4 v[142:145], v[196:197], off
	s_nop 0
	global_load_dwordx4 v[126:129], v[196:197], off offset:16
	v_lshl_add_u64 v[198:199], s[12:13], 0, v[4:5]
	global_load_dwordx4 v[146:149], v[198:199], off
	global_load_dwordx4 v[130:133], v[198:199], off offset:16
	s_mov_b64 s[26:27], 0x40000
	v_lshl_add_u64 v[4:5], v[192:193], 0, s[26:27]
	s_mov_b32 s26, 0x40000
	v_add_co_u32_e32 v150, vcc, s26, v192
	s_mov_b64 s[26:27], 0x42000
	s_nop 0
	v_addc_co_u32_e32 v151, vcc, 0, v193, vcc
	v_lshl_add_u64 v[186:187], v[192:193], 0, s[26:27]
	s_mov_b32 s26, 0x42000
	v_add_co_u32_e32 v152, vcc, s26, v192
	s_mov_b64 s[26:27], 0x80000
	s_nop 0
	v_addc_co_u32_e32 v153, vcc, 0, v193, vcc
	v_lshl_add_u64 v[188:189], v[192:193], 0, s[26:27]
	s_mov_b32 s26, 0x80000
	v_add_co_u32_e32 v154, vcc, s26, v192
	s_mov_b64 s[26:27], 0x82000
	s_nop 0
	v_addc_co_u32_e32 v155, vcc, 0, v193, vcc
	v_lshl_add_u64 v[190:191], v[192:193], 0, s[26:27]
	s_mov_b32 s26, 0x82000
	v_add_co_u32_e32 v156, vcc, s26, v192
	s_mov_b64 s[26:27], 0xc0000
	s_nop 0
	v_addc_co_u32_e32 v157, vcc, 0, v193, vcc
	v_lshl_add_u64 v[194:195], v[192:193], 0, s[26:27]
	s_mov_b32 s26, 0xc0000
	v_add_co_u32_e32 v228, vcc, s26, v192
	s_mov_b64 s[26:27], 0xc2000
	s_nop 0
	v_addc_co_u32_e32 v229, vcc, 0, v193, vcc
	v_lshl_add_u64 v[200:201], v[192:193], 0, s[26:27]
	s_mov_b32 s26, 0xc2000
	v_add_co_u32_e32 v230, vcc, s26, v192
	s_mov_b32 s26, 0x200000
	s_nop 0
	v_addc_co_u32_e32 v231, vcc, 0, v193, vcc
	global_load_dwordx4 v[212:215], v[150:151], off
	global_load_dwordx4 v[216:219], v[152:153], off
	global_load_dwordx4 v[162:165], v[154:155], off
	global_load_dwordx4 v[158:161], v[156:157], off
	s_nop 0
	global_load_dwordx4 v[154:157], v[228:229], off
	global_load_dwordx4 v[150:153], v[230:231], off
	v_lshl_add_u64 v[202:203], v[192:193], 0, s[18:19]
	v_readlane_b32 s76, v254, 28
	v_readlane_b32 s77, v254, 29
	v_readlane_b32 s76, v255, 8
	v_readlane_b32 s77, v255, 9
	v_readlane_b32 s69, v254, 21
	v_readlane_b32 s72, v254, 24
	v_readlane_b32 s73, v254, 25
	v_readlane_b32 s74, v254, 26
	v_readlane_b32 s75, v254, 27
	v_readlane_b32 s78, v254, 30
	v_readlane_b32 s79, v254, 31
	v_readlane_b32 s80, v254, 32
	v_readlane_b32 s81, v254, 33
	v_readlane_b32 s82, v254, 34
	v_readlane_b32 s83, v254, 35
	s_waitcnt vmcnt(0)
; __device__ __forceinline__ void unpack8(const u32x4 w, float (&v)[8]) { v[0] = bf_lo(w.x); v[1] = bf_hi(w.x); v[2] = bf_lo(w.y); v[3] = bf_hi(w.y); v[4] = bf_lo(w.z); v[5] = bf_hi(w.z); v[6] = bf_lo(w.w); v[7] = bf_hi(w.w); }
;     __device__ __forceinline__ void after(int te, f32x4 (&acc)[2][2][4][2], const Unit& u, int wr, int wc, int fr, int fq) const {
;     ...
;                     for (int m = 0; m < 4; ++m) { float vs[8], va[8]; unpack8(gs[m], vs); unpack8(ga[m], va);
; #pragma unroll
;                         for (int e = 0; e < 4; ++e) {
;                             acc[ai][bj][m][0][e] *= (1.f + __expf(-(va[e] + a0[e]))) * __builtin_amdgcn_rcpf(1.f + __expf(-(vs[e] + s0[e])));
;                             acc[ai][bj][m][1][e] *= (1.f + __expf(-(va[4 + e] + a1[e]))) * __builtin_amdgcn_rcpf(1.f + __expf(-(vs[4 + e] + s1[e]))); } }
	v_lshlrev_b32_e32 v3, 16, v204
	v_and_b32_e32 v204, 0xffff0000, v204
	v_lshlrev_b32_e32 v225, 16, v205
	v_and_b32_e32 v227, 0xffff0000, v205
	v_lshlrev_b32_e32 v205, 16, v206
	v_and_b32_e32 v228, 0xffff0000, v206
	v_lshlrev_b32_e32 v229, 16, v207
	v_and_b32_e32 v233, 0xffff0000, v207
	v_add_f32_e32 v3, v142, v3
	v_add_f32_e32 v204, v143, v204
	v_mul_f32_e32 v3, 0xbfb8aa3b, v3
	v_mul_f32_e32 v204, 0xbfb8aa3b, v204
	v_exp_f32_e32 v3, v3
	v_lshlrev_b32_e32 v230, 16, v209
	v_and_b32_e32 v231, 0xffff0000, v209
	v_exp_f32_e32 v209, v204
	v_lshlrev_b32_e32 v206, 16, v208
	v_and_b32_e32 v207, 0xffff0000, v208
	v_lshlrev_b32_e32 v208, 16, v210
	v_add_f32_e32 v206, v146, v206
	v_add_f32_e32 v208, v130, v208
	v_mul_f32_e32 v206, 0xbfb8aa3b, v206
	v_mul_f32_e32 v208, 0xbfb8aa3b, v208
	v_add_f32_e32 v3, 1.0, v3
	v_exp_f32_e32 v204, v206
	v_exp_f32_e32 v206, v208
	v_rcp_f32_e32 v208, v3
	v_add_f32_e32 v3, 1.0, v209
	v_rcp_f32_e32 v209, v3
	v_add_f32_e32 v3, v127, v228
	v_mul_f32_e32 v3, 0xbfb8aa3b, v3
	v_exp_f32_e32 v3, v3
	v_lshlrev_b32_e32 v234, 16, v211
	v_and_b32_e32 v235, 0xffff0000, v211
	v_add_f32_e32 v205, v126, v205
	v_add_f32_e32 v3, 1.0, v3
	v_rcp_f32_e32 v211, v3
	v_add_f32_e32 v3, v144, v225
	v_mul_f32_e32 v3, 0xbfb8aa3b, v3
	v_exp_f32_e32 v3, v3
	v_mul_f32_e32 v205, 0xbfb8aa3b, v205
	v_exp_f32_e32 v205, v205
	v_add_f32_e32 v225, v148, v230
	v_add_f32_e32 v3, 1.0, v3
	v_rcp_f32_e32 v230, v3
	v_add_f32_e32 v3, v128, v229
	v_mul_f32_e32 v3, 0xbfb8aa3b, v3
	v_add_f32_e32 v227, v145, v227
	v_mul_f32_e32 v225, 0xbfb8aa3b, v225
	v_exp_f32_e32 v3, v3
	v_mul_f32_e32 v227, 0xbfb8aa3b, v227
	v_add_f32_e32 v207, v147, v207
	v_exp_f32_e32 v228, v225
	v_add_f32_e32 v225, v132, v234
	v_exp_f32_e32 v227, v227
	v_and_b32_e32 v232, 0xffff0000, v210
	v_mul_f32_e32 v207, 0xbfb8aa3b, v207
	v_add_f32_e32 v205, 1.0, v205
	v_mul_f32_e32 v225, 0xbfb8aa3b, v225
	v_rcp_f32_e32 v210, v205
	v_exp_f32_e32 v205, v207
	v_add_f32_e32 v207, v131, v232
	v_exp_f32_e32 v232, v225
	v_add_f32_e32 v225, v149, v231
	v_add_f32_e32 v3, 1.0, v3
	v_mul_f32_e32 v225, 0xbfb8aa3b, v225
	v_exp_f32_e32 v229, v225
	v_rcp_f32_e32 v234, v3
	v_add_f32_e32 v3, 1.0, v227
	v_rcp_f32_e32 v231, v3
	v_pk_add_f32 v[228:229], v[228:229], 1.0 op_sel_hi:[1,0]
	v_pk_add_f32 v[204:205], v[204:205], 1.0 op_sel_hi:[1,0]
	v_add_f32_e32 v3, v133, v235
	v_pk_mul_f32 v[204:205], v[204:205], v[208:209]
	v_pk_mul_f32 v[208:209], v[228:229], v[230:231]
	v_mul_f32_e32 v3, 0xbfb8aa3b, v3
	v_pk_mul_f32 v[140:141], v[140:141], v[208:209]
	v_add_f32_e32 v208, v129, v233
	v_mul_f32_e32 v208, 0xbfb8aa3b, v208
	v_exp_f32_e32 v208, v208
	v_exp_f32_e32 v233, v3
	v_mul_f32_e32 v207, 0xbfb8aa3b, v207
	v_exp_f32_e32 v207, v207
	v_add_f32_e32 v3, 1.0, v208
	v_rcp_f32_e32 v235, v3
	v_lshlrev_b32_e32 v3, 16, v212
	v_add_f32_e32 v3, v142, v3
	v_mul_f32_e32 v3, 0xbfb8aa3b, v3
	v_exp_f32_e32 v3, v3
	v_pk_add_f32 v[206:207], v[206:207], 1.0 op_sel_hi:[1,0]
	v_pk_mul_f32 v[138:139], v[138:139], v[204:205]
	v_pk_mul_f32 v[206:207], v[206:207], v[210:211]
	v_add_f32_e32 v3, 1.0, v3
	v_pk_mul_f32 v[134:135], v[134:135], v[206:207]
	v_lshlrev_b32_e32 v207, 16, v214
	v_rcp_f32_e32 v206, v3
	v_add_f32_e32 v3, v126, v207
	v_mul_f32_e32 v3, 0xbfb8aa3b, v3
	v_exp_f32_e32 v3, v3
	v_pk_add_f32 v[204:205], v[232:233], 1.0 op_sel_hi:[1,0]
	v_lshlrev_b32_e32 v208, 16, v218
	v_pk_mul_f32 v[204:205], v[204:205], v[234:235]
	v_add_f32_e32 v3, 1.0, v3
	v_pk_mul_f32 v[136:137], v[136:137], v[204:205]
	v_and_b32_e32 v205, 0xffff0000, v212
	v_rcp_f32_e32 v210, v3
	v_add_f32_e32 v3, v143, v205
	v_mul_f32_e32 v3, 0xbfb8aa3b, v3
	v_exp_f32_e32 v3, v3
	v_add_f32_e32 v207, v130, v208
	v_and_b32_e32 v209, 0xffff0000, v214
	v_mul_f32_e32 v207, 0xbfb8aa3b, v207
	v_add_f32_e32 v3, 1.0, v3
	v_exp_f32_e32 v208, v207
	v_rcp_f32_e32 v207, v3
	v_add_f32_e32 v3, v127, v209
	v_mul_f32_e32 v3, 0xbfb8aa3b, v3
	v_exp_f32_e32 v3, v3
	v_lshlrev_b32_e32 v212, 16, v213
	v_and_b32_e32 v211, 0xffff0000, v216
	v_add_f32_e32 v205, v147, v211
	v_add_f32_e32 v3, 1.0, v3
	v_rcp_f32_e32 v211, v3
	v_add_f32_e32 v3, v144, v212
	v_mul_f32_e32 v3, 0xbfb8aa3b, v3
	v_exp_f32_e32 v3, v3
	v_lshlrev_b32_e32 v225, 16, v215
	v_lshlrev_b32_e32 v214, 16, v217
	v_and_b32_e32 v213, 0xffff0000, v213
	v_add_f32_e32 v3, 1.0, v3
	v_add_f32_e32 v212, v148, v214
	v_rcp_f32_e32 v214, v3
	v_add_f32_e32 v3, v128, v225
	v_mul_f32_e32 v3, 0xbfb8aa3b, v3
	v_add_f32_e32 v213, v145, v213
	v_and_b32_e32 v227, 0xffff0000, v215
	v_lshlrev_b32_e32 v204, 16, v216
	v_and_b32_e32 v215, 0xffff0000, v217
	v_and_b32_e32 v216, 0xffff0000, v218
	v_lshlrev_b32_e32 v217, 16, v219
	v_exp_f32_e32 v3, v3
	v_mul_f32_e32 v213, 0xbfb8aa3b, v213
	v_add_f32_e32 v209, v131, v216
	v_add_f32_e32 v216, v132, v217
	v_exp_f32_e32 v217, v213
	v_add_f32_e32 v204, v146, v204
	v_add_f32_e32 v215, v149, v215
	v_mul_f32_e32 v204, 0xbfb8aa3b, v204
	v_mul_f32_e32 v205, 0xbfb8aa3b, v205
	v_mul_f32_e32 v212, 0xbfb8aa3b, v212
	v_add_f32_e32 v3, 1.0, v3
	v_mul_f32_e32 v213, 0xbfb8aa3b, v215
	v_exp_f32_e32 v204, v204
	v_exp_f32_e32 v205, v205
	v_exp_f32_e32 v212, v212
	v_exp_f32_e32 v213, v213
	v_rcp_f32_e32 v218, v3
	v_add_f32_e32 v3, 1.0, v217
	v_rcp_f32_e32 v215, v3
	v_pk_add_f32 v[212:213], v[212:213], 1.0 op_sel_hi:[1,0]
	v_pk_add_f32 v[204:205], v[204:205], 1.0 op_sel_hi:[1,0]
	v_and_b32_e32 v219, 0xffff0000, v219
	v_pk_mul_f32 v[204:205], v[204:205], v[206:207]
	v_pk_mul_f32 v[206:207], v[212:213], v[214:215]
	v_add_f32_e32 v3, v133, v219
	v_pk_mul_f32 v[124:125], v[124:125], v[206:207]
	v_add_f32_e32 v206, v129, v227
	v_mul_f32_e32 v206, 0xbfb8aa3b, v206
	v_exp_f32_e32 v206, v206
	v_mul_f32_e32 v3, 0xbfb8aa3b, v3
	v_exp_f32_e32 v217, v3
; __device__ __forceinline__ void unpack8(const u32x4 w, float (&v)[8]) { v[0] = bf_lo(w.x); v[1] = bf_hi(w.x); v[2] = bf_lo(w.y); v[3] = bf_hi(w.y); v[4] = bf_lo(w.z); v[5] = bf_hi(w.z); v[6] = bf_lo(w.w); v[7] = bf_hi(w.w); }
;     __device__ __forceinline__ void after(int te, f32x4 (&acc)[2][2][4][2], const Unit& u, int wr, int wc, int fr, int fq) const {
;     ...
;                     for (int m = 0; m < 4; ++m) { float vs[8], va[8]; unpack8(gs[m], vs); unpack8(ga[m], va);
; #pragma unroll
;                         for (int e = 0; e < 4; ++e) {
;                             acc[ai][bj][m][0][e] *= (1.f + __expf(-(va[e] + a0[e]))) * __builtin_amdgcn_rcpf(1.f + __expf(-(vs[e] + s0[e])));
;                             acc[ai][bj][m][1][e] *= (1.f + __expf(-(va[4 + e] + a1[e]))) * __builtin_amdgcn_rcpf(1.f + __expf(-(vs[4 + e] + s1[e]))); } }
	v_mul_f32_e32 v216, 0xbfb8aa3b, v216
	v_add_f32_e32 v3, 1.0, v206
	v_rcp_f32_e32 v219, v3
	v_lshlrev_b32_e32 v3, 16, v162
	v_mul_f32_e32 v209, 0xbfb8aa3b, v209
	v_exp_f32_e32 v216, v216
	v_add_f32_e32 v3, v142, v3
	v_exp_f32_e32 v209, v209
	v_mul_f32_e32 v3, 0xbfb8aa3b, v3
	v_exp_f32_e32 v3, v3
	v_pk_mul_f32 v[122:123], v[122:123], v[204:205]
	v_pk_add_f32 v[204:205], v[216:217], 1.0 op_sel_hi:[1,0]
	v_pk_add_f32 v[206:207], v[208:209], 1.0 op_sel_hi:[1,0]
	v_pk_mul_f32 v[204:205], v[204:205], v[218:219]
	v_pk_mul_f32 v[206:207], v[206:207], v[210:211]
	v_pk_mul_f32 v[120:121], v[120:121], v[204:205]
	v_and_b32_e32 v204, 0xffff0000, v162
	v_lshlrev_b32_e32 v162, 16, v164
	v_add_f32_e32 v3, 1.0, v3
	v_pk_mul_f32 v[118:119], v[118:119], v[206:207]
	v_lshlrev_b32_e32 v206, 16, v159
	v_and_b32_e32 v210, 0xffff0000, v159
	v_lshlrev_b32_e32 v159, 16, v160
	v_and_b32_e32 v211, 0xffff0000, v160
	v_rcp_f32_e32 v160, v3
	v_add_f32_e32 v3, v126, v162
	v_mul_f32_e32 v3, 0xbfb8aa3b, v3
	v_exp_f32_e32 v3, v3
	v_lshlrev_b32_e32 v205, 16, v163
	v_and_b32_e32 v207, 0xffff0000, v163
	v_and_b32_e32 v163, 0xffff0000, v164
	v_lshlrev_b32_e32 v164, 16, v158
	v_add_f32_e32 v3, 1.0, v3
	v_lshlrev_b32_e32 v208, 16, v165
	v_and_b32_e32 v209, 0xffff0000, v165
	v_and_b32_e32 v165, 0xffff0000, v158
	v_add_f32_e32 v158, v146, v164
	v_rcp_f32_e32 v164, v3
	v_add_f32_e32 v3, v143, v204
	v_mul_f32_e32 v3, 0xbfb8aa3b, v3
	v_exp_f32_e32 v3, v3
	v_lshlrev_b32_e32 v212, 16, v161
	v_and_b32_e32 v213, 0xffff0000, v161
	v_add_f32_e32 v159, v130, v159
	v_add_f32_e32 v3, 1.0, v3
	v_rcp_f32_e32 v161, v3
	v_add_f32_e32 v3, v127, v163
	v_mul_f32_e32 v3, 0xbfb8aa3b, v3
	v_exp_f32_e32 v3, v3
	v_mul_f32_e32 v159, 0xbfb8aa3b, v159
	v_exp_f32_e32 v162, v159
	v_add_f32_e32 v159, v147, v165
	v_add_f32_e32 v3, 1.0, v3
	v_rcp_f32_e32 v165, v3
	v_add_f32_e32 v3, v144, v205
	v_mul_f32_e32 v3, 0xbfb8aa3b, v3
	v_exp_f32_e32 v3, v3
	v_add_f32_e32 v204, v148, v206
	v_add_f32_e32 v207, v145, v207
	v_mul_f32_e32 v207, 0xbfb8aa3b, v207
	v_add_f32_e32 v3, 1.0, v3
	v_rcp_f32_e32 v206, v3
	v_add_f32_e32 v3, v128, v208
	v_mul_f32_e32 v3, 0xbfb8aa3b, v3
	v_exp_f32_e32 v3, v3
	v_add_f32_e32 v205, v132, v212
	v_exp_f32_e32 v207, v207
	v_mul_f32_e32 v205, 0xbfb8aa3b, v205
	v_exp_f32_e32 v208, v205
	v_add_f32_e32 v205, v149, v210
	v_mul_f32_e32 v158, 0xbfb8aa3b, v158
	v_mul_f32_e32 v159, 0xbfb8aa3b, v159
	v_mul_f32_e32 v204, 0xbfb8aa3b, v204
	v_add_f32_e32 v3, 1.0, v3
	v_mul_f32_e32 v205, 0xbfb8aa3b, v205
	v_exp_f32_e32 v158, v158
	v_exp_f32_e32 v159, v159
	v_exp_f32_e32 v204, v204
	v_exp_f32_e32 v205, v205
	v_rcp_f32_e32 v210, v3
	v_add_f32_e32 v3, 1.0, v207
	v_rcp_f32_e32 v207, v3
	v_pk_add_f32 v[204:205], v[204:205], 1.0 op_sel_hi:[1,0]
	v_pk_add_f32 v[158:159], v[158:159], 1.0 op_sel_hi:[1,0]
	v_add_f32_e32 v3, v133, v213
	v_pk_mul_f32 v[158:159], v[158:159], v[160:161]
	v_pk_mul_f32 v[160:161], v[204:205], v[206:207]
	v_mul_f32_e32 v3, 0xbfb8aa3b, v3
	v_pk_mul_f32 v[116:117], v[116:117], v[160:161]
	v_add_f32_e32 v160, v129, v209
	v_mul_f32_e32 v160, 0xbfb8aa3b, v160
	v_exp_f32_e32 v160, v160
	v_exp_f32_e32 v209, v3
	v_add_f32_e32 v163, v131, v211
	v_mul_f32_e32 v163, 0xbfb8aa3b, v163
	v_add_f32_e32 v3, 1.0, v160
	v_rcp_f32_e32 v211, v3
	v_lshlrev_b32_e32 v3, 16, v154
	v_add_f32_e32 v3, v142, v3
	v_exp_f32_e32 v163, v163
	v_mul_f32_e32 v3, 0xbfb8aa3b, v3
	v_exp_f32_e32 v3, v3
	v_pk_mul_f32 v[114:115], v[114:115], v[158:159]
	v_pk_add_f32 v[158:159], v[208:209], 1.0 op_sel_hi:[1,0]
	v_pk_add_f32 v[160:161], v[162:163], 1.0 op_sel_hi:[1,0]
	v_pk_mul_f32 v[158:159], v[158:159], v[210:211]
	v_pk_mul_f32 v[160:161], v[160:161], v[164:165]
	v_pk_mul_f32 v[112:113], v[112:113], v[158:159]
	v_and_b32_e32 v158, 0xffff0000, v154
	v_lshlrev_b32_e32 v154, 16, v156
	v_add_f32_e32 v3, 1.0, v3
	v_pk_mul_f32 v[110:111], v[110:111], v[160:161]
	v_lshlrev_b32_e32 v160, 16, v151
	v_and_b32_e32 v204, 0xffff0000, v151
	v_lshlrev_b32_e32 v151, 16, v152
	v_and_b32_e32 v162, 0xffff0000, v152
	v_rcp_f32_e32 v152, v3
	v_add_f32_e32 v3, v126, v154
	v_mul_f32_e32 v3, 0xbfb8aa3b, v3
	v_exp_f32_e32 v3, v3
	v_lshlrev_b32_e32 v159, 16, v155
	v_and_b32_e32 v161, 0xffff0000, v155
	v_and_b32_e32 v155, 0xffff0000, v156
	v_lshlrev_b32_e32 v156, 16, v150
	v_add_f32_e32 v3, 1.0, v3
	v_lshlrev_b32_e32 v164, 16, v157
	v_and_b32_e32 v165, 0xffff0000, v157
	v_and_b32_e32 v157, 0xffff0000, v150
	v_add_f32_e32 v150, v146, v156
	v_rcp_f32_e32 v156, v3
	v_add_f32_e32 v3, v143, v158
	v_mul_f32_e32 v3, 0xbfb8aa3b, v3
	v_exp_f32_e32 v3, v3
	v_lshlrev_b32_e32 v205, 16, v153
	v_and_b32_e32 v206, 0xffff0000, v153
	v_add_f32_e32 v151, v130, v151
	v_add_f32_e32 v3, 1.0, v3
	v_rcp_f32_e32 v153, v3
	v_add_f32_e32 v3, v127, v155
	v_add_f32_e32 v155, v131, v162
	v_add_co_u32_e32 v162, vcc, s26, v192
	v_mul_f32_e32 v3, 0xbfb8aa3b, v3
	s_nop 0
	v_addc_co_u32_e32 v163, vcc, 0, v193, vcc
	global_load_dwordx4 v[228:231], v[162:163], off
	v_exp_f32_e32 v3, v3
	v_mul_f32_e32 v151, 0xbfb8aa3b, v151
	s_mov_b32 s26, 0x202000
	v_exp_f32_e32 v154, v151
	v_add_f32_e32 v3, 1.0, v3
	v_add_f32_e32 v151, v147, v157
	v_rcp_f32_e32 v157, v3
	v_add_f32_e32 v3, v144, v159
	v_add_co_u32_e32 v162, vcc, s26, v192
	v_mul_f32_e32 v3, 0xbfb8aa3b, v3
	s_nop 0
	v_addc_co_u32_e32 v163, vcc, 0, v193, vcc
	v_exp_f32_e32 v3, v3
	global_load_dwordx4 v[232:235], v[162:163], off
	v_add_f32_e32 v158, v148, v160
	v_add_f32_e32 v161, v145, v161
	v_add_f32_e32 v3, 1.0, v3
	v_rcp_f32_e32 v160, v3
	v_add_f32_e32 v3, v128, v164
	v_mul_f32_e32 v3, 0xbfb8aa3b, v3
	v_exp_f32_e32 v3, v3
	v_mul_f32_e32 v161, 0xbfb8aa3b, v161
	v_add_f32_e32 v159, v132, v205
	v_exp_f32_e32 v161, v161
	v_mul_f32_e32 v159, 0xbfb8aa3b, v159
; __device__ __forceinline__ void unpack8(const u32x4 w, float (&v)[8]) { v[0] = bf_lo(w.x); v[1] = bf_hi(w.x); v[2] = bf_lo(w.y); v[3] = bf_hi(w.y); v[4] = bf_lo(w.z); v[5] = bf_hi(w.z); v[6] = bf_lo(w.w); v[7] = bf_hi(w.w); }
;     __device__ __forceinline__ void after(int te, f32x4 (&acc)[2][2][4][2], const Unit& u, int wr, int wc, int fr, int fq) const {
;     ...
;                     for (int m = 0; m < 4; ++m) { const size_t r = (size_t)(row0 + ai * HALF + m * 16); gs[m] = *(const u32x4*)(proj + r * LDP + PGS + c); ga[m] = *(const u32x4*)(proj + r * LDP + PGA + c); }
; #pragma unroll
;                     for (int m = 0; m < 4; ++m) { float vs[8], va[8]; unpack8(gs[m], vs); unpack8(ga[m], va);
; #pragma unroll
;                         for (int e = 0; e < 4; ++e) {
;                             acc[ai][bj][m][0][e] *= (1.f + __expf(-(va[e] + a0[e]))) * __builtin_amdgcn_rcpf(1.f + __expf(-(vs[e] + s0[e])));
;                             acc[ai][bj][m][1][e] *= (1.f + __expf(-(va[4 + e] + a1[e]))) * __builtin_amdgcn_rcpf(1.f + __expf(-(vs[4 + e] + s1[e]))); } }
	v_exp_f32_e32 v162, v159
	v_add_f32_e32 v159, v149, v204
	v_mul_f32_e32 v150, 0xbfb8aa3b, v150
	v_mul_f32_e32 v151, 0xbfb8aa3b, v151
	v_mul_f32_e32 v158, 0xbfb8aa3b, v158
	v_add_f32_e32 v3, 1.0, v3
	v_mul_f32_e32 v159, 0xbfb8aa3b, v159
	v_exp_f32_e32 v150, v150
	v_exp_f32_e32 v151, v151
	v_exp_f32_e32 v158, v158
	v_exp_f32_e32 v159, v159
	v_rcp_f32_e32 v164, v3
	v_add_f32_e32 v3, 1.0, v161
	v_rcp_f32_e32 v161, v3
	v_pk_add_f32 v[158:159], v[158:159], 1.0 op_sel_hi:[1,0]
	v_pk_add_f32 v[150:151], v[150:151], 1.0 op_sel_hi:[1,0]
	v_add_f32_e32 v3, v133, v206
	v_pk_mul_f32 v[150:151], v[150:151], v[152:153]
	v_pk_mul_f32 v[152:153], v[158:159], v[160:161]
	v_mul_f32_e32 v3, 0xbfb8aa3b, v3
	v_pk_mul_f32 v[108:109], v[108:109], v[152:153]
	v_add_f32_e32 v152, v129, v165
	v_mul_f32_e32 v152, 0xbfb8aa3b, v152
	v_exp_f32_e32 v152, v152
	v_exp_f32_e32 v163, v3
	v_mul_f32_e32 v155, 0xbfb8aa3b, v155
	v_exp_f32_e32 v155, v155
	v_add_f32_e32 v3, 1.0, v152
	v_rcp_f32_e32 v165, v3
	s_mov_b64 s[26:27], 0x200000
	v_lshl_add_u64 v[218:219], v[192:193], 0, s[26:27]
	s_mov_b64 s[26:27], 0x202000
	v_pk_mul_f32 v[106:107], v[106:107], v[150:151]
	v_pk_add_f32 v[150:151], v[162:163], 1.0 op_sel_hi:[1,0]
	v_lshl_add_u64 v[216:217], v[192:193], 0, s[26:27]
	s_mov_b64 s[26:27], 0x240000
	v_pk_mul_f32 v[150:151], v[150:151], v[164:165]
	v_lshl_add_u64 v[204:205], v[192:193], 0, s[26:27]
	s_mov_b32 s26, 0x240000
	v_pk_add_f32 v[152:153], v[154:155], 1.0 op_sel_hi:[1,0]
	v_pk_mul_f32 v[104:105], v[104:105], v[150:151]
	v_add_co_u32_e32 v150, vcc, s26, v192
	s_mov_b64 s[26:27], 0x242000
	v_pk_mul_f32 v[152:153], v[152:153], v[156:157]
	v_addc_co_u32_e32 v151, vcc, 0, v193, vcc
	v_lshl_add_u64 v[206:207], v[192:193], 0, s[26:27]
	s_mov_b32 s26, 0x242000
	v_pk_mul_f32 v[102:103], v[102:103], v[152:153]
	v_add_co_u32_e32 v152, vcc, s26, v192
	s_mov_b64 s[26:27], 0x280000
	s_nop 0
	v_addc_co_u32_e32 v153, vcc, 0, v193, vcc
	global_load_dwordx4 v[236:239], v[150:151], off
	global_load_dwordx4 v[240:243], v[152:153], off
	s_waitcnt vmcnt(3)
	v_lshlrev_b32_e32 v3, 16, v228
	v_add_f32_e32 v3, v142, v3
	v_mul_f32_e32 v3, 0xbfb8aa3b, v3
	v_exp_f32_e32 v3, v3
	v_lshlrev_b32_e32 v227, 16, v229
	v_and_b32_e32 v245, 0xffff0000, v229
	v_lshlrev_b32_e32 v229, 16, v230
	v_add_f32_e32 v3, 1.0, v3
	v_and_b32_e32 v246, 0xffff0000, v230
	v_rcp_f32_e32 v230, v3
	v_add_f32_e32 v3, v126, v229
	v_mul_f32_e32 v3, 0xbfb8aa3b, v3
	v_exp_f32_e32 v3, v3
	v_lshl_add_u64 v[208:209], v[192:193], 0, s[26:27]
	s_mov_b32 s26, 0x280000
	v_add_co_u32_e32 v150, vcc, s26, v192
	s_mov_b64 s[26:27], 0x282000
	s_nop 0
	v_addc_co_u32_e32 v151, vcc, 0, v193, vcc
	v_lshl_add_u64 v[210:211], v[192:193], 0, s[26:27]
	s_mov_b32 s26, 0x282000
	v_add_co_u32_e32 v152, vcc, s26, v192
	v_and_b32_e32 v225, 0xffff0000, v228
	v_add_f32_e32 v3, 1.0, v3
	v_addc_co_u32_e32 v153, vcc, 0, v193, vcc
	global_load_dwordx4 v[162:165], v[150:151], off
	global_load_dwordx4 v[158:161], v[152:153], off
	v_lshlrev_b32_e32 v247, 16, v231
	v_and_b32_e32 v251, 0xffff0000, v231
	s_waitcnt vmcnt(4)
	v_lshlrev_b32_e32 v228, 16, v232
	v_and_b32_e32 v231, 0xffff0000, v232
	v_lshlrev_b32_e32 v248, 16, v233
	v_and_b32_e32 v249, 0xffff0000, v233
	v_lshlrev_b32_e32 v232, 16, v234
	v_and_b32_e32 v233, 0xffff0000, v234
	v_rcp_f32_e32 v234, v3
	v_add_f32_e32 v3, v143, v225
	v_mul_f32_e32 v3, 0xbfb8aa3b, v3
	v_exp_f32_e32 v3, v3
	v_add_f32_e32 v225, v147, v231
	v_lshlrev_b32_e32 v250, 16, v235
	v_and_b32_e32 v253, 0xffff0000, v235
	v_add_f32_e32 v3, 1.0, v3
	v_rcp_f32_e32 v231, v3
	v_add_f32_e32 v3, v127, v246
	v_mul_f32_e32 v3, 0xbfb8aa3b, v3
	v_exp_f32_e32 v3, v3
	v_add_f32_e32 v229, v130, v232
	v_mul_f32_e32 v229, 0xbfb8aa3b, v229
	v_mul_f32_e32 v225, 0xbfb8aa3b, v225
	v_add_f32_e32 v3, 1.0, v3
	v_rcp_f32_e32 v235, v3
	v_add_f32_e32 v3, v144, v227
	v_mul_f32_e32 v3, 0xbfb8aa3b, v3
	v_exp_f32_e32 v3, v3
	v_exp_f32_e32 v232, v229
	v_exp_f32_e32 v229, v225
	v_add_f32_e32 v225, v131, v233
	v_mul_f32_e32 v225, 0xbfb8aa3b, v225
	v_exp_f32_e32 v233, v225
	v_add_f32_e32 v225, v148, v248
	v_mul_f32_e32 v225, 0xbfb8aa3b, v225
	v_add_f32_e32 v3, 1.0, v3
	v_exp_f32_e32 v246, v225
	v_rcp_f32_e32 v248, v3
	v_add_f32_e32 v3, v128, v247
	v_add_f32_e32 v225, v132, v250
	v_mul_f32_e32 v3, 0xbfb8aa3b, v3
	v_mul_f32_e32 v225, 0xbfb8aa3b, v225
	v_add_f32_e32 v227, v145, v245
	v_exp_f32_e32 v3, v3
	v_exp_f32_e32 v250, v225
	v_add_f32_e32 v225, v149, v249
	v_mul_f32_e32 v227, 0xbfb8aa3b, v227
	v_exp_f32_e32 v227, v227
	v_mul_f32_e32 v225, 0xbfb8aa3b, v225
	v_exp_f32_e32 v247, v225
	v_add_f32_e32 v225, v129, v251
	v_mul_f32_e32 v225, 0xbfb8aa3b, v225
	v_add_f32_e32 v3, 1.0, v3
	v_exp_f32_e32 v225, v225
	v_rcp_f32_e32 v252, v3
	v_add_f32_e32 v3, 1.0, v227
	v_add_f32_e32 v228, v146, v228
	v_rcp_f32_e32 v249, v3
	v_add_f32_e32 v3, v133, v253
	v_mul_f32_e32 v228, 0xbfb8aa3b, v228
	v_mul_f32_e32 v3, 0xbfb8aa3b, v3
	v_exp_f32_e32 v228, v228
	v_exp_f32_e32 v251, v3
	v_add_f32_e32 v3, 1.0, v225
	v_rcp_f32_e32 v253, v3
	s_waitcnt vmcnt(3)
; __device__ __forceinline__ void unpack8(const u32x4 w, float (&v)[8]) { v[0] = bf_lo(w.x); v[1] = bf_hi(w.x); v[2] = bf_lo(w.y); v[3] = bf_hi(w.y); v[4] = bf_lo(w.z); v[5] = bf_hi(w.z); v[6] = bf_lo(w.w); v[7] = bf_hi(w.w); }
;     __device__ __forceinline__ void after(int te, f32x4 (&acc)[2][2][4][2], const Unit& u, int wr, int wc, int fr, int fq) const {
;     ...
;                     for (int m = 0; m < 4; ++m) { float vs[8], va[8]; unpack8(gs[m], vs); unpack8(ga[m], va);
; #pragma unroll
;                         for (int e = 0; e < 4; ++e) {
;                             acc[ai][bj][m][0][e] *= (1.f + __expf(-(va[e] + a0[e]))) * __builtin_amdgcn_rcpf(1.f + __expf(-(vs[e] + s0[e])));
;                             acc[ai][bj][m][1][e] *= (1.f + __expf(-(va[4 + e] + a1[e]))) * __builtin_amdgcn_rcpf(1.f + __expf(-(vs[4 + e] + s1[e]))); } }
	v_lshlrev_b32_e32 v3, 16, v236
	v_add_f32_e32 v3, v142, v3
	v_mul_f32_e32 v3, 0xbfb8aa3b, v3
	v_pk_add_f32 v[228:229], v[228:229], 1.0 op_sel_hi:[1,0]
	v_exp_f32_e32 v3, v3
	v_pk_add_f32 v[246:247], v[246:247], 1.0 op_sel_hi:[1,0]
	v_pk_mul_f32 v[228:229], v[228:229], v[230:231]
	v_pk_mul_f32 v[230:231], v[246:247], v[248:249]
	v_pk_mul_f32 v[98:99], v[98:99], v[228:229]
	v_pk_add_f32 v[228:229], v[250:251], 1.0 op_sel_hi:[1,0]
	v_pk_mul_f32 v[100:101], v[100:101], v[230:231]
	v_pk_add_f32 v[230:231], v[232:233], 1.0 op_sel_hi:[1,0]
	v_pk_mul_f32 v[228:229], v[228:229], v[252:253]
	v_pk_mul_f32 v[230:231], v[230:231], v[234:235]
	v_pk_mul_f32 v[96:97], v[96:97], v[228:229]
	v_lshlrev_b32_e32 v229, 16, v238
	v_add_f32_e32 v3, 1.0, v3
	v_pk_mul_f32 v[94:95], v[94:95], v[230:231]
	v_rcp_f32_e32 v230, v3
	v_add_f32_e32 v3, v126, v229
	v_mul_f32_e32 v3, 0xbfb8aa3b, v3
	v_exp_f32_e32 v3, v3
	v_and_b32_e32 v225, 0xffff0000, v236
	s_mov_b64 s[26:27], 0x2c0000
	v_lshl_add_u64 v[212:213], v[192:193], 0, s[26:27]
	v_add_f32_e32 v3, 1.0, v3
	v_rcp_f32_e32 v234, v3
	v_add_f32_e32 v3, v143, v225
	v_mul_f32_e32 v3, 0xbfb8aa3b, v3
	v_exp_f32_e32 v3, v3
	s_mov_b32 s26, 0x2c0000
	v_add_co_u32_e32 v150, vcc, s26, v192
	s_mov_b64 s[26:27], 0x2c2000
	s_nop 0
	v_addc_co_u32_e32 v151, vcc, 0, v193, vcc
	v_lshl_add_u64 v[214:215], v[192:193], 0, s[26:27]
	s_mov_b32 s26, 0x2c2000
	v_and_b32_e32 v233, 0xffff0000, v238
	s_waitcnt vmcnt(2)
	v_and_b32_e32 v231, 0xffff0000, v240
	v_add_f32_e32 v3, 1.0, v3
	v_add_co_u32_e32 v152, vcc, s26, v192
	v_add_f32_e32 v225, v147, v231
	v_rcp_f32_e32 v231, v3
	v_add_f32_e32 v3, v127, v233
	v_addc_co_u32_e32 v153, vcc, 0, v193, vcc
	v_mul_f32_e32 v3, 0xbfb8aa3b, v3
	global_load_dwordx4 v[154:157], v[150:151], off
	s_nop 0
	global_load_dwordx4 v[150:153], v[152:153], off
	v_exp_f32_e32 v3, v3
	v_lshlrev_b32_e32 v232, 16, v242
	v_add_f32_e32 v229, v130, v232
	v_lshlrev_b32_e32 v227, 16, v237
	v_and_b32_e32 v235, 0xffff0000, v242
	v_mul_f32_e32 v229, 0xbfb8aa3b, v229
	v_mul_f32_e32 v225, 0xbfb8aa3b, v225
	v_add_f32_e32 v3, 1.0, v3
	v_exp_f32_e32 v232, v229
	v_exp_f32_e32 v229, v225
	v_add_f32_e32 v225, v131, v235
	v_rcp_f32_e32 v235, v3
	v_add_f32_e32 v3, v144, v227
	v_mul_f32_e32 v3, 0xbfb8aa3b, v3
	v_exp_f32_e32 v3, v3
	v_lshlrev_b32_e32 v236, 16, v241
	v_mul_f32_e32 v225, 0xbfb8aa3b, v225
	v_exp_f32_e32 v233, v225
	v_add_f32_e32 v225, v148, v236
	v_lshlrev_b32_e32 v245, 16, v239
	v_lshlrev_b32_e32 v228, 16, v240
	v_lshlrev_b32_e32 v240, 16, v243
	v_mul_f32_e32 v225, 0xbfb8aa3b, v225
	v_add_f32_e32 v3, 1.0, v3
	v_and_b32_e32 v237, 0xffff0000, v237
	v_exp_f32_e32 v236, v225
	v_rcp_f32_e32 v238, v3
	v_add_f32_e32 v3, v128, v245
	v_add_f32_e32 v225, v132, v240
	v_and_b32_e32 v246, 0xffff0000, v239
	v_and_b32_e32 v239, 0xffff0000, v241
	v_mul_f32_e32 v3, 0xbfb8aa3b, v3
	v_mul_f32_e32 v225, 0xbfb8aa3b, v225
	v_add_f32_e32 v227, v145, v237
	v_exp_f32_e32 v3, v3
	v_exp_f32_e32 v240, v225
	v_add_f32_e32 v225, v149, v239
	v_mul_f32_e32 v227, 0xbfb8aa3b, v227
	v_exp_f32_e32 v227, v227
	v_mul_f32_e32 v225, 0xbfb8aa3b, v225
	v_exp_f32_e32 v237, v225
	v_add_f32_e32 v225, v129, v246
	v_mul_f32_e32 v225, 0xbfb8aa3b, v225
	v_add_f32_e32 v3, 1.0, v3
	v_exp_f32_e32 v225, v225
	v_and_b32_e32 v241, 0xffff0000, v243
	v_rcp_f32_e32 v242, v3
	v_add_f32_e32 v3, 1.0, v227
	v_rcp_f32_e32 v239, v3
	v_add_f32_e32 v3, v133, v241
	v_add_f32_e32 v228, v146, v228
	v_mul_f32_e32 v3, 0xbfb8aa3b, v3
	v_mul_f32_e32 v228, 0xbfb8aa3b, v228
	v_exp_f32_e32 v241, v3
	v_add_f32_e32 v3, 1.0, v225
	v_exp_f32_e32 v228, v228
	v_rcp_f32_e32 v243, v3
	s_waitcnt vmcnt(3)
	v_lshlrev_b32_e32 v3, 16, v162
	v_add_f32_e32 v3, v142, v3
	v_mul_f32_e32 v3, 0xbfb8aa3b, v3
	v_exp_f32_e32 v3, v3
	v_pk_add_f32 v[236:237], v[236:237], 1.0 op_sel_hi:[1,0]
	v_pk_add_f32 v[228:229], v[228:229], 1.0 op_sel_hi:[1,0]
	v_and_b32_e32 v225, 0xffff0000, v162
	v_pk_mul_f32 v[228:229], v[228:229], v[230:231]
	v_pk_mul_f32 v[230:231], v[236:237], v[238:239]
	v_pk_mul_f32 v[90:91], v[90:91], v[228:229]
	v_pk_mul_f32 v[92:93], v[92:93], v[230:231]
	v_pk_add_f32 v[228:229], v[240:241], 1.0 op_sel_hi:[1,0]
	v_pk_add_f32 v[230:231], v[232:233], 1.0 op_sel_hi:[1,0]
	v_pk_mul_f32 v[228:229], v[228:229], v[242:243]
	v_pk_mul_f32 v[230:231], v[230:231], v[234:235]
	v_lshlrev_b32_e32 v162, 16, v164
	v_add_f32_e32 v3, 1.0, v3
	v_pk_mul_f32 v[88:89], v[88:89], v[228:229]
	v_pk_mul_f32 v[86:87], v[86:87], v[230:231]
	s_waitcnt vmcnt(2)
; __device__ __forceinline__ void unpack8(const u32x4 w, float (&v)[8]) { v[0] = bf_lo(w.x); v[1] = bf_hi(w.x); v[2] = bf_lo(w.y); v[3] = bf_hi(w.y); v[4] = bf_lo(w.z); v[5] = bf_hi(w.z); v[6] = bf_lo(w.w); v[7] = bf_hi(w.w); }
;     __device__ __forceinline__ void after(int te, f32x4 (&acc)[2][2][4][2], const Unit& u, int wr, int wc, int fr, int fq) const {
;     ...
;                     for (int m = 0; m < 4; ++m) { const size_t r = (size_t)(row0 + ai * HALF + m * 16); gs[m] = *(const u32x4*)(proj + r * LDP + PGS + c); ga[m] = *(const u32x4*)(proj + r * LDP + PGA + c); }
; #pragma unroll
;                     for (int m = 0; m < 4; ++m) { float vs[8], va[8]; unpack8(gs[m], vs); unpack8(ga[m], va);
; #pragma unroll
;                         for (int e = 0; e < 4; ++e) {
;                             acc[ai][bj][m][0][e] *= (1.f + __expf(-(va[e] + a0[e]))) * __builtin_amdgcn_rcpf(1.f + __expf(-(vs[e] + s0[e])));
;                             acc[ai][bj][m][1][e] *= (1.f + __expf(-(va[4 + e] + a1[e]))) * __builtin_amdgcn_rcpf(1.f + __expf(-(vs[4 + e] + s1[e]))); } }
	v_lshlrev_b32_e32 v228, 16, v159
	v_and_b32_e32 v234, 0xffff0000, v159
	v_lshlrev_b32_e32 v159, 16, v160
	v_and_b32_e32 v230, 0xffff0000, v160
	v_rcp_f32_e32 v160, v3
	v_add_f32_e32 v3, v126, v162
	v_mul_f32_e32 v3, 0xbfb8aa3b, v3
	v_exp_f32_e32 v3, v3
	v_lshlrev_b32_e32 v227, 16, v163
	v_and_b32_e32 v229, 0xffff0000, v163
	v_and_b32_e32 v163, 0xffff0000, v164
	v_lshlrev_b32_e32 v164, 16, v158
	v_add_f32_e32 v3, 1.0, v3
	v_lshlrev_b32_e32 v231, 16, v165
	v_and_b32_e32 v233, 0xffff0000, v165
	v_and_b32_e32 v165, 0xffff0000, v158
	v_add_f32_e32 v158, v146, v164
	v_rcp_f32_e32 v164, v3
	v_add_f32_e32 v3, v143, v225
	v_mul_f32_e32 v3, 0xbfb8aa3b, v3
	v_exp_f32_e32 v3, v3
	v_lshlrev_b32_e32 v232, 16, v161
	v_and_b32_e32 v235, 0xffff0000, v161
	v_add_f32_e32 v159, v130, v159
	v_add_f32_e32 v3, 1.0, v3
	v_rcp_f32_e32 v161, v3
	v_add_f32_e32 v3, v127, v163
	v_mul_f32_e32 v3, 0xbfb8aa3b, v3
	v_exp_f32_e32 v3, v3
	v_mul_f32_e32 v159, 0xbfb8aa3b, v159
	v_exp_f32_e32 v162, v159
	v_add_f32_e32 v159, v147, v165
	v_add_f32_e32 v3, 1.0, v3
	v_rcp_f32_e32 v165, v3
	v_add_f32_e32 v3, v144, v227
	v_mul_f32_e32 v3, 0xbfb8aa3b, v3
	v_exp_f32_e32 v3, v3
	v_add_f32_e32 v163, v131, v230
	v_add_f32_e32 v225, v148, v228
	v_add_f32_e32 v227, v145, v229
	v_add_f32_e32 v3, 1.0, v3
	v_rcp_f32_e32 v230, v3
	v_add_f32_e32 v3, v128, v231
	v_mul_f32_e32 v3, 0xbfb8aa3b, v3
	v_mul_f32_e32 v225, 0xbfb8aa3b, v225
	v_exp_f32_e32 v3, v3
	v_mul_f32_e32 v227, 0xbfb8aa3b, v227
	v_exp_f32_e32 v228, v225
	v_add_f32_e32 v225, v132, v232
	v_exp_f32_e32 v227, v227
	v_mul_f32_e32 v225, 0xbfb8aa3b, v225
	v_exp_f32_e32 v232, v225
	v_add_f32_e32 v225, v149, v234
	v_mul_f32_e32 v158, 0xbfb8aa3b, v158
	v_mul_f32_e32 v159, 0xbfb8aa3b, v159
	v_add_f32_e32 v3, 1.0, v3
	v_mul_f32_e32 v225, 0xbfb8aa3b, v225
	v_exp_f32_e32 v158, v158
	v_exp_f32_e32 v159, v159
	v_exp_f32_e32 v229, v225
	v_rcp_f32_e32 v234, v3
	v_add_f32_e32 v3, 1.0, v227
	v_rcp_f32_e32 v231, v3
	v_pk_add_f32 v[228:229], v[228:229], 1.0 op_sel_hi:[1,0]
	v_pk_add_f32 v[158:159], v[158:159], 1.0 op_sel_hi:[1,0]
	v_add_f32_e32 v3, v133, v235
	v_pk_mul_f32 v[158:159], v[158:159], v[160:161]
	v_pk_mul_f32 v[160:161], v[228:229], v[230:231]
	v_mul_f32_e32 v3, 0xbfb8aa3b, v3
	v_pk_mul_f32 v[84:85], v[84:85], v[160:161]
	v_add_f32_e32 v160, v129, v233
	v_mul_f32_e32 v160, 0xbfb8aa3b, v160
	v_exp_f32_e32 v160, v160
	v_exp_f32_e32 v233, v3
	s_waitcnt vmcnt(1)
	v_lshlrev_b32_e32 v225, 16, v155
	v_and_b32_e32 v227, 0xffff0000, v155
	v_add_f32_e32 v3, 1.0, v160
	v_rcp_f32_e32 v235, v3
	v_lshlrev_b32_e32 v3, 16, v154
	v_add_f32_e32 v3, v142, v3
	v_mul_f32_e32 v3, 0xbfb8aa3b, v3
	v_exp_f32_e32 v3, v3
	v_lshlrev_b32_e32 v155, 16, v156
	v_and_b32_e32 v236, 0xffff0000, v156
	s_waitcnt vmcnt(0)
	v_lshlrev_b32_e32 v156, 16, v150
	v_add_f32_e32 v3, 1.0, v3
	v_mul_f32_e32 v163, 0xbfb8aa3b, v163
	v_add_f32_e32 v142, v146, v156
	v_rcp_f32_e32 v146, v3
	v_add_f32_e32 v3, v126, v155
	v_exp_f32_e32 v163, v163
	v_mul_f32_e32 v3, 0xbfb8aa3b, v3
	v_exp_f32_e32 v3, v3
	v_pk_mul_f32 v[82:83], v[82:83], v[158:159]
	v_pk_add_f32 v[158:159], v[232:233], 1.0 op_sel_hi:[1,0]
	v_pk_add_f32 v[160:161], v[162:163], 1.0 op_sel_hi:[1,0]
	v_pk_mul_f32 v[158:159], v[158:159], v[234:235]
	v_pk_mul_f32 v[160:161], v[160:161], v[164:165]
	v_and_b32_e32 v150, 0xffff0000, v150
	v_lshlrev_b32_e32 v239, 16, v151
	v_and_b32_e32 v240, 0xffff0000, v151
	v_lshlrev_b32_e32 v151, 16, v152
	global_load_dwordx4 v[228:231], v[192:193], off offset:256
	global_load_dwordx4 v[232:235], v[202:203], off offset:256
	v_add_f32_e32 v3, 1.0, v3
	v_pk_mul_f32 v[80:81], v[80:81], v[158:159]
	v_pk_mul_f32 v[78:79], v[78:79], v[160:161]
	v_and_b32_e32 v241, 0xffff0000, v152
	v_lshlrev_b32_e32 v242, 16, v153
	v_and_b32_e32 v243, 0xffff0000, v153
	v_add_f32_e32 v126, v130, v151
	v_rcp_f32_e32 v130, v3
	v_add_f32_e32 v3, v147, v150
	global_load_dwordx4 v[150:153], v[196:197], off offset:528
	global_load_dwordx4 v[158:161], v[196:197], off offset:512
	v_and_b32_e32 v154, 0xffff0000, v154
	v_lshlrev_b32_e32 v237, 16, v157
	v_and_b32_e32 v238, 0xffff0000, v157
	v_add_f32_e32 v143, v143, v154
	global_load_dwordx4 v[154:157], v[198:199], off offset:528
	global_load_dwordx4 v[162:165], v[198:199], off offset:512
	v_mul_f32_e32 v143, 0xbfb8aa3b, v143
	v_exp_f32_e32 v147, v143
	v_mul_f32_e32 v3, 0xbfb8aa3b, v3
	v_exp_f32_e32 v143, v3
	v_add_f32_e32 v145, v145, v227
	v_add_f32_e32 v3, 1.0, v147
	v_rcp_f32_e32 v147, v3
	v_add_f32_e32 v3, v127, v236
	v_mul_f32_e32 v3, 0xbfb8aa3b, v3
	v_exp_f32_e32 v3, v3
	v_add_f32_e32 v127, v131, v241
	v_mul_f32_e32 v145, 0xbfb8aa3b, v145
	v_add_f32_e32 v129, v129, v238
	v_add_f32_e32 v3, 1.0, v3
	v_rcp_f32_e32 v131, v3
	v_add_f32_e32 v3, v144, v225
	v_mul_f32_e32 v3, 0xbfb8aa3b, v3
	v_exp_f32_e32 v3, v3
	v_add_f32_e32 v144, v148, v239
	v_mul_f32_e32 v129, 0xbfb8aa3b, v129
	v_mul_f32_e32 v142, 0xbfb8aa3b, v142
	v_add_f32_e32 v3, 1.0, v3
	v_rcp_f32_e32 v148, v3
	v_add_f32_e32 v3, v128, v237
	v_mul_f32_e32 v3, 0xbfb8aa3b, v3
	v_exp_f32_e32 v3, v3
	v_add_f32_e32 v128, v132, v242
	v_add_f32_e32 v132, v149, v240
	v_exp_f32_e32 v149, v145
	v_add_f32_e32 v3, 1.0, v3
	v_mul_f32_e32 v132, 0xbfb8aa3b, v132
	v_exp_f32_e32 v145, v132
	v_rcp_f32_e32 v132, v3
	v_add_f32_e32 v3, 1.0, v149
	v_rcp_f32_e32 v149, v3
	v_add_f32_e32 v3, v133, v243
	v_exp_f32_e32 v133, v129
	v_mul_f32_e32 v126, 0xbfb8aa3b, v126
	v_mul_f32_e32 v127, 0xbfb8aa3b, v127
	v_mul_f32_e32 v144, 0xbfb8aa3b, v144
	v_mul_f32_e32 v128, 0xbfb8aa3b, v128
	v_mul_f32_e32 v3, 0xbfb8aa3b, v3
	v_exp_f32_e32 v142, v142
	v_exp_f32_e32 v126, v126
	v_exp_f32_e32 v127, v127
	v_exp_f32_e32 v144, v144
	v_exp_f32_e32 v128, v128
	v_exp_f32_e32 v129, v3
	v_add_f32_e32 v3, 1.0, v133
	v_rcp_f32_e32 v133, v3
	v_pk_add_f32 v[144:145], v[144:145], 1.0 op_sel_hi:[1,0]
	v_pk_add_f32 v[142:143], v[142:143], 1.0 op_sel_hi:[1,0]
	v_pk_add_f32 v[128:129], v[128:129], 1.0 op_sel_hi:[1,0]
	v_pk_add_f32 v[126:127], v[126:127], 1.0 op_sel_hi:[1,0]
	v_pk_mul_f32 v[142:143], v[142:143], v[146:147]
	v_pk_mul_f32 v[144:145], v[144:145], v[148:149]
	v_pk_mul_f32 v[126:127], v[126:127], v[130:131]
	v_pk_mul_f32 v[128:129], v[128:129], v[132:133]
	v_pk_mul_f32 v[76:77], v[76:77], v[144:145]
	v_pk_mul_f32 v[74:75], v[74:75], v[142:143]
	v_pk_mul_f32 v[72:73], v[72:73], v[128:129]
	v_pk_mul_f32 v[70:71], v[70:71], v[126:127]
	global_load_dwordx4 v[196:199], v[4:5], off offset:256
	global_load_dwordx4 v[236:239], v[186:187], off offset:256
	global_load_dwordx4 v[146:149], v[188:189], off offset:256
	global_load_dwordx4 v[142:145], v[190:191], off offset:256
	global_load_dwordx4 v[130:133], v[194:195], off offset:256
	global_load_dwordx4 v[126:129], v[200:201], off offset:256
	s_waitcnt vmcnt(11)
; __device__ __forceinline__ void unpack8(const u32x4 w, float (&v)[8]) { v[0] = bf_lo(w.x); v[1] = bf_hi(w.x); v[2] = bf_lo(w.y); v[3] = bf_hi(w.y); v[4] = bf_lo(w.z); v[5] = bf_hi(w.z); v[6] = bf_lo(w.w); v[7] = bf_hi(w.w); }
;     __device__ __forceinline__ void after(int te, f32x4 (&acc)[2][2][4][2], const Unit& u, int wr, int wc, int fr, int fq) const {
;     ...
;                     for (int m = 0; m < 4; ++m) { float vs[8], va[8]; unpack8(gs[m], vs); unpack8(ga[m], va);
; #pragma unroll
;                         for (int e = 0; e < 4; ++e) {
;                             acc[ai][bj][m][0][e] *= (1.f + __expf(-(va[e] + a0[e]))) * __builtin_amdgcn_rcpf(1.f + __expf(-(vs[e] + s0[e])));
;                             acc[ai][bj][m][1][e] *= (1.f + __expf(-(va[4 + e] + a1[e]))) * __builtin_amdgcn_rcpf(1.f + __expf(-(vs[4 + e] + s1[e]))); } }
	v_lshlrev_b32_e32 v3, 16, v228
	v_lshlrev_b32_e32 v187, 16, v230
	v_and_b32_e32 v5, 0xffff0000, v228
	s_waitcnt vmcnt(10)
	v_lshlrev_b32_e32 v188, 16, v234
	v_and_b32_e32 v189, 0xffff0000, v230
	v_lshlrev_b32_e32 v192, 16, v229
	v_and_b32_e32 v191, 0xffff0000, v232
	v_lshlrev_b32_e32 v195, 16, v231
	v_lshlrev_b32_e32 v194, 16, v233
	v_and_b32_e32 v193, 0xffff0000, v229
	v_lshlrev_b32_e32 v203, 16, v235
	s_waitcnt vmcnt(8)
	v_add_f32_e32 v3, v158, v3
	v_mul_f32_e32 v3, 0xbfb8aa3b, v3
	v_exp_f32_e32 v3, v3
	v_add_f32_e32 v193, v161, v193
	v_mul_f32_e32 v193, 0xbfb8aa3b, v193
	v_lshlrev_b32_e32 v4, 16, v232
	v_add_f32_e32 v3, 1.0, v3
	v_rcp_f32_e32 v186, v3
	v_add_f32_e32 v3, v150, v187
	v_mul_f32_e32 v3, 0xbfb8aa3b, v3
	v_exp_f32_e32 v3, v3
	s_waitcnt vmcnt(7)
	v_add_f32_e32 v187, v154, v188
	v_mul_f32_e32 v187, 0xbfb8aa3b, v187
	v_exp_f32_e32 v188, v187
	v_add_f32_e32 v3, 1.0, v3
	v_rcp_f32_e32 v190, v3
	v_add_f32_e32 v3, v159, v5
	v_mul_f32_e32 v3, 0xbfb8aa3b, v3
	v_exp_f32_e32 v3, v3
	s_waitcnt vmcnt(6)
	v_add_f32_e32 v5, v163, v191
	v_and_b32_e32 v202, 0xffff0000, v233
	v_and_b32_e32 v200, 0xffff0000, v234
	v_add_f32_e32 v3, 1.0, v3
	v_rcp_f32_e32 v187, v3
	v_add_f32_e32 v3, v151, v189
	v_mul_f32_e32 v3, 0xbfb8aa3b, v3
	v_exp_f32_e32 v3, v3
	v_add_f32_e32 v4, v162, v4
	v_add_f32_e32 v189, v155, v200
	v_mul_f32_e32 v4, 0xbfb8aa3b, v4
	v_add_f32_e32 v3, 1.0, v3
	v_rcp_f32_e32 v191, v3
	v_add_f32_e32 v3, v160, v192
	v_mul_f32_e32 v3, 0xbfb8aa3b, v3
	v_exp_f32_e32 v3, v3
	v_add_f32_e32 v192, v164, v194
	v_mul_f32_e32 v5, 0xbfb8aa3b, v5
	v_mul_f32_e32 v192, 0xbfb8aa3b, v192
	v_add_f32_e32 v3, 1.0, v3
	v_rcp_f32_e32 v194, v3
	v_add_f32_e32 v3, v152, v195
	v_mul_f32_e32 v3, 0xbfb8aa3b, v3
	v_exp_f32_e32 v3, v3
	v_add_f32_e32 v195, v156, v203
	v_exp_f32_e32 v203, v193
	v_mul_f32_e32 v195, 0xbfb8aa3b, v195
	v_exp_f32_e32 v200, v195
	v_add_f32_e32 v195, v165, v202
	v_add_f32_e32 v3, 1.0, v3
	v_mul_f32_e32 v193, 0xbfb8aa3b, v195
	v_exp_f32_e32 v4, v4
	v_exp_f32_e32 v5, v5
	v_exp_f32_e32 v192, v192
	v_exp_f32_e32 v193, v193
	v_rcp_f32_e32 v202, v3
	v_add_f32_e32 v3, 1.0, v203
	v_rcp_f32_e32 v195, v3
	v_pk_add_f32 v[192:193], v[192:193], 1.0 op_sel_hi:[1,0]
	v_pk_add_f32 v[4:5], v[4:5], 1.0 op_sel_hi:[1,0]
	v_and_b32_e32 v201, 0xffff0000, v231
	v_pk_mul_f32 v[4:5], v[4:5], v[186:187]
	v_pk_mul_f32 v[186:187], v[192:193], v[194:195]
	v_and_b32_e32 v225, 0xffff0000, v235
	v_pk_mul_f32 v[68:69], v[68:69], v[186:187]
	v_add_f32_e32 v186, v153, v201
	v_mul_f32_e32 v186, 0xbfb8aa3b, v186
	v_exp_f32_e32 v186, v186
	v_add_f32_e32 v3, v157, v225
	v_mul_f32_e32 v3, 0xbfb8aa3b, v3
	v_exp_f32_e32 v201, v3
	v_add_f32_e32 v3, 1.0, v186
	v_mul_f32_e32 v189, 0xbfb8aa3b, v189
	v_rcp_f32_e32 v203, v3
	s_waitcnt vmcnt(5)
	v_lshlrev_b32_e32 v3, 16, v196
	v_exp_f32_e32 v189, v189
	v_add_f32_e32 v3, v158, v3
	v_mul_f32_e32 v3, 0xbfb8aa3b, v3
	v_exp_f32_e32 v3, v3
	v_pk_add_f32 v[186:187], v[188:189], 1.0 op_sel_hi:[1,0]
	v_pk_mul_f32 v[66:67], v[66:67], v[4:5]
	v_pk_mul_f32 v[186:187], v[186:187], v[190:191]
	v_add_f32_e32 v3, 1.0, v3
	v_pk_mul_f32 v[62:63], v[62:63], v[186:187]
	v_lshlrev_b32_e32 v187, 16, v198
	v_rcp_f32_e32 v186, v3
	v_add_f32_e32 v3, v150, v187
	v_mul_f32_e32 v3, 0xbfb8aa3b, v3
	v_exp_f32_e32 v3, v3
	v_pk_add_f32 v[4:5], v[200:201], 1.0 op_sel_hi:[1,0]
	s_waitcnt vmcnt(4)
	v_lshlrev_b32_e32 v188, 16, v238
	v_pk_mul_f32 v[4:5], v[4:5], v[202:203]
	v_add_f32_e32 v3, 1.0, v3
	v_pk_mul_f32 v[64:65], v[64:65], v[4:5]
	v_and_b32_e32 v5, 0xffff0000, v196
	v_rcp_f32_e32 v190, v3
	v_add_f32_e32 v3, v159, v5
	v_mul_f32_e32 v3, 0xbfb8aa3b, v3
	v_exp_f32_e32 v3, v3
	v_add_f32_e32 v187, v154, v188
	v_and_b32_e32 v189, 0xffff0000, v198
	v_mul_f32_e32 v187, 0xbfb8aa3b, v187
	v_add_f32_e32 v3, 1.0, v3
	v_exp_f32_e32 v188, v187
	v_rcp_f32_e32 v187, v3
	v_add_f32_e32 v3, v151, v189
	v_mul_f32_e32 v3, 0xbfb8aa3b, v3
	v_exp_f32_e32 v3, v3
	v_lshlrev_b32_e32 v192, 16, v197
	v_and_b32_e32 v191, 0xffff0000, v236
	v_add_f32_e32 v5, v163, v191
	v_add_f32_e32 v3, 1.0, v3
	v_rcp_f32_e32 v191, v3
	v_add_f32_e32 v3, v160, v192
	v_mul_f32_e32 v3, 0xbfb8aa3b, v3
	v_exp_f32_e32 v3, v3
	v_lshlrev_b32_e32 v195, 16, v199
	v_lshlrev_b32_e32 v194, 16, v237
	v_and_b32_e32 v193, 0xffff0000, v197
	v_add_f32_e32 v3, 1.0, v3
	v_add_f32_e32 v192, v164, v194
	v_rcp_f32_e32 v194, v3
	v_add_f32_e32 v3, v152, v195
	v_mul_f32_e32 v3, 0xbfb8aa3b, v3
	v_add_f32_e32 v193, v161, v193
	v_and_b32_e32 v197, 0xffff0000, v199
	v_lshlrev_b32_e32 v199, 16, v239
	v_exp_f32_e32 v3, v3
	v_mul_f32_e32 v193, 0xbfb8aa3b, v193
	v_add_f32_e32 v195, v156, v199
	v_exp_f32_e32 v199, v193
	v_lshlrev_b32_e32 v4, 16, v236
	v_and_b32_e32 v198, 0xffff0000, v237
	v_and_b32_e32 v196, 0xffff0000, v238
	v_mul_f32_e32 v195, 0xbfb8aa3b, v195
	v_add_f32_e32 v4, v162, v4
	v_add_f32_e32 v189, v155, v196
	v_exp_f32_e32 v196, v195
	v_add_f32_e32 v195, v165, v198
	v_mul_f32_e32 v4, 0xbfb8aa3b, v4
	v_mul_f32_e32 v5, 0xbfb8aa3b, v5
	v_mul_f32_e32 v192, 0xbfb8aa3b, v192
	v_add_f32_e32 v3, 1.0, v3
	v_mul_f32_e32 v193, 0xbfb8aa3b, v195
	v_exp_f32_e32 v4, v4
	v_exp_f32_e32 v5, v5
	v_exp_f32_e32 v192, v192
	v_exp_f32_e32 v193, v193
	v_rcp_f32_e32 v198, v3
	v_add_f32_e32 v3, 1.0, v199
	v_rcp_f32_e32 v195, v3
	v_pk_add_f32 v[192:193], v[192:193], 1.0 op_sel_hi:[1,0]
	v_pk_add_f32 v[4:5], v[4:5], 1.0 op_sel_hi:[1,0]
	v_and_b32_e32 v200, 0xffff0000, v239
	v_pk_mul_f32 v[4:5], v[4:5], v[186:187]
	v_pk_mul_f32 v[186:187], v[192:193], v[194:195]
	v_add_f32_e32 v3, v157, v200
	v_pk_mul_f32 v[60:61], v[60:61], v[186:187]
	v_add_f32_e32 v186, v153, v197
	v_mul_f32_e32 v186, 0xbfb8aa3b, v186
	v_exp_f32_e32 v186, v186
	v_mul_f32_e32 v3, 0xbfb8aa3b, v3
	v_exp_f32_e32 v197, v3
	v_mul_f32_e32 v189, 0xbfb8aa3b, v189
	v_add_f32_e32 v3, 1.0, v186
	v_rcp_f32_e32 v199, v3
	s_waitcnt vmcnt(3)
; __device__ __forceinline__ void unpack8(const u32x4 w, float (&v)[8]) { v[0] = bf_lo(w.x); v[1] = bf_hi(w.x); v[2] = bf_lo(w.y); v[3] = bf_hi(w.y); v[4] = bf_lo(w.z); v[5] = bf_hi(w.z); v[6] = bf_lo(w.w); v[7] = bf_hi(w.w); }
;     __device__ __forceinline__ void after(int te, f32x4 (&acc)[2][2][4][2], const Unit& u, int wr, int wc, int fr, int fq) const {
;     ...
;                     for (int m = 0; m < 4; ++m) { const size_t r = (size_t)(row0 + ai * HALF + m * 16); gs[m] = *(const u32x4*)(proj + r * LDP + PGS + c); ga[m] = *(const u32x4*)(proj + r * LDP + PGA + c); }
; #pragma unroll
;                     for (int m = 0; m < 4; ++m) { float vs[8], va[8]; unpack8(gs[m], vs); unpack8(ga[m], va);
; #pragma unroll
;                         for (int e = 0; e < 4; ++e) {
;                             acc[ai][bj][m][0][e] *= (1.f + __expf(-(va[e] + a0[e]))) * __builtin_amdgcn_rcpf(1.f + __expf(-(vs[e] + s0[e])));
;                             acc[ai][bj][m][1][e] *= (1.f + __expf(-(va[4 + e] + a1[e]))) * __builtin_amdgcn_rcpf(1.f + __expf(-(vs[4 + e] + s1[e]))); } }
	v_lshlrev_b32_e32 v3, 16, v146
	v_add_f32_e32 v3, v158, v3
	v_exp_f32_e32 v189, v189
	v_mul_f32_e32 v3, 0xbfb8aa3b, v3
	v_exp_f32_e32 v3, v3
	v_pk_mul_f32 v[58:59], v[58:59], v[4:5]
	v_pk_add_f32 v[4:5], v[196:197], 1.0 op_sel_hi:[1,0]
	v_pk_add_f32 v[186:187], v[188:189], 1.0 op_sel_hi:[1,0]
	v_pk_mul_f32 v[4:5], v[4:5], v[198:199]
	v_pk_mul_f32 v[186:187], v[186:187], v[190:191]
	v_pk_mul_f32 v[56:57], v[56:57], v[4:5]
	v_and_b32_e32 v5, 0xffff0000, v146
	v_lshlrev_b32_e32 v146, 16, v148
	v_add_f32_e32 v3, 1.0, v3
	v_pk_mul_f32 v[54:55], v[54:55], v[186:187]
	v_lshlrev_b32_e32 v186, 16, v147
	v_and_b32_e32 v187, 0xffff0000, v147
	v_and_b32_e32 v147, 0xffff0000, v148
	s_waitcnt vmcnt(2)
	v_lshlrev_b32_e32 v4, 16, v142
	v_and_b32_e32 v148, 0xffff0000, v142
	v_rcp_f32_e32 v142, v3
	v_add_f32_e32 v3, v150, v146
	v_mul_f32_e32 v3, 0xbfb8aa3b, v3
	v_exp_f32_e32 v3, v3
	v_lshlrev_b32_e32 v188, 16, v149
	v_and_b32_e32 v189, 0xffff0000, v149
	v_lshlrev_b32_e32 v149, 16, v143
	v_add_f32_e32 v3, 1.0, v3
	v_rcp_f32_e32 v146, v3
	v_add_f32_e32 v3, v159, v5
	v_mul_f32_e32 v3, 0xbfb8aa3b, v3
	v_exp_f32_e32 v3, v3
	v_and_b32_e32 v190, 0xffff0000, v143
	v_lshlrev_b32_e32 v143, 16, v144
	v_add_f32_e32 v143, v154, v143
	v_mul_f32_e32 v143, 0xbfb8aa3b, v143
	v_add_f32_e32 v3, 1.0, v3
	v_and_b32_e32 v191, 0xffff0000, v144
	v_exp_f32_e32 v144, v143
	v_rcp_f32_e32 v143, v3
	v_add_f32_e32 v3, v151, v147
	v_mul_f32_e32 v3, 0xbfb8aa3b, v3
	v_exp_f32_e32 v3, v3
	v_add_f32_e32 v187, v161, v187
	v_lshlrev_b32_e32 v192, 16, v145
	v_mul_f32_e32 v187, 0xbfb8aa3b, v187
	v_add_f32_e32 v3, 1.0, v3
	v_rcp_f32_e32 v147, v3
	v_add_f32_e32 v3, v160, v186
	v_mul_f32_e32 v3, 0xbfb8aa3b, v3
	v_exp_f32_e32 v3, v3
	v_add_f32_e32 v5, v163, v148
	v_add_f32_e32 v148, v164, v149
	v_add_f32_e32 v149, v156, v192
	v_add_f32_e32 v3, 1.0, v3
	v_rcp_f32_e32 v186, v3
	v_add_f32_e32 v3, v152, v188
	v_mul_f32_e32 v3, 0xbfb8aa3b, v3
	v_exp_f32_e32 v3, v3
	v_exp_f32_e32 v187, v187
	v_mul_f32_e32 v149, 0xbfb8aa3b, v149
	v_add_f32_e32 v4, v162, v4
	v_exp_f32_e32 v188, v149
	v_add_f32_e32 v149, v165, v190
	v_mul_f32_e32 v4, 0xbfb8aa3b, v4
	v_mul_f32_e32 v5, 0xbfb8aa3b, v5
	v_mul_f32_e32 v148, 0xbfb8aa3b, v148
	v_add_f32_e32 v3, 1.0, v3
	v_mul_f32_e32 v149, 0xbfb8aa3b, v149
	v_exp_f32_e32 v4, v4
	v_exp_f32_e32 v5, v5
	v_exp_f32_e32 v148, v148
	v_exp_f32_e32 v149, v149
	v_rcp_f32_e32 v190, v3
	v_add_f32_e32 v3, 1.0, v187
	v_rcp_f32_e32 v187, v3
	v_pk_add_f32 v[148:149], v[148:149], 1.0 op_sel_hi:[1,0]
	v_pk_add_f32 v[4:5], v[4:5], 1.0 op_sel_hi:[1,0]
	v_and_b32_e32 v193, 0xffff0000, v145
	v_pk_mul_f32 v[4:5], v[4:5], v[142:143]
	v_pk_mul_f32 v[142:143], v[148:149], v[186:187]
	v_add_f32_e32 v3, v157, v193
	v_pk_mul_f32 v[52:53], v[52:53], v[142:143]
	v_add_f32_e32 v142, v153, v189
	v_mul_f32_e32 v142, 0xbfb8aa3b, v142
	v_mul_f32_e32 v3, 0xbfb8aa3b, v3
	v_exp_f32_e32 v142, v142
	v_exp_f32_e32 v189, v3
	v_pk_mul_f32 v[50:51], v[50:51], v[4:5]
	v_add_f32_e32 v3, 1.0, v142
	v_pk_add_f32 v[4:5], v[188:189], 1.0 op_sel_hi:[1,0]
	global_load_dwordx4 v[186:189], v[218:219], off offset:256
	v_add_f32_e32 v145, v155, v191
	v_rcp_f32_e32 v191, v3
	s_waitcnt vmcnt(2)
	v_lshlrev_b32_e32 v3, 16, v130
	v_mul_f32_e32 v145, 0xbfb8aa3b, v145
	v_add_f32_e32 v3, v158, v3
	v_exp_f32_e32 v145, v145
	v_mul_f32_e32 v3, 0xbfb8aa3b, v3
	v_exp_f32_e32 v3, v3
	v_pk_mul_f32 v[4:5], v[4:5], v[190:191]
	v_pk_add_f32 v[142:143], v[144:145], 1.0 op_sel_hi:[1,0]
	v_pk_mul_f32 v[48:49], v[48:49], v[4:5]
	v_pk_mul_f32 v[142:143], v[142:143], v[146:147]
	v_and_b32_e32 v5, 0xffff0000, v130
	v_lshlrev_b32_e32 v130, 16, v132
	v_add_f32_e32 v3, 1.0, v3
	v_pk_mul_f32 v[46:47], v[46:47], v[142:143]
	v_lshlrev_b32_e32 v142, 16, v131
	v_and_b32_e32 v143, 0xffff0000, v131
	v_and_b32_e32 v131, 0xffff0000, v132
	s_waitcnt vmcnt(1)
	v_lshlrev_b32_e32 v4, 16, v126
	v_and_b32_e32 v132, 0xffff0000, v126
	v_rcp_f32_e32 v126, v3
	v_add_f32_e32 v3, v150, v130
	v_mul_f32_e32 v3, 0xbfb8aa3b, v3
	v_exp_f32_e32 v3, v3
	global_load_dwordx4 v[190:193], v[216:217], off offset:256
	v_lshlrev_b32_e32 v144, 16, v133
	v_and_b32_e32 v145, 0xffff0000, v133
	v_add_f32_e32 v3, 1.0, v3
	v_rcp_f32_e32 v130, v3
	v_add_f32_e32 v3, v159, v5
	v_mul_f32_e32 v3, 0xbfb8aa3b, v3
	v_exp_f32_e32 v3, v3
	v_lshlrev_b32_e32 v133, 16, v127
	v_and_b32_e32 v146, 0xffff0000, v127
	v_lshlrev_b32_e32 v127, 16, v128
	v_add_f32_e32 v127, v154, v127
	v_mul_f32_e32 v127, 0xbfb8aa3b, v127
	v_add_f32_e32 v3, 1.0, v3
	v_and_b32_e32 v147, 0xffff0000, v128
	v_exp_f32_e32 v128, v127
	v_rcp_f32_e32 v127, v3
	v_add_f32_e32 v3, v151, v131
	v_mul_f32_e32 v3, 0xbfb8aa3b, v3
	v_exp_f32_e32 v3, v3
	v_add_f32_e32 v143, v161, v143
	v_lshlrev_b32_e32 v148, 16, v129
	v_mul_f32_e32 v143, 0xbfb8aa3b, v143
	v_add_f32_e32 v3, 1.0, v3
	v_rcp_f32_e32 v131, v3
	v_add_f32_e32 v3, v160, v142
	v_mul_f32_e32 v3, 0xbfb8aa3b, v3
	v_exp_f32_e32 v3, v3
	v_add_f32_e32 v5, v163, v132
	v_add_f32_e32 v132, v164, v133
	v_add_f32_e32 v133, v156, v148
	v_add_f32_e32 v3, 1.0, v3
	v_rcp_f32_e32 v142, v3
	v_add_f32_e32 v3, v152, v144
	v_mul_f32_e32 v3, 0xbfb8aa3b, v3
	v_exp_f32_e32 v3, v3
	v_exp_f32_e32 v143, v143
	v_mul_f32_e32 v133, 0xbfb8aa3b, v133
	v_add_f32_e32 v4, v162, v4
	v_exp_f32_e32 v144, v133
	v_add_f32_e32 v133, v165, v146
	v_mul_f32_e32 v4, 0xbfb8aa3b, v4
	v_mul_f32_e32 v5, 0xbfb8aa3b, v5
	v_mul_f32_e32 v132, 0xbfb8aa3b, v132
	v_add_f32_e32 v3, 1.0, v3
	v_mul_f32_e32 v133, 0xbfb8aa3b, v133
	v_exp_f32_e32 v4, v4
	v_exp_f32_e32 v5, v5
	v_exp_f32_e32 v132, v132
	v_exp_f32_e32 v133, v133
	v_rcp_f32_e32 v146, v3
	v_add_f32_e32 v3, 1.0, v143
	v_rcp_f32_e32 v143, v3
	v_pk_add_f32 v[132:133], v[132:133], 1.0 op_sel_hi:[1,0]
	v_pk_add_f32 v[4:5], v[4:5], 1.0 op_sel_hi:[1,0]
	v_and_b32_e32 v149, 0xffff0000, v129
	v_pk_mul_f32 v[4:5], v[4:5], v[126:127]
	v_pk_mul_f32 v[126:127], v[132:133], v[142:143]
	v_add_f32_e32 v129, v155, v147
	v_pk_mul_f32 v[44:45], v[44:45], v[126:127]
	v_add_f32_e32 v126, v153, v145
	v_mul_f32_e32 v126, 0xbfb8aa3b, v126
	v_exp_f32_e32 v126, v126
	v_mul_f32_e32 v129, 0xbfb8aa3b, v129
	v_add_f32_e32 v3, v157, v149
	v_exp_f32_e32 v129, v129
	v_mul_f32_e32 v3, 0xbfb8aa3b, v3
	v_exp_f32_e32 v145, v3
	v_add_f32_e32 v3, 1.0, v126
	v_rcp_f32_e32 v147, v3
	v_pk_add_f32 v[126:127], v[128:129], 1.0 op_sel_hi:[1,0]
	v_pk_mul_f32 v[42:43], v[42:43], v[4:5]
	v_pk_add_f32 v[4:5], v[144:145], 1.0 op_sel_hi:[1,0]
	v_pk_mul_f32 v[126:127], v[126:127], v[130:131]
	v_pk_mul_f32 v[4:5], v[4:5], v[146:147]
	v_pk_mul_f32 v[38:39], v[38:39], v[126:127]
	global_load_dwordx4 v[194:197], v[204:205], off offset:256
	global_load_dwordx4 v[198:201], v[206:207], off offset:256
	global_load_dwordx4 v[146:149], v[208:209], off offset:256
	global_load_dwordx4 v[142:145], v[210:211], off offset:256
	global_load_dwordx4 v[130:133], v[212:213], off offset:256
	global_load_dwordx4 v[126:129], v[214:215], off offset:256
	s_waitcnt vmcnt(7)
; __device__ __forceinline__ void unpack8(const u32x4 w, float (&v)[8]) { v[0] = bf_lo(w.x); v[1] = bf_hi(w.x); v[2] = bf_lo(w.y); v[3] = bf_hi(w.y); v[4] = bf_lo(w.z); v[5] = bf_hi(w.z); v[6] = bf_lo(w.w); v[7] = bf_hi(w.w); }
;     __device__ __forceinline__ void after(int te, f32x4 (&acc)[2][2][4][2], const Unit& u, int wr, int wc, int fr, int fq) const {
;     ...
;                     for (int m = 0; m < 4; ++m) { float vs[8], va[8]; unpack8(gs[m], vs); unpack8(ga[m], va);
; #pragma unroll
;                         for (int e = 0; e < 4; ++e) {
;                             acc[ai][bj][m][0][e] *= (1.f + __expf(-(va[e] + a0[e]))) * __builtin_amdgcn_rcpf(1.f + __expf(-(vs[e] + s0[e])));
;                             acc[ai][bj][m][1][e] *= (1.f + __expf(-(va[4 + e] + a1[e]))) * __builtin_amdgcn_rcpf(1.f + __expf(-(vs[4 + e] + s1[e]))); } }
	v_lshlrev_b32_e32 v3, 16, v186
	v_add_f32_e32 v3, v158, v3
	v_mul_f32_e32 v3, 0xbfb8aa3b, v3
	v_exp_f32_e32 v3, v3
	v_lshlrev_b32_e32 v202, 16, v187
	v_and_b32_e32 v203, 0xffff0000, v187
	v_lshlrev_b32_e32 v187, 16, v188
	v_add_f32_e32 v3, 1.0, v3
	v_pk_mul_f32 v[40:41], v[40:41], v[4:5]
	v_and_b32_e32 v5, 0xffff0000, v186
	v_rcp_f32_e32 v186, v3
	v_add_f32_e32 v3, v150, v187
	v_mul_f32_e32 v3, 0xbfb8aa3b, v3
	v_exp_f32_e32 v3, v3
	v_lshlrev_b32_e32 v205, 16, v189
	v_and_b32_e32 v207, 0xffff0000, v189
	s_waitcnt vmcnt(6)
	v_lshlrev_b32_e32 v4, 16, v190
	v_add_f32_e32 v3, 1.0, v3
	v_and_b32_e32 v189, 0xffff0000, v190
	v_rcp_f32_e32 v190, v3
	v_add_f32_e32 v3, v159, v5
	v_mul_f32_e32 v3, 0xbfb8aa3b, v3
	v_exp_f32_e32 v3, v3
	v_and_b32_e32 v204, 0xffff0000, v188
	v_lshlrev_b32_e32 v188, 16, v192
	v_add_f32_e32 v187, v154, v188
	v_mul_f32_e32 v187, 0xbfb8aa3b, v187
	v_add_f32_e32 v3, 1.0, v3
	v_exp_f32_e32 v188, v187
	v_rcp_f32_e32 v187, v3
	v_add_f32_e32 v3, v151, v204
	v_mul_f32_e32 v3, 0xbfb8aa3b, v3
	v_exp_f32_e32 v3, v3
	v_lshlrev_b32_e32 v206, 16, v191
	v_and_b32_e32 v208, 0xffff0000, v191
	v_and_b32_e32 v191, 0xffff0000, v192
	v_add_f32_e32 v3, 1.0, v3
	v_add_f32_e32 v5, v163, v189
	v_add_f32_e32 v189, v155, v191
	v_rcp_f32_e32 v191, v3
	v_add_f32_e32 v3, v160, v202
	v_mul_f32_e32 v3, 0xbfb8aa3b, v3
	v_exp_f32_e32 v3, v3
	v_add_f32_e32 v203, v161, v203
	v_lshlrev_b32_e32 v209, 16, v193
	v_mul_f32_e32 v203, 0xbfb8aa3b, v203
	v_add_f32_e32 v3, 1.0, v3
	v_rcp_f32_e32 v202, v3
	v_add_f32_e32 v3, v152, v205
	v_mul_f32_e32 v3, 0xbfb8aa3b, v3
	v_exp_f32_e32 v3, v3
	v_and_b32_e32 v210, 0xffff0000, v193
	v_add_f32_e32 v193, v156, v209
	v_exp_f32_e32 v203, v203
	v_mul_f32_e32 v193, 0xbfb8aa3b, v193
	v_add_f32_e32 v4, v162, v4
	v_add_f32_e32 v192, v164, v206
	v_exp_f32_e32 v204, v193
	v_add_f32_e32 v193, v165, v208
	v_mul_f32_e32 v4, 0xbfb8aa3b, v4
	v_mul_f32_e32 v5, 0xbfb8aa3b, v5
	v_mul_f32_e32 v192, 0xbfb8aa3b, v192
	v_add_f32_e32 v3, 1.0, v3
	v_mul_f32_e32 v193, 0xbfb8aa3b, v193
	v_exp_f32_e32 v4, v4
	v_exp_f32_e32 v5, v5
	v_exp_f32_e32 v192, v192
	v_exp_f32_e32 v193, v193
	v_rcp_f32_e32 v206, v3
	v_add_f32_e32 v3, 1.0, v203
	v_rcp_f32_e32 v203, v3
	v_pk_add_f32 v[192:193], v[192:193], 1.0 op_sel_hi:[1,0]
	v_pk_add_f32 v[4:5], v[4:5], 1.0 op_sel_hi:[1,0]
	v_add_f32_e32 v3, v157, v210
	v_pk_mul_f32 v[4:5], v[4:5], v[186:187]
	v_pk_mul_f32 v[186:187], v[192:193], v[202:203]
	v_mul_f32_e32 v3, 0xbfb8aa3b, v3
	v_pk_mul_f32 v[36:37], v[36:37], v[186:187]
	v_add_f32_e32 v186, v153, v207
	v_mul_f32_e32 v186, 0xbfb8aa3b, v186
	v_exp_f32_e32 v186, v186
	v_exp_f32_e32 v205, v3
	v_mul_f32_e32 v189, 0xbfb8aa3b, v189
	v_exp_f32_e32 v189, v189
	v_add_f32_e32 v3, 1.0, v186
	v_rcp_f32_e32 v207, v3
	s_waitcnt vmcnt(5)
	v_lshlrev_b32_e32 v3, 16, v194
	v_add_f32_e32 v3, v158, v3
	v_mul_f32_e32 v3, 0xbfb8aa3b, v3
	v_exp_f32_e32 v3, v3
	v_pk_add_f32 v[186:187], v[188:189], 1.0 op_sel_hi:[1,0]
	v_pk_mul_f32 v[34:35], v[34:35], v[4:5]
	v_pk_mul_f32 v[186:187], v[186:187], v[190:191]
	v_add_f32_e32 v3, 1.0, v3
	v_pk_mul_f32 v[30:31], v[30:31], v[186:187]
	v_lshlrev_b32_e32 v187, 16, v196
	v_rcp_f32_e32 v186, v3
	v_add_f32_e32 v3, v150, v187
	v_mul_f32_e32 v3, 0xbfb8aa3b, v3
	v_exp_f32_e32 v3, v3
	v_pk_add_f32 v[4:5], v[204:205], 1.0 op_sel_hi:[1,0]
	s_waitcnt vmcnt(4)
	v_lshlrev_b32_e32 v188, 16, v200
	v_pk_mul_f32 v[4:5], v[4:5], v[206:207]
	v_add_f32_e32 v3, 1.0, v3
	v_pk_mul_f32 v[32:33], v[32:33], v[4:5]
	v_and_b32_e32 v5, 0xffff0000, v194
	v_rcp_f32_e32 v190, v3
	v_add_f32_e32 v3, v159, v5
	v_mul_f32_e32 v3, 0xbfb8aa3b, v3
	v_exp_f32_e32 v3, v3
	v_add_f32_e32 v187, v154, v188
	v_and_b32_e32 v189, 0xffff0000, v196
	v_mul_f32_e32 v187, 0xbfb8aa3b, v187
	v_add_f32_e32 v3, 1.0, v3
	v_exp_f32_e32 v188, v187
	v_rcp_f32_e32 v187, v3
	v_add_f32_e32 v3, v151, v189
	v_mul_f32_e32 v3, 0xbfb8aa3b, v3
	v_exp_f32_e32 v3, v3
	v_lshlrev_b32_e32 v192, 16, v195
	v_and_b32_e32 v191, 0xffff0000, v198
	v_add_f32_e32 v5, v163, v191
	v_add_f32_e32 v3, 1.0, v3
	v_rcp_f32_e32 v191, v3
	v_add_f32_e32 v3, v160, v192
	v_mul_f32_e32 v3, 0xbfb8aa3b, v3
	v_exp_f32_e32 v3, v3
	v_and_b32_e32 v193, 0xffff0000, v195
	v_lshlrev_b32_e32 v195, 16, v197
	v_lshlrev_b32_e32 v194, 16, v199
	v_add_f32_e32 v3, 1.0, v3
	v_add_f32_e32 v192, v164, v194
	v_rcp_f32_e32 v194, v3
	v_add_f32_e32 v3, v152, v195
	v_mul_f32_e32 v3, 0xbfb8aa3b, v3
	v_add_f32_e32 v193, v161, v193
	v_lshlrev_b32_e32 v4, 16, v198
	v_and_b32_e32 v198, 0xffff0000, v199
	v_lshlrev_b32_e32 v199, 16, v201
	v_exp_f32_e32 v3, v3
	v_mul_f32_e32 v193, 0xbfb8aa3b, v193
	v_add_f32_e32 v195, v156, v199
	v_exp_f32_e32 v199, v193
	v_and_b32_e32 v196, 0xffff0000, v200
	v_mul_f32_e32 v195, 0xbfb8aa3b, v195
	v_add_f32_e32 v4, v162, v4
	v_add_f32_e32 v189, v155, v196
	v_exp_f32_e32 v196, v195
	v_add_f32_e32 v195, v165, v198
	v_mul_f32_e32 v4, 0xbfb8aa3b, v4
	v_mul_f32_e32 v5, 0xbfb8aa3b, v5
	v_mul_f32_e32 v192, 0xbfb8aa3b, v192
	v_add_f32_e32 v3, 1.0, v3
	v_mul_f32_e32 v193, 0xbfb8aa3b, v195
	v_exp_f32_e32 v4, v4
	v_exp_f32_e32 v5, v5
	v_exp_f32_e32 v192, v192
	v_exp_f32_e32 v193, v193
	v_rcp_f32_e32 v198, v3
	v_add_f32_e32 v3, 1.0, v199
	v_rcp_f32_e32 v195, v3
	v_pk_add_f32 v[192:193], v[192:193], 1.0 op_sel_hi:[1,0]
	v_pk_add_f32 v[4:5], v[4:5], 1.0 op_sel_hi:[1,0]
	v_and_b32_e32 v197, 0xffff0000, v197
	v_pk_mul_f32 v[4:5], v[4:5], v[186:187]
	v_pk_mul_f32 v[186:187], v[192:193], v[194:195]
	v_and_b32_e32 v200, 0xffff0000, v201
	v_pk_mul_f32 v[28:29], v[28:29], v[186:187]
	v_add_f32_e32 v186, v153, v197
	v_mul_f32_e32 v186, 0xbfb8aa3b, v186
	v_exp_f32_e32 v186, v186
	v_add_f32_e32 v3, v157, v200
	v_mul_f32_e32 v3, 0xbfb8aa3b, v3
	v_exp_f32_e32 v197, v3
	v_add_f32_e32 v3, 1.0, v186
	v_rcp_f32_e32 v199, v3
	s_waitcnt vmcnt(3)
; __device__ __forceinline__ void unpack8(const u32x4 w, float (&v)[8]) { v[0] = bf_lo(w.x); v[1] = bf_hi(w.x); v[2] = bf_lo(w.y); v[3] = bf_hi(w.y); v[4] = bf_lo(w.z); v[5] = bf_hi(w.z); v[6] = bf_lo(w.w); v[7] = bf_hi(w.w); }
;     __device__ __forceinline__ void after(int te, f32x4 (&acc)[2][2][4][2], const Unit& u, int wr, int wc, int fr, int fq) const {
;     ...
;                     for (int m = 0; m < 4; ++m) { float vs[8], va[8]; unpack8(gs[m], vs); unpack8(ga[m], va);
; #pragma unroll
;                         for (int e = 0; e < 4; ++e) {
;                             acc[ai][bj][m][0][e] *= (1.f + __expf(-(va[e] + a0[e]))) * __builtin_amdgcn_rcpf(1.f + __expf(-(vs[e] + s0[e])));
;                             acc[ai][bj][m][1][e] *= (1.f + __expf(-(va[4 + e] + a1[e]))) * __builtin_amdgcn_rcpf(1.f + __expf(-(vs[4 + e] + s1[e]))); } }
	v_lshlrev_b32_e32 v3, 16, v146
	v_mul_f32_e32 v189, 0xbfb8aa3b, v189
	v_add_f32_e32 v3, v158, v3
	v_exp_f32_e32 v189, v189
	v_mul_f32_e32 v3, 0xbfb8aa3b, v3
	v_exp_f32_e32 v3, v3
	v_pk_mul_f32 v[26:27], v[26:27], v[4:5]
	v_pk_add_f32 v[4:5], v[196:197], 1.0 op_sel_hi:[1,0]
	v_pk_add_f32 v[186:187], v[188:189], 1.0 op_sel_hi:[1,0]
	v_pk_mul_f32 v[4:5], v[4:5], v[198:199]
	v_pk_mul_f32 v[186:187], v[186:187], v[190:191]
	v_pk_mul_f32 v[24:25], v[24:25], v[4:5]
	v_and_b32_e32 v5, 0xffff0000, v146
	v_lshlrev_b32_e32 v146, 16, v148
	v_add_f32_e32 v3, 1.0, v3
	v_pk_mul_f32 v[22:23], v[22:23], v[186:187]
	v_lshlrev_b32_e32 v186, 16, v147
	v_and_b32_e32 v187, 0xffff0000, v147
	v_and_b32_e32 v147, 0xffff0000, v148
	s_waitcnt vmcnt(2)
	v_lshlrev_b32_e32 v4, 16, v142
	v_and_b32_e32 v148, 0xffff0000, v142
	v_rcp_f32_e32 v142, v3
	v_add_f32_e32 v3, v150, v146
	v_mul_f32_e32 v3, 0xbfb8aa3b, v3
	v_exp_f32_e32 v3, v3
	v_lshlrev_b32_e32 v188, 16, v149
	v_and_b32_e32 v189, 0xffff0000, v149
	v_lshlrev_b32_e32 v149, 16, v143
	v_add_f32_e32 v3, 1.0, v3
	v_rcp_f32_e32 v146, v3
	v_add_f32_e32 v3, v159, v5
	v_mul_f32_e32 v3, 0xbfb8aa3b, v3
	v_exp_f32_e32 v3, v3
	v_and_b32_e32 v190, 0xffff0000, v143
	v_lshlrev_b32_e32 v143, 16, v144
	v_add_f32_e32 v143, v154, v143
	v_mul_f32_e32 v143, 0xbfb8aa3b, v143
	v_add_f32_e32 v3, 1.0, v3
	v_and_b32_e32 v191, 0xffff0000, v144
	v_exp_f32_e32 v144, v143
	v_rcp_f32_e32 v143, v3
	v_add_f32_e32 v3, v151, v147
	v_mul_f32_e32 v3, 0xbfb8aa3b, v3
	v_exp_f32_e32 v3, v3
	v_add_f32_e32 v187, v161, v187
	v_lshlrev_b32_e32 v192, 16, v145
	v_mul_f32_e32 v187, 0xbfb8aa3b, v187
	v_add_f32_e32 v3, 1.0, v3
	v_rcp_f32_e32 v147, v3
	v_add_f32_e32 v3, v160, v186
	v_mul_f32_e32 v3, 0xbfb8aa3b, v3
	v_exp_f32_e32 v3, v3
	v_add_f32_e32 v5, v163, v148
	v_add_f32_e32 v148, v164, v149
	v_add_f32_e32 v149, v156, v192
	v_add_f32_e32 v3, 1.0, v3
	v_rcp_f32_e32 v186, v3
	v_add_f32_e32 v3, v152, v188
	v_mul_f32_e32 v3, 0xbfb8aa3b, v3
	v_exp_f32_e32 v3, v3
	v_exp_f32_e32 v187, v187
	v_mul_f32_e32 v149, 0xbfb8aa3b, v149
	v_add_f32_e32 v4, v162, v4
	v_exp_f32_e32 v188, v149
	v_add_f32_e32 v149, v165, v190
	v_mul_f32_e32 v4, 0xbfb8aa3b, v4
	v_mul_f32_e32 v5, 0xbfb8aa3b, v5
	v_mul_f32_e32 v148, 0xbfb8aa3b, v148
	v_add_f32_e32 v3, 1.0, v3
	v_mul_f32_e32 v149, 0xbfb8aa3b, v149
	v_exp_f32_e32 v4, v4
	v_exp_f32_e32 v5, v5
	v_exp_f32_e32 v148, v148
	v_exp_f32_e32 v149, v149
	v_rcp_f32_e32 v190, v3
	v_add_f32_e32 v3, 1.0, v187
	v_rcp_f32_e32 v187, v3
	v_pk_add_f32 v[148:149], v[148:149], 1.0 op_sel_hi:[1,0]
	v_pk_add_f32 v[4:5], v[4:5], 1.0 op_sel_hi:[1,0]
	v_and_b32_e32 v193, 0xffff0000, v145
	v_pk_mul_f32 v[4:5], v[4:5], v[142:143]
	v_pk_mul_f32 v[142:143], v[148:149], v[186:187]
	v_add_f32_e32 v3, v157, v193
	v_pk_mul_f32 v[20:21], v[20:21], v[142:143]
	v_add_f32_e32 v142, v153, v189
	v_mul_f32_e32 v142, 0xbfb8aa3b, v142
	v_exp_f32_e32 v142, v142
	v_mul_f32_e32 v3, 0xbfb8aa3b, v3
	v_exp_f32_e32 v189, v3
	v_add_f32_e32 v145, v155, v191
	v_add_f32_e32 v3, 1.0, v142
	v_rcp_f32_e32 v191, v3
	s_waitcnt vmcnt(1)
	v_lshlrev_b32_e32 v3, 16, v130
	v_mul_f32_e32 v145, 0xbfb8aa3b, v145
	v_add_f32_e32 v3, v158, v3
	v_exp_f32_e32 v145, v145
	v_mul_f32_e32 v3, 0xbfb8aa3b, v3
	v_exp_f32_e32 v3, v3
	v_pk_mul_f32 v[18:19], v[18:19], v[4:5]
	v_pk_add_f32 v[4:5], v[188:189], 1.0 op_sel_hi:[1,0]
	v_pk_add_f32 v[142:143], v[144:145], 1.0 op_sel_hi:[1,0]
	v_pk_mul_f32 v[4:5], v[4:5], v[190:191]
	v_pk_mul_f32 v[142:143], v[142:143], v[146:147]
	v_pk_mul_f32 v[16:17], v[16:17], v[4:5]
	v_and_b32_e32 v5, 0xffff0000, v130
	v_lshlrev_b32_e32 v130, 16, v132
	v_add_f32_e32 v3, 1.0, v3
	v_pk_mul_f32 v[14:15], v[14:15], v[142:143]
	v_lshlrev_b32_e32 v142, 16, v131
	v_and_b32_e32 v143, 0xffff0000, v131
	v_and_b32_e32 v131, 0xffff0000, v132
	s_waitcnt vmcnt(0)
	v_lshlrev_b32_e32 v4, 16, v126
	v_and_b32_e32 v132, 0xffff0000, v126
	v_rcp_f32_e32 v126, v3
	v_add_f32_e32 v3, v150, v130
	v_mul_f32_e32 v3, 0xbfb8aa3b, v3
	v_exp_f32_e32 v3, v3
	v_lshlrev_b32_e32 v144, 16, v133
	v_and_b32_e32 v145, 0xffff0000, v133
	v_lshlrev_b32_e32 v133, 16, v127
	v_add_f32_e32 v3, 1.0, v3
	v_rcp_f32_e32 v130, v3
	v_add_f32_e32 v3, v159, v5
	v_mul_f32_e32 v3, 0xbfb8aa3b, v3
	v_exp_f32_e32 v3, v3
	v_and_b32_e32 v146, 0xffff0000, v127
	v_lshlrev_b32_e32 v127, 16, v128
	v_add_f32_e32 v127, v154, v127
	v_mul_f32_e32 v127, 0xbfb8aa3b, v127
	v_add_f32_e32 v3, 1.0, v3
	v_and_b32_e32 v147, 0xffff0000, v128
	v_exp_f32_e32 v128, v127
	v_rcp_f32_e32 v127, v3
	v_add_f32_e32 v3, v151, v131
	v_mul_f32_e32 v3, 0xbfb8aa3b, v3
	v_exp_f32_e32 v3, v3
	v_add_f32_e32 v143, v161, v143
	v_lshlrev_b32_e32 v148, 16, v129
	v_mul_f32_e32 v143, 0xbfb8aa3b, v143
	v_add_f32_e32 v3, 1.0, v3
	v_rcp_f32_e32 v131, v3
	v_add_f32_e32 v3, v160, v142
	v_mul_f32_e32 v3, 0xbfb8aa3b, v3
	v_exp_f32_e32 v3, v3
	v_add_f32_e32 v5, v163, v132
	v_add_f32_e32 v132, v164, v133
	v_add_f32_e32 v133, v156, v148
	v_add_f32_e32 v3, 1.0, v3
	v_rcp_f32_e32 v142, v3
	v_add_f32_e32 v3, v152, v144
	v_mul_f32_e32 v3, 0xbfb8aa3b, v3
	v_exp_f32_e32 v3, v3
	v_exp_f32_e32 v143, v143
	v_mul_f32_e32 v133, 0xbfb8aa3b, v133
	v_add_f32_e32 v4, v162, v4
	v_exp_f32_e32 v144, v133
	v_add_f32_e32 v133, v165, v146
	v_mul_f32_e32 v4, 0xbfb8aa3b, v4
	v_mul_f32_e32 v5, 0xbfb8aa3b, v5
	v_mul_f32_e32 v132, 0xbfb8aa3b, v132
	v_add_f32_e32 v3, 1.0, v3
	v_mul_f32_e32 v133, 0xbfb8aa3b, v133
	v_exp_f32_e32 v4, v4
	v_exp_f32_e32 v5, v5
	v_exp_f32_e32 v132, v132
	v_exp_f32_e32 v133, v133
	v_rcp_f32_e32 v146, v3
	v_add_f32_e32 v3, 1.0, v143
	v_rcp_f32_e32 v143, v3
	v_pk_add_f32 v[132:133], v[132:133], 1.0 op_sel_hi:[1,0]
	v_pk_add_f32 v[4:5], v[4:5], 1.0 op_sel_hi:[1,0]
	v_and_b32_e32 v149, 0xffff0000, v129
	v_pk_mul_f32 v[4:5], v[4:5], v[126:127]
	v_pk_mul_f32 v[126:127], v[132:133], v[142:143]
	v_add_f32_e32 v129, v155, v147
	v_pk_mul_f32 v[12:13], v[12:13], v[126:127]
	v_add_f32_e32 v126, v153, v145
	v_mul_f32_e32 v126, 0xbfb8aa3b, v126
	v_exp_f32_e32 v126, v126
	v_add_f32_e32 v3, v157, v149
	v_mul_f32_e32 v129, 0xbfb8aa3b, v129
	v_mul_f32_e32 v3, 0xbfb8aa3b, v3
	v_exp_f32_e32 v129, v129
	v_exp_f32_e32 v145, v3
	v_add_f32_e32 v3, 1.0, v126
	v_rcp_f32_e32 v147, v3
	v_pk_mul_f32 v[10:11], v[10:11], v[4:5]
	v_pk_add_f32 v[4:5], v[144:145], 1.0 op_sel_hi:[1,0]
	v_pk_add_f32 v[126:127], v[128:129], 1.0 op_sel_hi:[1,0]
	v_pk_mul_f32 v[4:5], v[4:5], v[146:147]
	v_pk_mul_f32 v[126:127], v[126:127], v[130:131]
	v_pk_mul_f32 v[8:9], v[8:9], v[4:5]
	v_pk_mul_f32 v[6:7], v[6:7], v[126:127]

; #define PG8_STAGE(bufoff, gbase, voff) do { _Pragma("unroll") for (int _i = 0; _i < 2; ++_i) \
;         __builtin_amdgcn_global_load_lds((const unsigned*)((const char*)(gbase) + (voff)[_i]), (LAS unsigned*)(lds + (bufoff) + ldsw + _i * 8192), 16, 0, 0); } while (0)
; #define PG8_LDA(dst, b, h) do { _Pragma("unroll") for (int m = 0; m < 4; ++m) _Pragma("unroll") for (int k = 0; k < 2; ++k) dst[m][k] = *(const LAS bf16x8*)(lds + PG8_SA(b, h) + aoff + m * 2048 + k * 1024); } while (0)
; #define PG8_LDB(dst, b, h) do { _Pragma("unroll") for (int n = 0; n < 2; ++n) _Pragma("unroll") for (int k = 0; k < 2; ++k) dst[n][k] = *(const LAS bf16x8*)(lds + PG8_SB(b, h) + boff + n * 2048 + k * 1024); } while (0)
; #define PG8_MMA(ai, bj, At, Bt) do { __builtin_amdgcn_s_setprio(1); _Pragma("unroll") for (int m = 0; m < 4; ++m) _Pragma("unroll") for (int n = 0; n < 2; ++n) _Pragma("unroll") for (int k = 0; k < 2; ++k) \
;         acc[ai][bj][m][n] = __builtin_amdgcn_mfma_f32_16x16x32_bf16(Bt[n][k], At[m][k], acc[ai][bj][m][n], 0, 0, 0); __builtin_amdgcn_s_setprio(0); } while (0)
; #define PG8_WAIT_V(n) asm volatile("s_waitcnt vmcnt(" #n ")" ::: "memory")
; #define PG8_WAIT_L(n) asm volatile("s_waitcnt lgkmcnt(" #n ")" ::: "memory")
; #define PG8_BAR __builtin_amdgcn_s_barrier()
; #define PG8_SCHED __builtin_amdgcn_sched_barrier(0)
; template <class Epi, class Sched, bool ALIGN_EPI, class Hook = NoHook>
; __device__ __forceinline__ void gemm_phase(LAS unsigned char* lds, const Gemm g, const Sched& S, const Epi& E, const Hook& H = Hook()) {
;     ...
;             PG8_LDB(B0, 0, 0); PG8_LDB(B1, 0, 1); PG8_SCHED; PG8_LDA(At, 0, 0); PG8_STAGE(PG8_SA(1, 1), a1 + hA, voffA);
;             PG8_WAIT_V(8); PG8_WAIT_L(0); PG8_BAR; PG8_MMA(0, 0, At, B0); PG8_MMA(0, 1, At, B1); PG8_BAR; PG8_SCHED;
;             PG8_LDA(At, 0, 1); PG8_STAGE(PG8_SB(0, 0), b2, voffB); PG8_STAGE(PG8_SB(0, 1), b2 + hB, voffB); PG8_STAGE(PG8_SA(0, 0), a2, voffA);
;             PG8_WAIT_V(8); PG8_WAIT_L(0); PG8_BAR; PG8_MMA(1, 0, At, B0); PG8_MMA(1, 1, At, B1); PG8_BAR; PG8_SCHED;
;             PG8_LDB(B0, 1, 0); PG8_LDB(B1, 1, 1); PG8_SCHED; PG8_LDA(At, 1, 0); PG8_STAGE(PG8_SA(0, 1), a2 + hA, voffA);
;             PG8_WAIT_V(8); PG8_WAIT_L(0); PG8_BAR; PG8_MMA(0, 0, At, B0); PG8_MMA(0, 1, At, B1); PG8_BAR; PG8_SCHED;
.LBB0_850:
	ds_read_b128 v[146:149], v1
	ds_read_b128 v[150:153], v1 offset:1024
	ds_read_b128 v[154:157], v1 offset:2048
	ds_read_b128 v[158:161], v1 offset:3072
	ds_read_b128 v[162:165], v142
	ds_read_b128 v[166:169], v142 offset:1024
	ds_read_b128 v[170:173], v142 offset:2048
	ds_read_b128 v[174:177], v142 offset:3072
	s_add_u32 s20, s6, 0x87c00080
	s_addc_u32 s21, s7, -1
	s_cmp_lg_u32 s42, 60
	s_cselect_b32 s20, s20, 0
	s_cselect_b32 s21, s21, 0
	s_add_u32 s22, s2, s20
	s_addc_u32 s23, s3, s21
	s_add_u32 s20, s14, s20
	s_addc_u32 s21, s15, s21
	s_mov_b32 m0, s43
	v_lshl_add_u64 v[178:179], v[138:139], 0, s[6:7]
	ds_read_b128 v[186:189], v143
	ds_read_b128 v[190:193], v143 offset:1024
	ds_read_b128 v[194:197], v143 offset:2048
	ds_read_b128 v[198:201], v143 offset:3072
	ds_read_b128 v[202:205], v143 offset:4096
	ds_read_b128 v[206:209], v143 offset:5120
	ds_read_b128 v[210:213], v143 offset:6144
	ds_read_b128 v[214:217], v143 offset:7168
	global_load_lds_dwordx4 v[178:179], off
	v_lshl_add_u64 v[178:179], v[140:141], 0, s[6:7]
	s_mov_b32 m0, s44
	s_nop 0
	global_load_lds_dwordx4 v[178:179], off
	s_waitcnt vmcnt(8)
	s_waitcnt lgkmcnt(0)
	s_barrier
	s_setprio 1
	s_waitcnt lgkmcnt(0)
	v_mfma_f32_16x16x32_bf16 v[54:57], v[146:149], v[186:189], v[54:57]
	v_mfma_f32_16x16x32_bf16 v[34:37], v[154:157], v[186:189], v[34:37]
	v_mfma_f32_16x16x32_bf16 v[42:45], v[146:149], v[194:197], v[42:45]
	v_mfma_f32_16x16x32_bf16 v[30:33], v[154:157], v[194:197], v[30:33]
	v_mfma_f32_16x16x32_bf16 v[62:65], v[146:149], v[202:205], v[62:65]
	v_mfma_f32_16x16x32_bf16 v[50:53], v[154:157], v[202:205], v[50:53]
	v_mfma_f32_16x16x32_bf16 v[78:81], v[146:149], v[210:213], v[78:81]
	v_mfma_f32_16x16x32_bf16 v[70:73], v[154:157], v[210:213], v[70:73]
	v_mfma_f32_16x16x32_bf16 v[54:57], v[150:153], v[190:193], v[54:57]
	v_mfma_f32_16x16x32_bf16 v[34:37], v[158:161], v[190:193], v[34:37]
	v_mfma_f32_16x16x32_bf16 v[42:45], v[150:153], v[198:201], v[42:45]
	v_mfma_f32_16x16x32_bf16 v[30:33], v[158:161], v[198:201], v[30:33]
	v_mfma_f32_16x16x32_bf16 v[62:65], v[150:153], v[206:209], v[62:65]
	v_mfma_f32_16x16x32_bf16 v[50:53], v[158:161], v[206:209], v[50:53]
	v_mfma_f32_16x16x32_bf16 v[78:81], v[150:153], v[214:217], v[78:81]
	v_mfma_f32_16x16x32_bf16 v[70:73], v[158:161], v[214:217], v[70:73]
	s_setprio 0
	s_setprio 1
	v_mfma_f32_16x16x32_bf16 v[10:13], v[162:165], v[186:189], v[10:13]
	v_mfma_f32_16x16x32_bf16 v[2:5], v[170:173], v[186:189], v[2:5]
	v_mfma_f32_16x16x32_bf16 v[14:17], v[162:165], v[194:197], v[14:17]
	v_mfma_f32_16x16x32_bf16 v[6:9], v[170:173], v[194:197], v[6:9]
	v_mfma_f32_16x16x32_bf16 v[22:25], v[162:165], v[202:205], v[22:25]
	v_mfma_f32_16x16x32_bf16 v[18:21], v[170:173], v[202:205], v[18:21]
	v_mfma_f32_16x16x32_bf16 v[38:41], v[162:165], v[210:213], v[38:41]
	v_mfma_f32_16x16x32_bf16 v[26:29], v[170:173], v[210:213], v[26:29]
	v_mfma_f32_16x16x32_bf16 v[10:13], v[166:169], v[190:193], v[10:13]
	v_mfma_f32_16x16x32_bf16 v[2:5], v[174:177], v[190:193], v[2:5]
	v_mfma_f32_16x16x32_bf16 v[14:17], v[166:169], v[198:201], v[14:17]
	v_mfma_f32_16x16x32_bf16 v[6:9], v[174:177], v[198:201], v[6:9]
	v_mfma_f32_16x16x32_bf16 v[22:25], v[166:169], v[206:209], v[22:25]
	v_mfma_f32_16x16x32_bf16 v[18:21], v[174:177], v[206:209], v[18:21]
	v_mfma_f32_16x16x32_bf16 v[38:41], v[166:169], v[214:217], v[38:41]
	v_mfma_f32_16x16x32_bf16 v[26:29], v[174:177], v[214:217], v[26:29]
	s_setprio 0
	s_barrier
	s_mov_b32 m0, s45
	s_add_u32 s54, s20, 0x100000
	ds_read_b128 v[186:189], v143 offset:16384
	ds_read_b128 v[190:193], v143 offset:17408
	ds_read_b128 v[194:197], v143 offset:18432
	ds_read_b128 v[198:201], v143 offset:19456
	ds_read_b128 v[202:205], v143 offset:20480
	ds_read_b128 v[206:209], v143 offset:21504
	ds_read_b128 v[210:213], v143 offset:22528
	ds_read_b128 v[214:217], v143 offset:23552
	global_load_lds_dwordx4 v132, s[20:21]
	s_mov_b32 m0, s46
	s_addc_u32 s55, s21, 0
	global_load_lds_dwordx4 v136, s[20:21]
	s_mov_b32 m0, s47
	v_lshl_add_u64 v[220:221], s[22:23], 0, v[134:135]
	global_load_lds_dwordx4 v132, s[54:55]
	s_mov_b32 m0, s48
	s_nop 0
	global_load_lds_dwordx4 v136, s[54:55]
	v_lshl_add_u64 v[218:219], s[22:23], 0, v[130:131]
	s_mov_b32 m0, s28
	s_nop 0
	global_load_lds_dwordx4 v130, s[22:23]
	s_mov_b32 m0, s29
	s_nop 0
	global_load_lds_dwordx4 v134, s[22:23]
	s_waitcnt vmcnt(8)
	s_waitcnt lgkmcnt(0)
	s_barrier
	s_setprio 1
	s_waitcnt lgkmcnt(0)
	v_mfma_f32_16x16x32_bf16 v[94:97], v[146:149], v[186:189], v[94:97]
	v_mfma_f32_16x16x32_bf16 v[86:89], v[154:157], v[186:189], v[86:89]
	v_mfma_f32_16x16x32_bf16 v[102:105], v[146:149], v[194:197], v[102:105]
	v_mfma_f32_16x16x32_bf16 v[98:101], v[154:157], v[194:197], v[98:101]
	v_mfma_f32_16x16x32_bf16 v[110:113], v[146:149], v[202:205], v[110:113]
	v_mfma_f32_16x16x32_bf16 v[106:109], v[154:157], v[202:205], v[106:109]
	v_mfma_f32_16x16x32_bf16 v[126:129], v[146:149], v[210:213], v[126:129]
	v_mfma_f32_16x16x32_bf16 v[122:125], v[154:157], v[210:213], v[122:125]
	v_mfma_f32_16x16x32_bf16 v[94:97], v[150:153], v[190:193], v[94:97]
	v_mfma_f32_16x16x32_bf16 v[86:89], v[158:161], v[190:193], v[86:89]
	v_mfma_f32_16x16x32_bf16 v[102:105], v[150:153], v[198:201], v[102:105]
	v_mfma_f32_16x16x32_bf16 v[98:101], v[158:161], v[198:201], v[98:101]
	v_mfma_f32_16x16x32_bf16 v[110:113], v[150:153], v[206:209], v[110:113]
	v_mfma_f32_16x16x32_bf16 v[106:109], v[158:161], v[206:209], v[106:109]
	v_mfma_f32_16x16x32_bf16 v[126:129], v[150:153], v[214:217], v[126:129]
	v_mfma_f32_16x16x32_bf16 v[122:125], v[158:161], v[214:217], v[122:125]
	s_setprio 0
	s_setprio 1
	v_mfma_f32_16x16x32_bf16 v[58:61], v[162:165], v[186:189], v[58:61]
	v_mfma_f32_16x16x32_bf16 v[46:49], v[170:173], v[186:189], v[46:49]
	v_mfma_f32_16x16x32_bf16 v[74:77], v[162:165], v[194:197], v[74:77]
	v_mfma_f32_16x16x32_bf16 v[66:69], v[170:173], v[194:197], v[66:69]
	v_mfma_f32_16x16x32_bf16 v[90:93], v[162:165], v[202:205], v[90:93]
	v_mfma_f32_16x16x32_bf16 v[82:85], v[170:173], v[202:205], v[82:85]
	v_mfma_f32_16x16x32_bf16 v[118:121], v[162:165], v[210:213], v[118:121]
	v_mfma_f32_16x16x32_bf16 v[114:117], v[170:173], v[210:213], v[114:117]
	v_mfma_f32_16x16x32_bf16 v[58:61], v[166:169], v[190:193], v[58:61]
	v_mfma_f32_16x16x32_bf16 v[46:49], v[174:177], v[190:193], v[46:49]
	v_mfma_f32_16x16x32_bf16 v[74:77], v[166:169], v[198:201], v[74:77]
	v_mfma_f32_16x16x32_bf16 v[66:69], v[174:177], v[198:201], v[66:69]
	v_mfma_f32_16x16x32_bf16 v[90:93], v[166:169], v[206:209], v[90:93]
	v_mfma_f32_16x16x32_bf16 v[82:85], v[174:177], v[206:209], v[82:85]
	v_mfma_f32_16x16x32_bf16 v[118:121], v[166:169], v[214:217], v[118:121]
	v_mfma_f32_16x16x32_bf16 v[114:117], v[174:177], v[214:217], v[114:117]
	s_setprio 0
	s_barrier
; #define PG8_STAGE(bufoff, gbase, voff) do { _Pragma("unroll") for (int _i = 0; _i < 2; ++_i) \
;         __builtin_amdgcn_global_load_lds((const unsigned*)((const char*)(gbase) + (voff)[_i]), (LAS unsigned*)(lds + (bufoff) + ldsw + _i * 8192), 16, 0, 0); } while (0)
; #define PG8_LDA(dst, b, h) do { _Pragma("unroll") for (int m = 0; m < 4; ++m) _Pragma("unroll") for (int k = 0; k < 2; ++k) dst[m][k] = *(const LAS bf16x8*)(lds + PG8_SA(b, h) + aoff + m * 2048 + k * 1024); } while (0)
; #define PG8_LDB(dst, b, h) do { _Pragma("unroll") for (int n = 0; n < 2; ++n) _Pragma("unroll") for (int k = 0; k < 2; ++k) dst[n][k] = *(const LAS bf16x8*)(lds + PG8_SB(b, h) + boff + n * 2048 + k * 1024); } while (0)
; #define PG8_MMA(ai, bj, At, Bt) do { __builtin_amdgcn_s_setprio(1); _Pragma("unroll") for (int m = 0; m < 4; ++m) _Pragma("unroll") for (int n = 0; n < 2; ++n) _Pragma("unroll") for (int k = 0; k < 2; ++k) \
;         acc[ai][bj][m][n] = __builtin_amdgcn_mfma_f32_16x16x32_bf16(Bt[n][k], At[m][k], acc[ai][bj][m][n], 0, 0, 0); __builtin_amdgcn_s_setprio(0); } while (0)
; #define PG8_WAIT_V(n) asm volatile("s_waitcnt vmcnt(" #n ")" ::: "memory")
; #define PG8_WAIT_L(n) asm volatile("s_waitcnt lgkmcnt(" #n ")" ::: "memory")
; #define PG8_BAR __builtin_amdgcn_s_barrier()
; #define PG8_SCHED __builtin_amdgcn_sched_barrier(0)
; template <class Epi, class Sched, bool ALIGN_EPI, class Hook = NoHook>
; __device__ __forceinline__ void gemm_phase(LAS unsigned char* lds, const Gemm g, const Sched& S, const Epi& E, const Hook& H = Hook()) {
;     ...
;             PG8_LDB(B0, 1, 0); PG8_LDB(B1, 1, 1); PG8_SCHED; PG8_LDA(At, 1, 0); PG8_STAGE(PG8_SA(0, 1), a2 + hA, voffA);
;             PG8_WAIT_V(8); PG8_WAIT_L(0); PG8_BAR; PG8_MMA(0, 0, At, B0); PG8_MMA(0, 1, At, B1); PG8_BAR; PG8_SCHED;
;             PG8_LDA(At, 1, 1); PG8_STAGE(PG8_SB(1, 0), b3, voffB); PG8_STAGE(PG8_SB(1, 1), b3 + hB, voffB); PG8_STAGE(PG8_SA(1, 0), a3, voffA);
;             PG8_WAIT_V(8); PG8_WAIT_L(0); PG8_BAR; PG8_MMA(1, 0, At, B0); PG8_MMA(1, 1, At, B1); PG8_BAR; PG8_SCHED;
;     ...
;         if constexpr (ALIGN_EPI) { if (wr == 0) PG8_BAR; }
	ds_read_b128 v[146:149], v144
	ds_read_b128 v[150:153], v144 offset:1024
	ds_read_b128 v[154:157], v144 offset:2048
	ds_read_b128 v[158:161], v144 offset:3072
	ds_read_b128 v[162:165], v145
	ds_read_b128 v[166:169], v145 offset:1024
	ds_read_b128 v[170:173], v145 offset:2048
	ds_read_b128 v[174:177], v145 offset:3072
	s_add_u32 s22, s22, 0x100000
	s_addc_u32 s23, s23, 0
	s_mov_b32 m0, s38
	ds_read_b128 v[186:189], v143 offset:32768
	ds_read_b128 v[190:193], v143 offset:33792
	ds_read_b128 v[194:197], v143 offset:34816
	ds_read_b128 v[198:201], v143 offset:35840
	ds_read_b128 v[202:205], v143 offset:36864
	ds_read_b128 v[206:209], v143 offset:37888
	ds_read_b128 v[210:213], v143 offset:38912
	ds_read_b128 v[214:217], v143 offset:39936
	global_load_lds_dwordx4 v130, s[22:23]
	s_mov_b32 m0, s39
	s_nop 0
	global_load_lds_dwordx4 v134, s[22:23]
	s_waitcnt vmcnt(8)
	s_waitcnt lgkmcnt(0)
	s_barrier
	s_setprio 1
	s_waitcnt lgkmcnt(0)
	v_mfma_f32_16x16x32_bf16 v[54:57], v[146:149], v[186:189], v[54:57]
	v_mfma_f32_16x16x32_bf16 v[34:37], v[154:157], v[186:189], v[34:37]
	v_mfma_f32_16x16x32_bf16 v[42:45], v[146:149], v[194:197], v[42:45]
	v_mfma_f32_16x16x32_bf16 v[30:33], v[154:157], v[194:197], v[30:33]
	v_mfma_f32_16x16x32_bf16 v[62:65], v[146:149], v[202:205], v[62:65]
	v_mfma_f32_16x16x32_bf16 v[50:53], v[154:157], v[202:205], v[50:53]
	v_mfma_f32_16x16x32_bf16 v[78:81], v[146:149], v[210:213], v[78:81]
	v_mfma_f32_16x16x32_bf16 v[70:73], v[154:157], v[210:213], v[70:73]
	v_mfma_f32_16x16x32_bf16 v[54:57], v[150:153], v[190:193], v[54:57]
	v_mfma_f32_16x16x32_bf16 v[34:37], v[158:161], v[190:193], v[34:37]
	v_mfma_f32_16x16x32_bf16 v[42:45], v[150:153], v[198:201], v[42:45]
	v_mfma_f32_16x16x32_bf16 v[30:33], v[158:161], v[198:201], v[30:33]
	v_mfma_f32_16x16x32_bf16 v[62:65], v[150:153], v[206:209], v[62:65]
	v_mfma_f32_16x16x32_bf16 v[50:53], v[158:161], v[206:209], v[50:53]
	v_mfma_f32_16x16x32_bf16 v[78:81], v[150:153], v[214:217], v[78:81]
	v_mfma_f32_16x16x32_bf16 v[70:73], v[158:161], v[214:217], v[70:73]
	s_setprio 0
	s_setprio 1
	v_mfma_f32_16x16x32_bf16 v[10:13], v[162:165], v[186:189], v[10:13]
	v_mfma_f32_16x16x32_bf16 v[2:5], v[170:173], v[186:189], v[2:5]
	v_mfma_f32_16x16x32_bf16 v[14:17], v[162:165], v[194:197], v[14:17]
	v_mfma_f32_16x16x32_bf16 v[6:9], v[170:173], v[194:197], v[6:9]
	v_mfma_f32_16x16x32_bf16 v[22:25], v[162:165], v[202:205], v[22:25]
	v_mfma_f32_16x16x32_bf16 v[18:21], v[170:173], v[202:205], v[18:21]
	v_mfma_f32_16x16x32_bf16 v[38:41], v[162:165], v[210:213], v[38:41]
	v_mfma_f32_16x16x32_bf16 v[26:29], v[170:173], v[210:213], v[26:29]
	v_mfma_f32_16x16x32_bf16 v[10:13], v[166:169], v[190:193], v[10:13]
	v_mfma_f32_16x16x32_bf16 v[2:5], v[174:177], v[190:193], v[2:5]
	v_mfma_f32_16x16x32_bf16 v[14:17], v[166:169], v[198:201], v[14:17]
	v_mfma_f32_16x16x32_bf16 v[6:9], v[174:177], v[198:201], v[6:9]
	v_mfma_f32_16x16x32_bf16 v[22:25], v[166:169], v[206:209], v[22:25]
	v_mfma_f32_16x16x32_bf16 v[18:21], v[174:177], v[206:209], v[18:21]
	v_mfma_f32_16x16x32_bf16 v[38:41], v[166:169], v[214:217], v[38:41]
	v_mfma_f32_16x16x32_bf16 v[26:29], v[174:177], v[214:217], v[26:29]
	s_setprio 0
	s_barrier
	s_mov_b32 m0, s49
	s_add_u32 s56, s20, s4
	s_addc_u32 s57, s21, s5
	s_add_u32 s20, s20, 0x100080
	ds_read_b128 v[186:189], v143 offset:49152
	ds_read_b128 v[190:193], v143 offset:50176
	ds_read_b128 v[194:197], v143 offset:51200
	ds_read_b128 v[198:201], v143 offset:52224
	ds_read_b128 v[202:205], v143 offset:53248
	ds_read_b128 v[206:209], v143 offset:54272
	ds_read_b128 v[210:213], v143 offset:55296
	ds_read_b128 v[214:217], v143 offset:56320
	global_load_lds_dwordx4 v132, s[56:57]
	s_mov_b32 m0, s50
	s_addc_u32 s21, s21, 0
	global_load_lds_dwordx4 v136, s[56:57]
	s_mov_b32 m0, s51
	s_nop 0
	global_load_lds_dwordx4 v132, s[20:21]
	s_mov_b32 m0, s52
	s_nop 0
	global_load_lds_dwordx4 v136, s[20:21]
	v_lshl_add_u64 v[178:179], v[218:219], 0, s[4:5]
	s_mov_b32 m0, s40
	s_nop 0
	global_load_lds_dwordx4 v[178:179], off
	v_lshl_add_u64 v[178:179], v[220:221], 0, s[4:5]
	s_mov_b32 m0, s41
	s_nop 0
	global_load_lds_dwordx4 v[178:179], off
	s_waitcnt vmcnt(8)
	s_waitcnt lgkmcnt(0)
	s_barrier
	s_setprio 1
	s_waitcnt lgkmcnt(0)
	v_mfma_f32_16x16x32_bf16 v[94:97], v[146:149], v[186:189], v[94:97]
	v_mfma_f32_16x16x32_bf16 v[86:89], v[154:157], v[186:189], v[86:89]
	v_mfma_f32_16x16x32_bf16 v[102:105], v[146:149], v[194:197], v[102:105]
	v_mfma_f32_16x16x32_bf16 v[98:101], v[154:157], v[194:197], v[98:101]
	v_mfma_f32_16x16x32_bf16 v[110:113], v[146:149], v[202:205], v[110:113]
	v_mfma_f32_16x16x32_bf16 v[106:109], v[154:157], v[202:205], v[106:109]
	v_mfma_f32_16x16x32_bf16 v[126:129], v[146:149], v[210:213], v[126:129]
	v_mfma_f32_16x16x32_bf16 v[122:125], v[154:157], v[210:213], v[122:125]
	v_mfma_f32_16x16x32_bf16 v[94:97], v[150:153], v[190:193], v[94:97]
	v_mfma_f32_16x16x32_bf16 v[86:89], v[158:161], v[190:193], v[86:89]
	v_mfma_f32_16x16x32_bf16 v[102:105], v[150:153], v[198:201], v[102:105]
	v_mfma_f32_16x16x32_bf16 v[98:101], v[158:161], v[198:201], v[98:101]
	v_mfma_f32_16x16x32_bf16 v[110:113], v[150:153], v[206:209], v[110:113]
	v_mfma_f32_16x16x32_bf16 v[106:109], v[158:161], v[206:209], v[106:109]
	v_mfma_f32_16x16x32_bf16 v[126:129], v[150:153], v[214:217], v[126:129]
	v_mfma_f32_16x16x32_bf16 v[122:125], v[158:161], v[214:217], v[122:125]
	s_setprio 0
	s_setprio 1
	v_mfma_f32_16x16x32_bf16 v[58:61], v[162:165], v[186:189], v[58:61]
	v_mfma_f32_16x16x32_bf16 v[46:49], v[170:173], v[186:189], v[46:49]
	v_mfma_f32_16x16x32_bf16 v[74:77], v[162:165], v[194:197], v[74:77]
	v_mfma_f32_16x16x32_bf16 v[66:69], v[170:173], v[194:197], v[66:69]
	v_mfma_f32_16x16x32_bf16 v[90:93], v[162:165], v[202:205], v[90:93]
	v_mfma_f32_16x16x32_bf16 v[82:85], v[170:173], v[202:205], v[82:85]
	v_mfma_f32_16x16x32_bf16 v[118:121], v[162:165], v[210:213], v[118:121]
	v_mfma_f32_16x16x32_bf16 v[114:117], v[170:173], v[210:213], v[114:117]
	v_mfma_f32_16x16x32_bf16 v[58:61], v[166:169], v[190:193], v[58:61]
	v_mfma_f32_16x16x32_bf16 v[46:49], v[174:177], v[190:193], v[46:49]
	v_mfma_f32_16x16x32_bf16 v[74:77], v[166:169], v[198:201], v[74:77]
	v_mfma_f32_16x16x32_bf16 v[66:69], v[174:177], v[198:201], v[66:69]
	v_mfma_f32_16x16x32_bf16 v[90:93], v[166:169], v[206:209], v[90:93]
	v_mfma_f32_16x16x32_bf16 v[82:85], v[174:177], v[206:209], v[82:85]
	v_mfma_f32_16x16x32_bf16 v[118:121], v[166:169], v[214:217], v[118:121]
	v_mfma_f32_16x16x32_bf16 v[114:117], v[174:177], v[214:217], v[114:117]
	s_setprio 0
	s_barrier
	s_add_i32 s42, s42, 2
	s_add_u32 s6, s6, 0x100
	s_addc_u32 s7, s7, 0
	s_cmp_gt_u32 s42, 61
	s_cbranch_scc0 .LBB0_850
	s_cmpk_lt_u32 s26, 0x100
	s_cbranch_scc0 .LBB0_853
	s_barrier

; #define PG8_STAGE(bufoff, gbase, voff) do { _Pragma("unroll") for (int _i = 0; _i < 2; ++_i) \
;         __builtin_amdgcn_global_load_lds((const unsigned*)((const char*)(gbase) + (voff)[_i]), (LAS unsigned*)(lds + (bufoff) + ldsw + _i * 8192), 16, 0, 0); } while (0)
; #define PG8_LDA(dst, b, h) do { _Pragma("unroll") for (int m = 0; m < 4; ++m) _Pragma("unroll") for (int k = 0; k < 2; ++k) dst[m][k] = *(const LAS bf16x8*)(lds + PG8_SA(b, h) + aoff + m * 2048 + k * 1024); } while (0)
; #define PG8_LDB(dst, b, h) do { _Pragma("unroll") for (int n = 0; n < 2; ++n) _Pragma("unroll") for (int k = 0; k < 2; ++k) dst[n][k] = *(const LAS bf16x8*)(lds + PG8_SB(b, h) + boff + n * 2048 + k * 1024); } while (0)
; #define PG8_MMA(ai, bj, At, Bt) do { __builtin_amdgcn_s_setprio(1); _Pragma("unroll") for (int m = 0; m < 4; ++m) _Pragma("unroll") for (int n = 0; n < 2; ++n) _Pragma("unroll") for (int k = 0; k < 2; ++k) \
;         acc[ai][bj][m][n] = __builtin_amdgcn_mfma_f32_16x16x32_bf16(Bt[n][k], At[m][k], acc[ai][bj][m][n], 0, 0, 0); __builtin_amdgcn_s_setprio(0); } while (0)
; #define PG8_WAIT_V(n) asm volatile("s_waitcnt vmcnt(" #n ")" ::: "memory")
; #define PG8_WAIT_L(n) asm volatile("s_waitcnt lgkmcnt(" #n ")" ::: "memory")
; #define PG8_BAR __builtin_amdgcn_s_barrier()
; #define PG8_SCHED __builtin_amdgcn_sched_barrier(0)
; template <class Epi, class Sched, bool ALIGN_EPI, class Hook = NoHook>
; __device__ __forceinline__ void gemm_phase(LAS unsigned char* lds, const Gemm g, const Sched& S, const Epi& E, const Hook& H = Hook()) {
;     ...
;             PG8_LDB(B0, 0, 0); PG8_LDB(B1, 0, 1); PG8_SCHED; PG8_LDA(At, 0, 0); PG8_STAGE(PG8_SA(1, 1), a1 + hA, voffA);
;             PG8_WAIT_V(8); PG8_WAIT_L(0); PG8_BAR; PG8_MMA(0, 0, At, B0); PG8_MMA(0, 1, At, B1); PG8_BAR; PG8_SCHED;
;             PG8_LDA(At, 0, 1); PG8_STAGE(PG8_SB(0, 0), b2, voffB); PG8_STAGE(PG8_SB(0, 1), b2 + hB, voffB); PG8_STAGE(PG8_SA(0, 0), a2, voffA);
;             PG8_WAIT_V(8); PG8_WAIT_L(0); PG8_BAR; PG8_MMA(1, 0, At, B0); PG8_MMA(1, 1, At, B1); PG8_BAR; PG8_SCHED;
;             PG8_LDB(B0, 1, 0); PG8_LDB(B1, 1, 1); PG8_SCHED; PG8_LDA(At, 1, 0); PG8_STAGE(PG8_SA(0, 1), a2 + hA, voffA);
;             PG8_WAIT_V(8); PG8_WAIT_L(0); PG8_BAR; PG8_MMA(0, 0, At, B0); PG8_MMA(0, 1, At, B1); PG8_BAR; PG8_SCHED;
.LBB0_896:
	ds_read_b128 v[146:149], v140
	ds_read_b128 v[150:153], v140 offset:1024
	ds_read_b128 v[154:157], v140 offset:2048
	ds_read_b128 v[158:161], v140 offset:3072
	ds_read_b128 v[162:165], v141
	ds_read_b128 v[166:169], v141 offset:1024
	ds_read_b128 v[170:173], v141 offset:2048
	ds_read_b128 v[174:177], v141 offset:3072
	s_add_u32 s10, s6, 0x87c00080
	s_addc_u32 s11, s7, -1
	s_cmp_lg_u32 s18, 60
	s_cselect_b32 s10, s10, 0
	s_cselect_b32 s11, s11, 0
	s_add_u32 s16, s2, s10
	s_addc_u32 s17, s3, s11
	s_add_u32 s10, s14, s10
	s_addc_u32 s11, s15, s11
	s_mov_b32 m0, s19
	v_lshl_add_u64 v[178:179], v[136:137], 0, s[6:7]
	ds_read_b128 v[186:189], v142
	ds_read_b128 v[190:193], v142 offset:1024
	ds_read_b128 v[194:197], v142 offset:2048
	ds_read_b128 v[198:201], v142 offset:3072
	ds_read_b128 v[202:205], v142 offset:4096
	ds_read_b128 v[206:209], v142 offset:5120
	ds_read_b128 v[210:213], v142 offset:6144
	ds_read_b128 v[214:217], v142 offset:7168
	global_load_lds_dwordx4 v[178:179], off
	v_lshl_add_u64 v[178:179], v[138:139], 0, s[6:7]
	s_mov_b32 m0, s31
	s_nop 0
	global_load_lds_dwordx4 v[178:179], off
	s_waitcnt vmcnt(8)
	s_waitcnt lgkmcnt(0)
	s_barrier
	s_setprio 1
	s_waitcnt lgkmcnt(0)
	v_mfma_f32_16x16x32_bf16 v[54:57], v[146:149], v[186:189], v[54:57]
	v_mfma_f32_16x16x32_bf16 v[34:37], v[154:157], v[186:189], v[34:37]
	v_mfma_f32_16x16x32_bf16 v[42:45], v[146:149], v[194:197], v[42:45]
	v_mfma_f32_16x16x32_bf16 v[30:33], v[154:157], v[194:197], v[30:33]
	v_mfma_f32_16x16x32_bf16 v[62:65], v[146:149], v[202:205], v[62:65]
	v_mfma_f32_16x16x32_bf16 v[50:53], v[154:157], v[202:205], v[50:53]
	v_mfma_f32_16x16x32_bf16 v[78:81], v[146:149], v[210:213], v[78:81]
	v_mfma_f32_16x16x32_bf16 v[70:73], v[154:157], v[210:213], v[70:73]
	v_mfma_f32_16x16x32_bf16 v[54:57], v[150:153], v[190:193], v[54:57]
	v_mfma_f32_16x16x32_bf16 v[34:37], v[158:161], v[190:193], v[34:37]
	v_mfma_f32_16x16x32_bf16 v[42:45], v[150:153], v[198:201], v[42:45]
	v_mfma_f32_16x16x32_bf16 v[30:33], v[158:161], v[198:201], v[30:33]
	v_mfma_f32_16x16x32_bf16 v[62:65], v[150:153], v[206:209], v[62:65]
	v_mfma_f32_16x16x32_bf16 v[50:53], v[158:161], v[206:209], v[50:53]
	v_mfma_f32_16x16x32_bf16 v[78:81], v[150:153], v[214:217], v[78:81]
	v_mfma_f32_16x16x32_bf16 v[70:73], v[158:161], v[214:217], v[70:73]
	s_setprio 0
	s_setprio 1
	v_mfma_f32_16x16x32_bf16 v[10:13], v[162:165], v[186:189], v[10:13]
	v_mfma_f32_16x16x32_bf16 v[2:5], v[170:173], v[186:189], v[2:5]
	v_mfma_f32_16x16x32_bf16 v[14:17], v[162:165], v[194:197], v[14:17]
	v_mfma_f32_16x16x32_bf16 v[6:9], v[170:173], v[194:197], v[6:9]
	v_mfma_f32_16x16x32_bf16 v[22:25], v[162:165], v[202:205], v[22:25]
	v_mfma_f32_16x16x32_bf16 v[18:21], v[170:173], v[202:205], v[18:21]
	v_mfma_f32_16x16x32_bf16 v[38:41], v[162:165], v[210:213], v[38:41]
	v_mfma_f32_16x16x32_bf16 v[26:29], v[170:173], v[210:213], v[26:29]
	v_mfma_f32_16x16x32_bf16 v[10:13], v[166:169], v[190:193], v[10:13]
	v_mfma_f32_16x16x32_bf16 v[2:5], v[174:177], v[190:193], v[2:5]
	v_mfma_f32_16x16x32_bf16 v[14:17], v[166:169], v[198:201], v[14:17]
	v_mfma_f32_16x16x32_bf16 v[6:9], v[174:177], v[198:201], v[6:9]
	v_mfma_f32_16x16x32_bf16 v[22:25], v[166:169], v[206:209], v[22:25]
	v_mfma_f32_16x16x32_bf16 v[18:21], v[174:177], v[206:209], v[18:21]
	v_mfma_f32_16x16x32_bf16 v[38:41], v[166:169], v[214:217], v[38:41]
	v_mfma_f32_16x16x32_bf16 v[26:29], v[174:177], v[214:217], v[26:29]
	s_setprio 0
	s_barrier
	s_mov_b32 m0, s33
	s_add_u32 s46, s10, 0x100000
	ds_read_b128 v[186:189], v142 offset:16384
	ds_read_b128 v[190:193], v142 offset:17408
	ds_read_b128 v[194:197], v142 offset:18432
	ds_read_b128 v[198:201], v142 offset:19456
	ds_read_b128 v[202:205], v142 offset:20480
	ds_read_b128 v[206:209], v142 offset:21504
	ds_read_b128 v[210:213], v142 offset:22528
	ds_read_b128 v[214:217], v142 offset:23552
	global_load_lds_dwordx4 v180, s[10:11]
	s_mov_b32 m0, s34
	s_addc_u32 s47, s11, 0
	global_load_lds_dwordx4 v134, s[10:11]
	s_mov_b32 m0, s35
	v_lshl_add_u64 v[222:223], s[16:17], 0, v[132:133]
	global_load_lds_dwordx4 v180, s[46:47]
	s_mov_b32 m0, s42
	s_nop 0
	global_load_lds_dwordx4 v134, s[46:47]
	v_lshl_add_u64 v[220:221], s[16:17], 0, v[130:131]
	s_mov_b32 m0, s27
	s_nop 0
	global_load_lds_dwordx4 v130, s[16:17]
	s_mov_b32 m0, s28
	s_nop 0
	global_load_lds_dwordx4 v132, s[16:17]
	s_waitcnt vmcnt(8)
	s_waitcnt lgkmcnt(0)
	s_barrier
	s_setprio 1
	s_waitcnt lgkmcnt(0)
	v_mfma_f32_16x16x32_bf16 v[94:97], v[146:149], v[186:189], v[94:97]
	v_mfma_f32_16x16x32_bf16 v[86:89], v[154:157], v[186:189], v[86:89]
	v_mfma_f32_16x16x32_bf16 v[102:105], v[146:149], v[194:197], v[102:105]
	v_mfma_f32_16x16x32_bf16 v[98:101], v[154:157], v[194:197], v[98:101]
	v_mfma_f32_16x16x32_bf16 v[110:113], v[146:149], v[202:205], v[110:113]
	v_mfma_f32_16x16x32_bf16 v[106:109], v[154:157], v[202:205], v[106:109]
	v_mfma_f32_16x16x32_bf16 v[126:129], v[146:149], v[210:213], v[126:129]
	v_mfma_f32_16x16x32_bf16 v[122:125], v[154:157], v[210:213], v[122:125]
	v_mfma_f32_16x16x32_bf16 v[94:97], v[150:153], v[190:193], v[94:97]
	v_mfma_f32_16x16x32_bf16 v[86:89], v[158:161], v[190:193], v[86:89]
	v_mfma_f32_16x16x32_bf16 v[102:105], v[150:153], v[198:201], v[102:105]
	v_mfma_f32_16x16x32_bf16 v[98:101], v[158:161], v[198:201], v[98:101]
	v_mfma_f32_16x16x32_bf16 v[110:113], v[150:153], v[206:209], v[110:113]
	v_mfma_f32_16x16x32_bf16 v[106:109], v[158:161], v[206:209], v[106:109]
	v_mfma_f32_16x16x32_bf16 v[126:129], v[150:153], v[214:217], v[126:129]
	v_mfma_f32_16x16x32_bf16 v[122:125], v[158:161], v[214:217], v[122:125]
	s_setprio 0
	s_setprio 1
	v_mfma_f32_16x16x32_bf16 v[58:61], v[162:165], v[186:189], v[58:61]
	v_mfma_f32_16x16x32_bf16 v[46:49], v[170:173], v[186:189], v[46:49]
	v_mfma_f32_16x16x32_bf16 v[74:77], v[162:165], v[194:197], v[74:77]
	v_mfma_f32_16x16x32_bf16 v[66:69], v[170:173], v[194:197], v[66:69]
	v_mfma_f32_16x16x32_bf16 v[90:93], v[162:165], v[202:205], v[90:93]
	v_mfma_f32_16x16x32_bf16 v[82:85], v[170:173], v[202:205], v[82:85]
	v_mfma_f32_16x16x32_bf16 v[118:121], v[162:165], v[210:213], v[118:121]
	v_mfma_f32_16x16x32_bf16 v[114:117], v[170:173], v[210:213], v[114:117]
	v_mfma_f32_16x16x32_bf16 v[58:61], v[166:169], v[190:193], v[58:61]
	v_mfma_f32_16x16x32_bf16 v[46:49], v[174:177], v[190:193], v[46:49]
	v_mfma_f32_16x16x32_bf16 v[74:77], v[166:169], v[198:201], v[74:77]
	v_mfma_f32_16x16x32_bf16 v[66:69], v[174:177], v[198:201], v[66:69]
	v_mfma_f32_16x16x32_bf16 v[90:93], v[166:169], v[206:209], v[90:93]
	v_mfma_f32_16x16x32_bf16 v[82:85], v[174:177], v[206:209], v[82:85]
	v_mfma_f32_16x16x32_bf16 v[118:121], v[166:169], v[214:217], v[118:121]
	v_mfma_f32_16x16x32_bf16 v[114:117], v[174:177], v[214:217], v[114:117]
	s_setprio 0
	s_barrier
; #define PG8_STAGE(bufoff, gbase, voff) do { _Pragma("unroll") for (int _i = 0; _i < 2; ++_i) \
;         __builtin_amdgcn_global_load_lds((const unsigned*)((const char*)(gbase) + (voff)[_i]), (LAS unsigned*)(lds + (bufoff) + ldsw + _i * 8192), 16, 0, 0); } while (0)
; #define PG8_LDA(dst, b, h) do { _Pragma("unroll") for (int m = 0; m < 4; ++m) _Pragma("unroll") for (int k = 0; k < 2; ++k) dst[m][k] = *(const LAS bf16x8*)(lds + PG8_SA(b, h) + aoff + m * 2048 + k * 1024); } while (0)
; #define PG8_LDB(dst, b, h) do { _Pragma("unroll") for (int n = 0; n < 2; ++n) _Pragma("unroll") for (int k = 0; k < 2; ++k) dst[n][k] = *(const LAS bf16x8*)(lds + PG8_SB(b, h) + boff + n * 2048 + k * 1024); } while (0)
; #define PG8_MMA(ai, bj, At, Bt) do { __builtin_amdgcn_s_setprio(1); _Pragma("unroll") for (int m = 0; m < 4; ++m) _Pragma("unroll") for (int n = 0; n < 2; ++n) _Pragma("unroll") for (int k = 0; k < 2; ++k) \
;         acc[ai][bj][m][n] = __builtin_amdgcn_mfma_f32_16x16x32_bf16(Bt[n][k], At[m][k], acc[ai][bj][m][n], 0, 0, 0); __builtin_amdgcn_s_setprio(0); } while (0)
; #define PG8_WAIT_V(n) asm volatile("s_waitcnt vmcnt(" #n ")" ::: "memory")
; #define PG8_WAIT_L(n) asm volatile("s_waitcnt lgkmcnt(" #n ")" ::: "memory")
; #define PG8_BAR __builtin_amdgcn_s_barrier()
; #define PG8_SCHED __builtin_amdgcn_sched_barrier(0)
; template <class Epi, class Sched, bool ALIGN_EPI, class Hook = NoHook>
; __device__ __forceinline__ void gemm_phase(LAS unsigned char* lds, const Gemm g, const Sched& S, const Epi& E, const Hook& H = Hook()) {
;     ...
;             PG8_LDB(B0, 1, 0); PG8_LDB(B1, 1, 1); PG8_SCHED; PG8_LDA(At, 1, 0); PG8_STAGE(PG8_SA(0, 1), a2 + hA, voffA);
;             PG8_WAIT_V(8); PG8_WAIT_L(0); PG8_BAR; PG8_MMA(0, 0, At, B0); PG8_MMA(0, 1, At, B1); PG8_BAR; PG8_SCHED;
;             PG8_LDA(At, 1, 1); PG8_STAGE(PG8_SB(1, 0), b3, voffB); PG8_STAGE(PG8_SB(1, 1), b3 + hB, voffB); PG8_STAGE(PG8_SA(1, 0), a3, voffA);
;             PG8_WAIT_V(8); PG8_WAIT_L(0); PG8_BAR; PG8_MMA(1, 0, At, B0); PG8_MMA(1, 1, At, B1); PG8_BAR; PG8_SCHED;
;         }
;         if constexpr (Hook::ON) H.after(te, acc, cur, wr, wc, fr, fq);
;         }
;         if constexpr (ALIGN_EPI) { if (wr == 0) PG8_BAR; }
	ds_read_b128 v[146:149], v143
	ds_read_b128 v[150:153], v143 offset:1024
	ds_read_b128 v[154:157], v143 offset:2048
	ds_read_b128 v[158:161], v143 offset:3072
	ds_read_b128 v[162:165], v144
	ds_read_b128 v[166:169], v144 offset:1024
	ds_read_b128 v[170:173], v144 offset:2048
	ds_read_b128 v[174:177], v144 offset:3072
	s_add_u32 s16, s16, 0x100000
	s_addc_u32 s17, s17, 0
	s_mov_b32 m0, s29
	ds_read_b128 v[186:189], v142 offset:32768
	ds_read_b128 v[190:193], v142 offset:33792
	ds_read_b128 v[194:197], v142 offset:34816
	ds_read_b128 v[198:201], v142 offset:35840
	ds_read_b128 v[202:205], v142 offset:36864
	ds_read_b128 v[206:209], v142 offset:37888
	ds_read_b128 v[210:213], v142 offset:38912
	ds_read_b128 v[214:217], v142 offset:39936
	global_load_lds_dwordx4 v130, s[16:17]
	s_mov_b32 m0, s39
	s_nop 0
	global_load_lds_dwordx4 v132, s[16:17]
	s_waitcnt vmcnt(8)
	s_waitcnt lgkmcnt(0)
	s_barrier
	s_setprio 1
	s_waitcnt lgkmcnt(0)
	v_mfma_f32_16x16x32_bf16 v[54:57], v[146:149], v[186:189], v[54:57]
	v_mfma_f32_16x16x32_bf16 v[34:37], v[154:157], v[186:189], v[34:37]
	v_mfma_f32_16x16x32_bf16 v[42:45], v[146:149], v[194:197], v[42:45]
	v_mfma_f32_16x16x32_bf16 v[30:33], v[154:157], v[194:197], v[30:33]
	v_mfma_f32_16x16x32_bf16 v[62:65], v[146:149], v[202:205], v[62:65]
	v_mfma_f32_16x16x32_bf16 v[50:53], v[154:157], v[202:205], v[50:53]
	v_mfma_f32_16x16x32_bf16 v[78:81], v[146:149], v[210:213], v[78:81]
	v_mfma_f32_16x16x32_bf16 v[70:73], v[154:157], v[210:213], v[70:73]
	v_mfma_f32_16x16x32_bf16 v[54:57], v[150:153], v[190:193], v[54:57]
	v_mfma_f32_16x16x32_bf16 v[34:37], v[158:161], v[190:193], v[34:37]
	v_mfma_f32_16x16x32_bf16 v[42:45], v[150:153], v[198:201], v[42:45]
	v_mfma_f32_16x16x32_bf16 v[30:33], v[158:161], v[198:201], v[30:33]
	v_mfma_f32_16x16x32_bf16 v[62:65], v[150:153], v[206:209], v[62:65]
	v_mfma_f32_16x16x32_bf16 v[50:53], v[158:161], v[206:209], v[50:53]
	v_mfma_f32_16x16x32_bf16 v[78:81], v[150:153], v[214:217], v[78:81]
	v_mfma_f32_16x16x32_bf16 v[70:73], v[158:161], v[214:217], v[70:73]
	s_setprio 0
	s_setprio 1
	v_mfma_f32_16x16x32_bf16 v[10:13], v[162:165], v[186:189], v[10:13]
	v_mfma_f32_16x16x32_bf16 v[2:5], v[170:173], v[186:189], v[2:5]
	v_mfma_f32_16x16x32_bf16 v[14:17], v[162:165], v[194:197], v[14:17]
	v_mfma_f32_16x16x32_bf16 v[6:9], v[170:173], v[194:197], v[6:9]
	v_mfma_f32_16x16x32_bf16 v[22:25], v[162:165], v[202:205], v[22:25]
	v_mfma_f32_16x16x32_bf16 v[18:21], v[170:173], v[202:205], v[18:21]
	v_mfma_f32_16x16x32_bf16 v[38:41], v[162:165], v[210:213], v[38:41]
	v_mfma_f32_16x16x32_bf16 v[26:29], v[170:173], v[210:213], v[26:29]
	v_mfma_f32_16x16x32_bf16 v[10:13], v[166:169], v[190:193], v[10:13]
	v_mfma_f32_16x16x32_bf16 v[2:5], v[174:177], v[190:193], v[2:5]
	v_mfma_f32_16x16x32_bf16 v[14:17], v[166:169], v[198:201], v[14:17]
	v_mfma_f32_16x16x32_bf16 v[6:9], v[174:177], v[198:201], v[6:9]
	v_mfma_f32_16x16x32_bf16 v[22:25], v[166:169], v[206:209], v[22:25]
	v_mfma_f32_16x16x32_bf16 v[18:21], v[174:177], v[206:209], v[18:21]
	v_mfma_f32_16x16x32_bf16 v[38:41], v[166:169], v[214:217], v[38:41]
	v_mfma_f32_16x16x32_bf16 v[26:29], v[174:177], v[214:217], v[26:29]
	s_setprio 0
	s_barrier
	s_mov_b32 m0, s36
	s_add_u32 s48, s10, s4
	s_addc_u32 s49, s11, s5
	s_add_u32 s10, s10, 0x100080
	ds_read_b128 v[186:189], v142 offset:49152
	ds_read_b128 v[190:193], v142 offset:50176
	ds_read_b128 v[194:197], v142 offset:51200
	ds_read_b128 v[198:201], v142 offset:52224
	ds_read_b128 v[202:205], v142 offset:53248
	ds_read_b128 v[206:209], v142 offset:54272
	ds_read_b128 v[210:213], v142 offset:55296
	ds_read_b128 v[214:217], v142 offset:56320
	global_load_lds_dwordx4 v180, s[48:49]
	s_mov_b32 m0, s43
	s_addc_u32 s11, s11, 0
	global_load_lds_dwordx4 v134, s[48:49]
	s_mov_b32 m0, s37
	s_nop 0
	global_load_lds_dwordx4 v180, s[10:11]
	s_mov_b32 m0, s44
	s_nop 0
	global_load_lds_dwordx4 v134, s[10:11]
	v_lshl_add_u64 v[178:179], v[220:221], 0, s[4:5]
	s_mov_b32 m0, s40
	s_nop 0
	global_load_lds_dwordx4 v[178:179], off
	v_lshl_add_u64 v[178:179], v[222:223], 0, s[4:5]
	s_mov_b32 m0, s41
	s_nop 0
	global_load_lds_dwordx4 v[178:179], off
	s_waitcnt vmcnt(8)
	s_waitcnt lgkmcnt(0)
	s_barrier
	s_setprio 1
	s_waitcnt lgkmcnt(0)
	v_mfma_f32_16x16x32_bf16 v[94:97], v[146:149], v[186:189], v[94:97]
	v_mfma_f32_16x16x32_bf16 v[86:89], v[154:157], v[186:189], v[86:89]
	v_mfma_f32_16x16x32_bf16 v[102:105], v[146:149], v[194:197], v[102:105]
	v_mfma_f32_16x16x32_bf16 v[98:101], v[154:157], v[194:197], v[98:101]
	v_mfma_f32_16x16x32_bf16 v[110:113], v[146:149], v[202:205], v[110:113]
	v_mfma_f32_16x16x32_bf16 v[106:109], v[154:157], v[202:205], v[106:109]
	v_mfma_f32_16x16x32_bf16 v[126:129], v[146:149], v[210:213], v[126:129]
	v_mfma_f32_16x16x32_bf16 v[122:125], v[154:157], v[210:213], v[122:125]
	v_mfma_f32_16x16x32_bf16 v[94:97], v[150:153], v[190:193], v[94:97]
	v_mfma_f32_16x16x32_bf16 v[86:89], v[158:161], v[190:193], v[86:89]
	v_mfma_f32_16x16x32_bf16 v[102:105], v[150:153], v[198:201], v[102:105]
	v_mfma_f32_16x16x32_bf16 v[98:101], v[158:161], v[198:201], v[98:101]
	v_mfma_f32_16x16x32_bf16 v[110:113], v[150:153], v[206:209], v[110:113]
	v_mfma_f32_16x16x32_bf16 v[106:109], v[158:161], v[206:209], v[106:109]
	v_mfma_f32_16x16x32_bf16 v[126:129], v[150:153], v[214:217], v[126:129]
	v_mfma_f32_16x16x32_bf16 v[122:125], v[158:161], v[214:217], v[122:125]
	s_setprio 0
	s_setprio 1
	v_mfma_f32_16x16x32_bf16 v[58:61], v[162:165], v[186:189], v[58:61]
	v_mfma_f32_16x16x32_bf16 v[46:49], v[170:173], v[186:189], v[46:49]
	v_mfma_f32_16x16x32_bf16 v[74:77], v[162:165], v[194:197], v[74:77]
	v_mfma_f32_16x16x32_bf16 v[66:69], v[170:173], v[194:197], v[66:69]
	v_mfma_f32_16x16x32_bf16 v[90:93], v[162:165], v[202:205], v[90:93]
	v_mfma_f32_16x16x32_bf16 v[82:85], v[170:173], v[202:205], v[82:85]
	v_mfma_f32_16x16x32_bf16 v[118:121], v[162:165], v[210:213], v[118:121]
	v_mfma_f32_16x16x32_bf16 v[114:117], v[170:173], v[210:213], v[114:117]
	v_mfma_f32_16x16x32_bf16 v[58:61], v[166:169], v[190:193], v[58:61]
	v_mfma_f32_16x16x32_bf16 v[46:49], v[174:177], v[190:193], v[46:49]
	v_mfma_f32_16x16x32_bf16 v[74:77], v[166:169], v[198:201], v[74:77]
	v_mfma_f32_16x16x32_bf16 v[66:69], v[174:177], v[198:201], v[66:69]
	v_mfma_f32_16x16x32_bf16 v[90:93], v[166:169], v[206:209], v[90:93]
	v_mfma_f32_16x16x32_bf16 v[82:85], v[174:177], v[206:209], v[82:85]
	v_mfma_f32_16x16x32_bf16 v[118:121], v[166:169], v[214:217], v[118:121]
	v_mfma_f32_16x16x32_bf16 v[114:117], v[174:177], v[214:217], v[114:117]
	s_setprio 0
	s_barrier
	s_add_i32 s18, s18, 2
	s_add_u32 s6, s6, 0x100
	s_addc_u32 s7, s7, 0
	s_cmp_gt_u32 s18, 61
	s_cbranch_scc0 .LBB0_896
	s_cmpk_lt_u32 s22, 0x100
	s_cbranch_scc0 .LBB0_899
	s_barrier

; #define PG8_STAGE(bufoff, gbase, voff) do { _Pragma("unroll") for (int _i = 0; _i < 2; ++_i) \
;         __builtin_amdgcn_global_load_lds((const unsigned*)((const char*)(gbase) + (voff)[_i]), (LAS unsigned*)(lds + (bufoff) + ldsw + _i * 8192), 16, 0, 0); } while (0)
; #define PG8_LDA(dst, b, h) do { _Pragma("unroll") for (int m = 0; m < 4; ++m) _Pragma("unroll") for (int k = 0; k < 2; ++k) dst[m][k] = *(const LAS bf16x8*)(lds + PG8_SA(b, h) + aoff + m * 2048 + k * 1024); } while (0)
; #define PG8_LDB(dst, b, h) do { _Pragma("unroll") for (int n = 0; n < 2; ++n) _Pragma("unroll") for (int k = 0; k < 2; ++k) dst[n][k] = *(const LAS bf16x8*)(lds + PG8_SB(b, h) + boff + n * 2048 + k * 1024); } while (0)
; #define PG8_MMA(ai, bj, At, Bt) do { __builtin_amdgcn_s_setprio(1); _Pragma("unroll") for (int m = 0; m < 4; ++m) _Pragma("unroll") for (int n = 0; n < 2; ++n) _Pragma("unroll") for (int k = 0; k < 2; ++k) \
;         acc[ai][bj][m][n] = __builtin_amdgcn_mfma_f32_16x16x32_bf16(Bt[n][k], At[m][k], acc[ai][bj][m][n], 0, 0, 0); __builtin_amdgcn_s_setprio(0); } while (0)
; #define PG8_WAIT_V(n) asm volatile("s_waitcnt vmcnt(" #n ")" ::: "memory")
; #define PG8_WAIT_L(n) asm volatile("s_waitcnt lgkmcnt(" #n ")" ::: "memory")
; #define PG8_BAR __builtin_amdgcn_s_barrier()
; template <class Epi, class Sched, bool ALIGN_EPI, class Hook = NoHook>
; __device__ __forceinline__ void gemm_phase(LAS unsigned char* lds, const Gemm g, const Sched& S, const Epi& E, const Hook& H = Hook()) {
;     ...
;             const bool last = (t == nt - 2);
;             const char* a1 = cA + (size_t)(t + 1) * kstep;
;             const char* a2 = last ? nA : cA + (size_t)(t + 2) * kstep; const char* b2 = last ? nB : cB + (size_t)(t + 2) * kstep;
;             const char* a3 = a2 + kstep; const char* b3 = b2 + kstep;
;             if (last && has_next) S.a_ready(nxt);
;             PG8_LDB(B0, 0, 0); PG8_LDB(B1, 0, 1); PG8_SCHED; PG8_LDA(At, 0, 0); PG8_STAGE(PG8_SA(1, 1), a1 + hA, voffA);
;             PG8_WAIT_V(8); PG8_WAIT_L(0); PG8_BAR; PG8_MMA(0, 0, At, B0); PG8_MMA(0, 1, At, B1); PG8_BAR; PG8_SCHED;
;             PG8_LDA(At, 0, 1); PG8_STAGE(PG8_SB(0, 0), b2, voffB); PG8_STAGE(PG8_SB(0, 1), b2 + hB, voffB); PG8_STAGE(PG8_SA(0, 0), a2, voffA);
;             PG8_WAIT_V(8); PG8_WAIT_L(0); PG8_BAR; PG8_MMA(1, 0, At, B0); PG8_MMA(1, 1, At, B1); PG8_BAR; PG8_SCHED;
.LBB0_1001:
	ds_read_b128 v[106:109], v246
	ds_read_b128 v[110:113], v246 offset:1024
	ds_read_b128 v[114:117], v246 offset:2048
	ds_read_b128 v[118:121], v246 offset:3072
	ds_read_b128 v[122:125], v247
	ds_read_b128 v[126:129], v247 offset:1024
	ds_read_b128 v[130:133], v247 offset:2048
	ds_read_b128 v[134:137], v247 offset:3072
	s_add_u32 s42, s6, 0x100
	s_addc_u32 s43, s7, 0
	s_cmp_eq_u32 s70, 60
	s_cselect_b32 s47, s35, s43
	s_cselect_b32 s46, s66, s42
	s_cselect_b32 s45, s31, s69
	s_cselect_b32 s44, s67, s68
	s_add_i32 m0, s51, 0xc000
	ds_read_b128 v[138:141], v248
	ds_read_b128 v[142:145], v248 offset:1024
	ds_read_b128 v[146:149], v248 offset:2048
	ds_read_b128 v[150:153], v248 offset:3072
	ds_read_b128 v[154:157], v248 offset:4096
	ds_read_b128 v[158:161], v248 offset:5120
	ds_read_b128 v[162:165], v248 offset:6144
	ds_read_b128 v[170:173], v248 offset:7168
	global_load_lds_dwordx4 v236, s[6:7]
	s_add_i32 m0, s51, 0xe000
	s_nop 0
	global_load_lds_dwordx4 v238, s[6:7]
	s_waitcnt vmcnt(8)
	s_waitcnt lgkmcnt(0)
	s_barrier
	s_setprio 1
	s_waitcnt lgkmcnt(0)
	v_mfma_f32_16x16x32_bf16 v[190:193], v[106:109], v[138:141], v[190:193]
	v_mfma_f32_16x16x32_bf16 v[178:181], v[114:117], v[138:141], v[178:181]
	v_mfma_f32_16x16x32_bf16 v[182:185], v[106:109], v[146:149], v[182:185]
	v_mfma_f32_16x16x32_bf16 v[98:101], v[114:117], v[146:149], v[98:101]
	v_mfma_f32_16x16x32_bf16 v[102:105], v[106:109], v[154:157], v[102:105]
	v_mfma_f32_16x16x32_bf16 v[86:89], v[114:117], v[154:157], v[86:89]
	v_mfma_f32_16x16x32_bf16 v[78:81], v[106:109], v[162:165], v[78:81]
	v_mfma_f32_16x16x32_bf16 v[70:73], v[114:117], v[162:165], v[70:73]
	v_mfma_f32_16x16x32_bf16 v[190:193], v[110:113], v[142:145], v[190:193]
	v_mfma_f32_16x16x32_bf16 v[178:181], v[118:121], v[142:145], v[178:181]
	v_mfma_f32_16x16x32_bf16 v[182:185], v[110:113], v[150:153], v[182:185]
	v_mfma_f32_16x16x32_bf16 v[98:101], v[118:121], v[150:153], v[98:101]
	v_mfma_f32_16x16x32_bf16 v[102:105], v[110:113], v[158:161], v[102:105]
	v_mfma_f32_16x16x32_bf16 v[86:89], v[118:121], v[158:161], v[86:89]
	v_mfma_f32_16x16x32_bf16 v[78:81], v[110:113], v[170:173], v[78:81]
	v_mfma_f32_16x16x32_bf16 v[70:73], v[118:121], v[170:173], v[70:73]
	s_setprio 0
	s_setprio 1
	v_mfma_f32_16x16x32_bf16 v[186:189], v[122:125], v[138:141], v[186:189]
	v_mfma_f32_16x16x32_bf16 v[138:141], v[130:133], v[138:141], v[174:177]
	v_mfma_f32_16x16x32_bf16 v[94:97], v[130:133], v[146:149], v[94:97]
	v_mfma_f32_16x16x32_bf16 v[90:93], v[122:125], v[154:157], v[90:93]
	v_mfma_f32_16x16x32_bf16 v[82:85], v[130:133], v[154:157], v[82:85]
	v_mfma_f32_16x16x32_bf16 v[74:77], v[122:125], v[162:165], v[74:77]
	v_mfma_f32_16x16x32_bf16 v[66:69], v[130:133], v[162:165], v[66:69]
	v_mfma_f32_16x16x32_bf16 v[186:189], v[126:129], v[142:145], v[186:189]
	v_mfma_f32_16x16x32_bf16 v[138:141], v[134:137], v[142:145], v[138:141]
	v_mfma_f32_16x16x32_bf16 v[142:145], v[122:125], v[146:149], v[166:169]
	v_mfma_f32_16x16x32_bf16 v[94:97], v[134:137], v[150:153], v[94:97]
	v_mfma_f32_16x16x32_bf16 v[90:93], v[126:129], v[158:161], v[90:93]
	v_mfma_f32_16x16x32_bf16 v[82:85], v[134:137], v[158:161], v[82:85]
	v_mfma_f32_16x16x32_bf16 v[74:77], v[126:129], v[170:173], v[74:77]
	v_mfma_f32_16x16x32_bf16 v[66:69], v[134:137], v[170:173], v[66:69]
	v_mfma_f32_16x16x32_bf16 v[142:145], v[126:129], v[150:153], v[142:145]
	s_setprio 0
	s_barrier
	s_add_i32 s6, s63, s29
	s_mov_b32 m0, s6
	ds_read_b128 v[146:149], v248 offset:16384
	ds_read_b128 v[150:153], v248 offset:17408
	ds_read_b128 v[154:157], v248 offset:18432
	ds_read_b128 v[158:161], v248 offset:19456
	ds_read_b128 v[162:165], v248 offset:20480
	ds_read_b128 v[166:169], v248 offset:21504
	ds_read_b128 v[170:173], v248 offset:22528
	ds_read_b128 v[174:177], v248 offset:23552
	global_load_lds_dwordx4 v232, s[44:45]
	s_add_i32 m0, s6, 0x2000
	s_add_u32 s6, s44, 0x100000
	s_addc_u32 s7, s45, 0
	s_add_i32 s71, s64, s29
	global_load_lds_dwordx4 v228, s[44:45]
	s_mov_b32 m0, s71
	s_nop 0
	global_load_lds_dwordx4 v232, s[6:7]
	s_add_i32 m0, s71, 0x2000
	s_nop 0
	global_load_lds_dwordx4 v228, s[6:7]
	s_mov_b32 m0, s51
	s_nop 0
	global_load_lds_dwordx4 v234, s[46:47]
	s_mov_b32 m0, s52
	s_nop 0
	global_load_lds_dwordx4 v230, s[46:47]
	s_waitcnt vmcnt(8)
	s_waitcnt lgkmcnt(0)
	s_barrier
	s_setprio 1
	s_waitcnt lgkmcnt(0)
	v_mfma_f32_16x16x32_bf16 v[62:65], v[106:109], v[146:149], v[62:65]
	v_mfma_f32_16x16x32_bf16 v[54:57], v[114:117], v[146:149], v[54:57]
	v_mfma_f32_16x16x32_bf16 v[46:49], v[106:109], v[154:157], v[46:49]
	v_mfma_f32_16x16x32_bf16 v[22:25], v[114:117], v[154:157], v[22:25]
	v_mfma_f32_16x16x32_bf16 v[42:45], v[106:109], v[162:165], v[42:45]
	v_mfma_f32_16x16x32_bf16 v[10:13], v[114:117], v[162:165], v[10:13]
	v_mfma_f32_16x16x32_bf16 v[38:41], v[106:109], v[170:173], v[38:41]
	v_mfma_f32_16x16x32_bf16 v[14:17], v[114:117], v[170:173], v[14:17]
	v_mfma_f32_16x16x32_bf16 v[62:65], v[110:113], v[150:153], v[62:65]
	v_mfma_f32_16x16x32_bf16 v[54:57], v[118:121], v[150:153], v[54:57]
	v_mfma_f32_16x16x32_bf16 v[46:49], v[110:113], v[158:161], v[46:49]
	v_mfma_f32_16x16x32_bf16 v[22:25], v[118:121], v[158:161], v[22:25]
	v_mfma_f32_16x16x32_bf16 v[42:45], v[110:113], v[166:169], v[42:45]
	v_mfma_f32_16x16x32_bf16 v[10:13], v[118:121], v[166:169], v[10:13]
	v_mfma_f32_16x16x32_bf16 v[38:41], v[110:113], v[174:177], v[38:41]
	v_mfma_f32_16x16x32_bf16 v[14:17], v[118:121], v[174:177], v[14:17]
	s_setprio 0
	s_setprio 1
	v_mfma_f32_16x16x32_bf16 v[58:61], v[122:125], v[146:149], v[58:61]
	v_mfma_f32_16x16x32_bf16 v[50:53], v[130:133], v[146:149], v[50:53]
	v_mfma_f32_16x16x32_bf16 v[34:37], v[122:125], v[154:157], v[34:37]
	v_mfma_f32_16x16x32_bf16 v[18:21], v[130:133], v[154:157], v[18:21]
	v_mfma_f32_16x16x32_bf16 v[30:33], v[122:125], v[162:165], v[30:33]
	v_mfma_f32_16x16x32_bf16 v[2:5], v[130:133], v[162:165], v[2:5]
	v_mfma_f32_16x16x32_bf16 v[26:29], v[122:125], v[170:173], v[26:29]
	v_mfma_f32_16x16x32_bf16 v[6:9], v[130:133], v[170:173], v[6:9]
	v_mfma_f32_16x16x32_bf16 v[58:61], v[126:129], v[150:153], v[58:61]
	v_mfma_f32_16x16x32_bf16 v[50:53], v[134:137], v[150:153], v[50:53]
	v_mfma_f32_16x16x32_bf16 v[34:37], v[126:129], v[158:161], v[34:37]
	v_mfma_f32_16x16x32_bf16 v[18:21], v[134:137], v[158:161], v[18:21]
	v_mfma_f32_16x16x32_bf16 v[30:33], v[126:129], v[166:169], v[30:33]
	v_mfma_f32_16x16x32_bf16 v[2:5], v[134:137], v[166:169], v[2:5]
	v_mfma_f32_16x16x32_bf16 v[26:29], v[126:129], v[174:177], v[26:29]
	v_mfma_f32_16x16x32_bf16 v[6:9], v[134:137], v[174:177], v[6:9]
	s_setprio 0
	s_barrier
; #define PG8_STAGE(bufoff, gbase, voff) do { _Pragma("unroll") for (int _i = 0; _i < 2; ++_i) \
;         __builtin_amdgcn_global_load_lds((const unsigned*)((const char*)(gbase) + (voff)[_i]), (LAS unsigned*)(lds + (bufoff) + ldsw + _i * 8192), 16, 0, 0); } while (0)
; #define PG8_LDA(dst, b, h) do { _Pragma("unroll") for (int m = 0; m < 4; ++m) _Pragma("unroll") for (int k = 0; k < 2; ++k) dst[m][k] = *(const LAS bf16x8*)(lds + PG8_SA(b, h) + aoff + m * 2048 + k * 1024); } while (0)
; #define PG8_LDB(dst, b, h) do { _Pragma("unroll") for (int n = 0; n < 2; ++n) _Pragma("unroll") for (int k = 0; k < 2; ++k) dst[n][k] = *(const LAS bf16x8*)(lds + PG8_SB(b, h) + boff + n * 2048 + k * 1024); } while (0)
; #define PG8_MMA(ai, bj, At, Bt) do { __builtin_amdgcn_s_setprio(1); _Pragma("unroll") for (int m = 0; m < 4; ++m) _Pragma("unroll") for (int n = 0; n < 2; ++n) _Pragma("unroll") for (int k = 0; k < 2; ++k) \
;         acc[ai][bj][m][n] = __builtin_amdgcn_mfma_f32_16x16x32_bf16(Bt[n][k], At[m][k], acc[ai][bj][m][n], 0, 0, 0); __builtin_amdgcn_s_setprio(0); } while (0)
; #define PG8_WAIT_V(n) asm volatile("s_waitcnt vmcnt(" #n ")" ::: "memory")
; #define PG8_WAIT_L(n) asm volatile("s_waitcnt lgkmcnt(" #n ")" ::: "memory")
; #define PG8_BAR __builtin_amdgcn_s_barrier()
; #define PG8_SCHED __builtin_amdgcn_sched_barrier(0)
; template <class Epi, class Sched, bool ALIGN_EPI, class Hook = NoHook>
; __device__ __forceinline__ void gemm_phase(LAS unsigned char* lds, const Gemm g, const Sched& S, const Epi& E, const Hook& H = Hook()) {
;     ...
;             PG8_LDB(B0, 1, 0); PG8_LDB(B1, 1, 1); PG8_SCHED; PG8_LDA(At, 1, 0); PG8_STAGE(PG8_SA(0, 1), a2 + hA, voffA);
;             PG8_WAIT_V(8); PG8_WAIT_L(0); PG8_BAR; PG8_MMA(0, 0, At, B0); PG8_MMA(0, 1, At, B1); PG8_BAR; PG8_SCHED;
;             PG8_LDA(At, 1, 1); PG8_STAGE(PG8_SB(1, 0), b3, voffB); PG8_STAGE(PG8_SB(1, 1), b3 + hB, voffB); PG8_STAGE(PG8_SA(1, 0), a3, voffA);
;             PG8_WAIT_V(8); PG8_WAIT_L(0); PG8_BAR; PG8_MMA(1, 0, At, B0); PG8_MMA(1, 1, At, B1); PG8_BAR; PG8_SCHED;
;         }
;         if constexpr (Hook::ON) H.after(te, acc, cur, wr, wc, fr, fq);
;         }
;         if constexpr (ALIGN_EPI) { if (wr == 0) PG8_BAR; }
	s_add_i32 s71, 0, 0x18000
	s_add_i32 s72, 0, 0x1c000
	v_add_u32_e32 v118, s71, v245
	v_add_u32_e32 v134, s72, v245
	ds_read_b128 v[106:109], v118
	ds_read_b128 v[110:113], v118 offset:1024
	ds_read_b128 v[114:117], v118 offset:2048
	ds_read_b128 v[118:121], v118 offset:3072
	ds_read_b128 v[122:125], v134
	ds_read_b128 v[126:129], v134 offset:1024
	ds_read_b128 v[130:133], v134 offset:2048
	ds_read_b128 v[134:137], v134 offset:3072
	s_add_u32 s6, s46, 0x8000
	s_addc_u32 s7, s47, 0
	s_mov_b32 m0, s53
	ds_read_b128 v[146:149], v248 offset:32768
	ds_read_b128 v[150:153], v248 offset:33792
	ds_read_b128 v[154:157], v248 offset:34816
	ds_read_b128 v[158:161], v248 offset:35840
	ds_read_b128 v[162:165], v248 offset:36864
	ds_read_b128 v[170:173], v248 offset:37888
	ds_read_b128 v[194:197], v248 offset:38912
	ds_read_b128 v[198:201], v248 offset:39936
	global_load_lds_dwordx4 v234, s[6:7]
	s_mov_b32 m0, s54
	s_nop 0
	global_load_lds_dwordx4 v230, s[6:7]
	s_waitcnt vmcnt(8)
	s_waitcnt lgkmcnt(0)
	s_barrier
	s_setprio 1
	s_waitcnt lgkmcnt(0)
	v_mfma_f32_16x16x32_bf16 v[166:169], v[106:109], v[146:149], v[190:193]
	v_mfma_f32_16x16x32_bf16 v[190:193], v[110:113], v[150:153], v[166:169]
	v_mfma_f32_16x16x32_bf16 v[166:169], v[114:117], v[146:149], v[178:181]
	v_mfma_f32_16x16x32_bf16 v[178:181], v[118:121], v[150:153], v[166:169]
	v_mfma_f32_16x16x32_bf16 v[166:169], v[106:109], v[154:157], v[182:185]
	v_mfma_f32_16x16x32_bf16 v[98:101], v[114:117], v[154:157], v[98:101]
	v_mfma_f32_16x16x32_bf16 v[102:105], v[106:109], v[162:165], v[102:105]
	v_mfma_f32_16x16x32_bf16 v[86:89], v[114:117], v[162:165], v[86:89]
	v_mfma_f32_16x16x32_bf16 v[78:81], v[106:109], v[194:197], v[78:81]
	v_mfma_f32_16x16x32_bf16 v[70:73], v[114:117], v[194:197], v[70:73]
	v_mfma_f32_16x16x32_bf16 v[182:185], v[110:113], v[158:161], v[166:169]
	v_mfma_f32_16x16x32_bf16 v[98:101], v[118:121], v[158:161], v[98:101]
	v_mfma_f32_16x16x32_bf16 v[102:105], v[110:113], v[170:173], v[102:105]
	v_mfma_f32_16x16x32_bf16 v[86:89], v[118:121], v[170:173], v[86:89]
	v_mfma_f32_16x16x32_bf16 v[78:81], v[110:113], v[198:201], v[78:81]
	v_mfma_f32_16x16x32_bf16 v[70:73], v[118:121], v[198:201], v[70:73]
	s_setprio 0
	s_setprio 1
	v_mfma_f32_16x16x32_bf16 v[138:141], v[130:133], v[146:149], v[138:141]
	v_mfma_f32_16x16x32_bf16 v[166:169], v[122:125], v[146:149], v[186:189]
	v_mfma_f32_16x16x32_bf16 v[174:177], v[134:137], v[150:153], v[138:141]
	v_mfma_f32_16x16x32_bf16 v[138:141], v[122:125], v[154:157], v[142:145]
	v_mfma_f32_16x16x32_bf16 v[94:97], v[130:133], v[154:157], v[94:97]
	v_mfma_f32_16x16x32_bf16 v[90:93], v[122:125], v[162:165], v[90:93]
	v_mfma_f32_16x16x32_bf16 v[82:85], v[130:133], v[162:165], v[82:85]
	v_mfma_f32_16x16x32_bf16 v[74:77], v[122:125], v[194:197], v[74:77]
	v_mfma_f32_16x16x32_bf16 v[66:69], v[130:133], v[194:197], v[66:69]
	v_mfma_f32_16x16x32_bf16 v[186:189], v[126:129], v[150:153], v[166:169]
	v_mfma_f32_16x16x32_bf16 v[166:169], v[126:129], v[158:161], v[138:141]
	v_mfma_f32_16x16x32_bf16 v[94:97], v[134:137], v[158:161], v[94:97]
	v_mfma_f32_16x16x32_bf16 v[90:93], v[126:129], v[170:173], v[90:93]
	v_mfma_f32_16x16x32_bf16 v[82:85], v[134:137], v[170:173], v[82:85]
	v_mfma_f32_16x16x32_bf16 v[74:77], v[126:129], v[198:201], v[74:77]
	v_mfma_f32_16x16x32_bf16 v[66:69], v[134:137], v[198:201], v[66:69]
	s_setprio 0
	s_barrier
	s_add_i32 s6, s71, s29
	s_add_u32 s74, s44, s14
	s_addc_u32 s75, s45, s15
	s_mov_b32 m0, s6
	ds_read_b128 v[138:141], v248 offset:49152
	ds_read_b128 v[142:145], v248 offset:50176
	ds_read_b128 v[146:149], v248 offset:51200
	ds_read_b128 v[150:153], v248 offset:52224
	ds_read_b128 v[154:157], v248 offset:53248
	ds_read_b128 v[158:161], v248 offset:54272
	ds_read_b128 v[162:165], v248 offset:55296
	ds_read_b128 v[170:173], v248 offset:56320
	global_load_lds_dwordx4 v232, s[74:75]
	s_add_i32 m0, s6, 0x2000
	s_add_u32 s6, s44, 0x100080
	s_addc_u32 s7, s45, 0
	s_add_i32 s44, s72, s29
	global_load_lds_dwordx4 v228, s[74:75]
	s_mov_b32 m0, s44
	s_nop 0
	global_load_lds_dwordx4 v232, s[6:7]
	s_add_i32 m0, s44, 0x2000
	s_nop 0
	global_load_lds_dwordx4 v228, s[6:7]
	s_add_u32 s78, s46, s14
	s_addc_u32 s79, s47, s15
	s_mov_b32 m0, s57
	s_nop 0
	global_load_lds_dwordx4 v234, s[78:79]
	s_mov_b32 m0, s58
	s_nop 0
	global_load_lds_dwordx4 v230, s[78:79]
	s_waitcnt vmcnt(8)
	s_waitcnt lgkmcnt(0)
	s_barrier
	s_setprio 1
	s_waitcnt lgkmcnt(0)
	v_mfma_f32_16x16x32_bf16 v[62:65], v[106:109], v[138:141], v[62:65]
	v_mfma_f32_16x16x32_bf16 v[54:57], v[114:117], v[138:141], v[54:57]
	v_mfma_f32_16x16x32_bf16 v[46:49], v[106:109], v[146:149], v[46:49]
	v_mfma_f32_16x16x32_bf16 v[22:25], v[114:117], v[146:149], v[22:25]
	v_mfma_f32_16x16x32_bf16 v[42:45], v[106:109], v[154:157], v[42:45]
	v_mfma_f32_16x16x32_bf16 v[10:13], v[114:117], v[154:157], v[10:13]
	v_mfma_f32_16x16x32_bf16 v[38:41], v[106:109], v[162:165], v[38:41]
	v_mfma_f32_16x16x32_bf16 v[14:17], v[114:117], v[162:165], v[14:17]
	v_mfma_f32_16x16x32_bf16 v[62:65], v[110:113], v[142:145], v[62:65]
	v_mfma_f32_16x16x32_bf16 v[54:57], v[118:121], v[142:145], v[54:57]
	v_mfma_f32_16x16x32_bf16 v[46:49], v[110:113], v[150:153], v[46:49]
	v_mfma_f32_16x16x32_bf16 v[22:25], v[118:121], v[150:153], v[22:25]
	v_mfma_f32_16x16x32_bf16 v[42:45], v[110:113], v[158:161], v[42:45]
	v_mfma_f32_16x16x32_bf16 v[10:13], v[118:121], v[158:161], v[10:13]
	v_mfma_f32_16x16x32_bf16 v[38:41], v[110:113], v[170:173], v[38:41]
	v_mfma_f32_16x16x32_bf16 v[14:17], v[118:121], v[170:173], v[14:17]
	s_setprio 0
	s_setprio 1
	v_mfma_f32_16x16x32_bf16 v[58:61], v[122:125], v[138:141], v[58:61]
	v_mfma_f32_16x16x32_bf16 v[50:53], v[130:133], v[138:141], v[50:53]
	v_mfma_f32_16x16x32_bf16 v[34:37], v[122:125], v[146:149], v[34:37]
	v_mfma_f32_16x16x32_bf16 v[18:21], v[130:133], v[146:149], v[18:21]
	v_mfma_f32_16x16x32_bf16 v[30:33], v[122:125], v[154:157], v[30:33]
	v_mfma_f32_16x16x32_bf16 v[2:5], v[130:133], v[154:157], v[2:5]
	v_mfma_f32_16x16x32_bf16 v[26:29], v[122:125], v[162:165], v[26:29]
	v_mfma_f32_16x16x32_bf16 v[6:9], v[130:133], v[162:165], v[6:9]
	v_mfma_f32_16x16x32_bf16 v[58:61], v[126:129], v[142:145], v[58:61]
	v_mfma_f32_16x16x32_bf16 v[50:53], v[134:137], v[142:145], v[50:53]
	v_mfma_f32_16x16x32_bf16 v[34:37], v[126:129], v[150:153], v[34:37]
	v_mfma_f32_16x16x32_bf16 v[18:21], v[134:137], v[150:153], v[18:21]
	v_mfma_f32_16x16x32_bf16 v[30:33], v[126:129], v[158:161], v[30:33]
	v_mfma_f32_16x16x32_bf16 v[2:5], v[134:137], v[158:161], v[2:5]
	v_mfma_f32_16x16x32_bf16 v[26:29], v[126:129], v[170:173], v[26:29]
	v_mfma_f32_16x16x32_bf16 v[6:9], v[134:137], v[170:173], v[6:9]
	s_setprio 0
	s_barrier
	s_add_i32 s70, s70, 2
	s_add_u32 s68, s68, 0x100
	s_addc_u32 s69, s69, 0
	s_cmp_gt_u32 s70, 61
	s_mov_b64 s[6:7], s[42:43]
	s_cbranch_scc0 .LBB0_1001
	s_and_b64 vcc, exec, s[2:3]
	s_cbranch_vccz .LBB0_1004
	s_barrier

; #define PG8_STAGE(bufoff, gbase, voff) do { _Pragma("unroll") for (int _i = 0; _i < 2; ++_i) \
;         __builtin_amdgcn_global_load_lds((const unsigned*)((const char*)(gbase) + (voff)[_i]), (LAS unsigned*)(lds + (bufoff) + ldsw + _i * 8192), 16, 0, 0); } while (0)
; #define PG8_LDA(dst, b, h) do { _Pragma("unroll") for (int m = 0; m < 4; ++m) _Pragma("unroll") for (int k = 0; k < 2; ++k) dst[m][k] = *(const LAS bf16x8*)(lds + PG8_SA(b, h) + aoff + m * 2048 + k * 1024); } while (0)
; #define PG8_LDB(dst, b, h) do { _Pragma("unroll") for (int n = 0; n < 2; ++n) _Pragma("unroll") for (int k = 0; k < 2; ++k) dst[n][k] = *(const LAS bf16x8*)(lds + PG8_SB(b, h) + boff + n * 2048 + k * 1024); } while (0)
; #define PG8_MMA(ai, bj, At, Bt) do { __builtin_amdgcn_s_setprio(1); _Pragma("unroll") for (int m = 0; m < 4; ++m) _Pragma("unroll") for (int n = 0; n < 2; ++n) _Pragma("unroll") for (int k = 0; k < 2; ++k) \
;         acc[ai][bj][m][n] = __builtin_amdgcn_mfma_f32_16x16x32_bf16(Bt[n][k], At[m][k], acc[ai][bj][m][n], 0, 0, 0); __builtin_amdgcn_s_setprio(0); } while (0)
; #define PG8_WAIT_V(n) asm volatile("s_waitcnt vmcnt(" #n ")" ::: "memory")
; #define PG8_WAIT_L(n) asm volatile("s_waitcnt lgkmcnt(" #n ")" ::: "memory")
; #define PG8_BAR __builtin_amdgcn_s_barrier()
; template <class Epi, class Sched, bool ALIGN_EPI, class Hook = NoHook>
; __device__ __forceinline__ void gemm_phase(LAS unsigned char* lds, const Gemm g, const Sched& S, const Epi& E, const Hook& H = Hook()) {
;     ...
;             const bool last = (t == nt - 2);
;             const char* a1 = cA + (size_t)(t + 1) * kstep;
;             const char* a2 = last ? nA : cA + (size_t)(t + 2) * kstep; const char* b2 = last ? nB : cB + (size_t)(t + 2) * kstep;
;             const char* a3 = a2 + kstep; const char* b3 = b2 + kstep;
;             if (last && has_next) S.a_ready(nxt);
;             PG8_LDB(B0, 0, 0); PG8_LDB(B1, 0, 1); PG8_SCHED; PG8_LDA(At, 0, 0); PG8_STAGE(PG8_SA(1, 1), a1 + hA, voffA);
;             PG8_WAIT_V(8); PG8_WAIT_L(0); PG8_BAR; PG8_MMA(0, 0, At, B0); PG8_MMA(0, 1, At, B1); PG8_BAR; PG8_SCHED;
;             PG8_LDA(At, 0, 1); PG8_STAGE(PG8_SB(0, 0), b2, voffB); PG8_STAGE(PG8_SB(0, 1), b2 + hB, voffB); PG8_STAGE(PG8_SA(0, 0), a2, voffA);
;             PG8_WAIT_V(8); PG8_WAIT_L(0); PG8_BAR; PG8_MMA(1, 0, At, B0); PG8_MMA(1, 1, At, B1); PG8_BAR; PG8_SCHED;
.LBB0_1360:
	ds_read_b128 v[146:149], v1
	ds_read_b128 v[150:153], v1 offset:1024
	ds_read_b128 v[154:157], v1 offset:2048
	ds_read_b128 v[158:161], v1 offset:3072
	ds_read_b128 v[164:167], v142
	ds_read_b128 v[170:173], v142 offset:1024
	ds_read_b128 v[174:177], v142 offset:2048
	ds_read_b128 v[178:181], v142 offset:3072
	s_add_u32 s14, s4, 0xbb050080
	s_addc_u32 s15, s5, -1
	s_cmpk_lg_i32 s41, 0xa8
	s_cselect_b32 s14, s14, 0
	s_cselect_b32 s15, s15, 0
	s_add_u32 s20, s0, s14
	s_addc_u32 s21, s1, s15
	s_add_u32 s14, s12, s14
	s_addc_u32 s15, s13, s15
	s_mov_b32 m0, s42
	v_lshl_add_u64 v[214:215], v[138:139], 0, s[4:5]
	ds_read_b128 v[182:185], v143
	ds_read_b128 v[186:189], v143 offset:1024
	ds_read_b128 v[190:193], v143 offset:2048
	ds_read_b128 v[194:197], v143 offset:3072
	ds_read_b128 v[198:201], v143 offset:4096
	ds_read_b128 v[202:205], v143 offset:5120
	ds_read_b128 v[206:209], v143 offset:6144
	ds_read_b128 v[210:213], v143 offset:7168
	global_load_lds_dwordx4 v[214:215], off
	v_lshl_add_u64 v[214:215], v[140:141], 0, s[4:5]
	s_mov_b32 m0, s43
	s_nop 0
	global_load_lds_dwordx4 v[214:215], off
	s_waitcnt vmcnt(8)
	s_waitcnt lgkmcnt(0)
	s_barrier
	s_setprio 1
	s_waitcnt lgkmcnt(0)
	v_mfma_f32_16x16x32_bf16 v[82:85], v[146:149], v[182:185], v[82:85]
	v_mfma_f32_16x16x32_bf16 v[54:57], v[154:157], v[182:185], v[54:57]
	v_mfma_f32_16x16x32_bf16 v[58:61], v[146:149], v[190:193], v[58:61]
	v_mfma_f32_16x16x32_bf16 v[42:45], v[154:157], v[190:193], v[42:45]
	v_mfma_f32_16x16x32_bf16 v[70:73], v[146:149], v[198:201], v[70:73]
	v_mfma_f32_16x16x32_bf16 v[50:53], v[154:157], v[198:201], v[50:53]
	v_mfma_f32_16x16x32_bf16 v[86:89], v[146:149], v[206:209], v[86:89]
	v_mfma_f32_16x16x32_bf16 v[74:77], v[154:157], v[206:209], v[74:77]
	v_mfma_f32_16x16x32_bf16 v[82:85], v[150:153], v[186:189], v[82:85]
	v_mfma_f32_16x16x32_bf16 v[54:57], v[158:161], v[186:189], v[54:57]
	v_mfma_f32_16x16x32_bf16 v[58:61], v[150:153], v[194:197], v[58:61]
	v_mfma_f32_16x16x32_bf16 v[42:45], v[158:161], v[194:197], v[42:45]
	v_mfma_f32_16x16x32_bf16 v[70:73], v[150:153], v[202:205], v[70:73]
	v_mfma_f32_16x16x32_bf16 v[50:53], v[158:161], v[202:205], v[50:53]
	v_mfma_f32_16x16x32_bf16 v[86:89], v[150:153], v[210:213], v[86:89]
	v_mfma_f32_16x16x32_bf16 v[74:77], v[158:161], v[210:213], v[74:77]
	s_setprio 0
	s_setprio 1
	v_mfma_f32_16x16x32_bf16 v[14:17], v[164:167], v[182:185], v[14:17]
	v_mfma_f32_16x16x32_bf16 v[2:5], v[174:177], v[182:185], v[2:5]
	v_mfma_f32_16x16x32_bf16 v[18:21], v[164:167], v[190:193], v[18:21]
	v_mfma_f32_16x16x32_bf16 v[6:9], v[174:177], v[190:193], v[6:9]
	v_mfma_f32_16x16x32_bf16 v[22:25], v[164:167], v[198:201], v[22:25]
	v_mfma_f32_16x16x32_bf16 v[10:13], v[174:177], v[198:201], v[10:13]
	v_mfma_f32_16x16x32_bf16 v[30:33], v[164:167], v[206:209], v[30:33]
	v_mfma_f32_16x16x32_bf16 v[26:29], v[174:177], v[206:209], v[26:29]
	v_mfma_f32_16x16x32_bf16 v[14:17], v[170:173], v[186:189], v[14:17]
	v_mfma_f32_16x16x32_bf16 v[2:5], v[178:181], v[186:189], v[2:5]
	v_mfma_f32_16x16x32_bf16 v[18:21], v[170:173], v[194:197], v[18:21]
	v_mfma_f32_16x16x32_bf16 v[6:9], v[178:181], v[194:197], v[6:9]
	v_mfma_f32_16x16x32_bf16 v[22:25], v[170:173], v[202:205], v[22:25]
	v_mfma_f32_16x16x32_bf16 v[10:13], v[178:181], v[202:205], v[10:13]
	v_mfma_f32_16x16x32_bf16 v[30:33], v[170:173], v[210:213], v[30:33]
	v_mfma_f32_16x16x32_bf16 v[26:29], v[178:181], v[210:213], v[26:29]
	s_setprio 0
	s_barrier
	s_mov_b32 m0, s44
	s_add_u32 s52, s14, 0x2b0000
	ds_read_b128 v[182:185], v143 offset:16384
	ds_read_b128 v[186:189], v143 offset:17408
	ds_read_b128 v[190:193], v143 offset:18432
	ds_read_b128 v[194:197], v143 offset:19456
	ds_read_b128 v[198:201], v143 offset:20480
	ds_read_b128 v[202:205], v143 offset:21504
	ds_read_b128 v[206:209], v143 offset:22528
	ds_read_b128 v[210:213], v143 offset:23552
	global_load_lds_dwordx4 v132, s[14:15]
	s_mov_b32 m0, s45
	s_addc_u32 s53, s15, 0
	global_load_lds_dwordx4 v136, s[14:15]
	s_mov_b32 m0, s46
	v_lshl_add_u64 v[220:221], s[20:21], 0, v[134:135]
	global_load_lds_dwordx4 v132, s[52:53]
	s_mov_b32 m0, s47
	s_nop 0
	global_load_lds_dwordx4 v136, s[52:53]
	v_lshl_add_u64 v[218:219], s[20:21], 0, v[130:131]
	s_mov_b32 m0, s25
	s_nop 0
	global_load_lds_dwordx4 v130, s[20:21]
	s_mov_b32 m0, s27
	s_nop 0
	global_load_lds_dwordx4 v134, s[20:21]
	s_waitcnt vmcnt(8)
	s_waitcnt lgkmcnt(0)
	s_barrier
	s_setprio 1
	s_waitcnt lgkmcnt(0)
	v_mfma_f32_16x16x32_bf16 v[94:97], v[146:149], v[182:185], v[94:97]
	v_mfma_f32_16x16x32_bf16 v[90:93], v[154:157], v[182:185], v[90:93]
	v_mfma_f32_16x16x32_bf16 v[106:109], v[146:149], v[190:193], v[106:109]
	v_mfma_f32_16x16x32_bf16 v[98:101], v[154:157], v[190:193], v[98:101]
	v_mfma_f32_16x16x32_bf16 v[110:113], v[146:149], v[198:201], v[110:113]
	v_mfma_f32_16x16x32_bf16 v[102:105], v[154:157], v[198:201], v[102:105]
	v_mfma_f32_16x16x32_bf16 v[126:129], v[146:149], v[206:209], v[126:129]
	v_mfma_f32_16x16x32_bf16 v[122:125], v[154:157], v[206:209], v[122:125]
	v_mfma_f32_16x16x32_bf16 v[94:97], v[150:153], v[186:189], v[94:97]
	v_mfma_f32_16x16x32_bf16 v[90:93], v[158:161], v[186:189], v[90:93]
	v_mfma_f32_16x16x32_bf16 v[106:109], v[150:153], v[194:197], v[106:109]
	v_mfma_f32_16x16x32_bf16 v[98:101], v[158:161], v[194:197], v[98:101]
	v_mfma_f32_16x16x32_bf16 v[110:113], v[150:153], v[202:205], v[110:113]
	v_mfma_f32_16x16x32_bf16 v[102:105], v[158:161], v[202:205], v[102:105]
	v_mfma_f32_16x16x32_bf16 v[126:129], v[150:153], v[210:213], v[126:129]
	v_mfma_f32_16x16x32_bf16 v[122:125], v[158:161], v[210:213], v[122:125]
	s_setprio 0
	s_setprio 1
	v_mfma_f32_16x16x32_bf16 v[38:41], v[164:167], v[182:185], v[38:41]
	v_mfma_f32_16x16x32_bf16 v[34:37], v[174:177], v[182:185], v[34:37]
	v_mfma_f32_16x16x32_bf16 v[66:69], v[164:167], v[190:193], v[66:69]
	v_mfma_f32_16x16x32_bf16 v[46:49], v[174:177], v[190:193], v[46:49]
	v_mfma_f32_16x16x32_bf16 v[78:81], v[164:167], v[198:201], v[78:81]
	v_mfma_f32_16x16x32_bf16 v[62:65], v[174:177], v[198:201], v[62:65]
	v_mfma_f32_16x16x32_bf16 v[118:121], v[164:167], v[206:209], v[118:121]
	v_mfma_f32_16x16x32_bf16 v[114:117], v[174:177], v[206:209], v[114:117]
	v_mfma_f32_16x16x32_bf16 v[38:41], v[170:173], v[186:189], v[38:41]
	v_mfma_f32_16x16x32_bf16 v[34:37], v[178:181], v[186:189], v[34:37]
	v_mfma_f32_16x16x32_bf16 v[66:69], v[170:173], v[194:197], v[66:69]
	v_mfma_f32_16x16x32_bf16 v[46:49], v[178:181], v[194:197], v[46:49]
	v_mfma_f32_16x16x32_bf16 v[78:81], v[170:173], v[202:205], v[78:81]
	v_mfma_f32_16x16x32_bf16 v[62:65], v[178:181], v[202:205], v[62:65]
	v_mfma_f32_16x16x32_bf16 v[118:121], v[170:173], v[210:213], v[118:121]
	v_mfma_f32_16x16x32_bf16 v[114:117], v[178:181], v[210:213], v[114:117]
	s_setprio 0
	s_barrier
; #define PG8_STAGE(bufoff, gbase, voff) do { _Pragma("unroll") for (int _i = 0; _i < 2; ++_i) \
;         __builtin_amdgcn_global_load_lds((const unsigned*)((const char*)(gbase) + (voff)[_i]), (LAS unsigned*)(lds + (bufoff) + ldsw + _i * 8192), 16, 0, 0); } while (0)
; #define PG8_LDA(dst, b, h) do { _Pragma("unroll") for (int m = 0; m < 4; ++m) _Pragma("unroll") for (int k = 0; k < 2; ++k) dst[m][k] = *(const LAS bf16x8*)(lds + PG8_SA(b, h) + aoff + m * 2048 + k * 1024); } while (0)
; #define PG8_LDB(dst, b, h) do { _Pragma("unroll") for (int n = 0; n < 2; ++n) _Pragma("unroll") for (int k = 0; k < 2; ++k) dst[n][k] = *(const LAS bf16x8*)(lds + PG8_SB(b, h) + boff + n * 2048 + k * 1024); } while (0)
; #define PG8_MMA(ai, bj, At, Bt) do { __builtin_amdgcn_s_setprio(1); _Pragma("unroll") for (int m = 0; m < 4; ++m) _Pragma("unroll") for (int n = 0; n < 2; ++n) _Pragma("unroll") for (int k = 0; k < 2; ++k) \
;         acc[ai][bj][m][n] = __builtin_amdgcn_mfma_f32_16x16x32_bf16(Bt[n][k], At[m][k], acc[ai][bj][m][n], 0, 0, 0); __builtin_amdgcn_s_setprio(0); } while (0)
; #define PG8_WAIT_V(n) asm volatile("s_waitcnt vmcnt(" #n ")" ::: "memory")
; #define PG8_WAIT_L(n) asm volatile("s_waitcnt lgkmcnt(" #n ")" ::: "memory")
; #define PG8_BAR __builtin_amdgcn_s_barrier()
; #define PG8_SCHED __builtin_amdgcn_sched_barrier(0)
; template <class Epi, class Sched, bool ALIGN_EPI, class Hook = NoHook>
; __device__ __forceinline__ void gemm_phase(LAS unsigned char* lds, const Gemm g, const Sched& S, const Epi& E, const Hook& H = Hook()) {
;     ...
;             PG8_LDB(B0, 1, 0); PG8_LDB(B1, 1, 1); PG8_SCHED; PG8_LDA(At, 1, 0); PG8_STAGE(PG8_SA(0, 1), a2 + hA, voffA);
;             PG8_WAIT_V(8); PG8_WAIT_L(0); PG8_BAR; PG8_MMA(0, 0, At, B0); PG8_MMA(0, 1, At, B1); PG8_BAR; PG8_SCHED;
;             PG8_LDA(At, 1, 1); PG8_STAGE(PG8_SB(1, 0), b3, voffB); PG8_STAGE(PG8_SB(1, 1), b3 + hB, voffB); PG8_STAGE(PG8_SA(1, 0), a3, voffA);
;             PG8_WAIT_V(8); PG8_WAIT_L(0); PG8_BAR; PG8_MMA(1, 0, At, B0); PG8_MMA(1, 1, At, B1); PG8_BAR; PG8_SCHED;
;         }
;         if constexpr (Hook::ON) H.after(te, acc, cur, wr, wc, fr, fq);
;         }
;         if constexpr (ALIGN_EPI) { if (wr == 0) PG8_BAR; }
	ds_read_b128 v[146:149], v144
	ds_read_b128 v[150:153], v144 offset:1024
	ds_read_b128 v[154:157], v144 offset:2048
	ds_read_b128 v[158:161], v144 offset:3072
	ds_read_b128 v[164:167], v145
	ds_read_b128 v[170:173], v145 offset:1024
	ds_read_b128 v[174:177], v145 offset:2048
	ds_read_b128 v[178:181], v145 offset:3072
	s_add_u32 s20, s20, 0x2b0000
	s_addc_u32 s21, s21, 0
	s_mov_b32 m0, s28
	ds_read_b128 v[182:185], v143 offset:32768
	ds_read_b128 v[186:189], v143 offset:33792
	ds_read_b128 v[190:193], v143 offset:34816
	ds_read_b128 v[194:197], v143 offset:35840
	ds_read_b128 v[198:201], v143 offset:36864
	ds_read_b128 v[202:205], v143 offset:37888
	ds_read_b128 v[206:209], v143 offset:38912
	ds_read_b128 v[210:213], v143 offset:39936
	global_load_lds_dwordx4 v130, s[20:21]
	s_mov_b32 m0, s38
	s_nop 0
	global_load_lds_dwordx4 v134, s[20:21]
	s_waitcnt vmcnt(8)
	s_waitcnt lgkmcnt(0)
	s_barrier
	s_setprio 1
	s_waitcnt lgkmcnt(0)
	v_mfma_f32_16x16x32_bf16 v[82:85], v[146:149], v[182:185], v[82:85]
	v_mfma_f32_16x16x32_bf16 v[54:57], v[154:157], v[182:185], v[54:57]
	v_mfma_f32_16x16x32_bf16 v[58:61], v[146:149], v[190:193], v[58:61]
	v_mfma_f32_16x16x32_bf16 v[42:45], v[154:157], v[190:193], v[42:45]
	v_mfma_f32_16x16x32_bf16 v[70:73], v[146:149], v[198:201], v[70:73]
	v_mfma_f32_16x16x32_bf16 v[50:53], v[154:157], v[198:201], v[50:53]
	v_mfma_f32_16x16x32_bf16 v[86:89], v[146:149], v[206:209], v[86:89]
	v_mfma_f32_16x16x32_bf16 v[74:77], v[154:157], v[206:209], v[74:77]
	v_mfma_f32_16x16x32_bf16 v[82:85], v[150:153], v[186:189], v[82:85]
	v_mfma_f32_16x16x32_bf16 v[54:57], v[158:161], v[186:189], v[54:57]
	v_mfma_f32_16x16x32_bf16 v[58:61], v[150:153], v[194:197], v[58:61]
	v_mfma_f32_16x16x32_bf16 v[42:45], v[158:161], v[194:197], v[42:45]
	v_mfma_f32_16x16x32_bf16 v[70:73], v[150:153], v[202:205], v[70:73]
	v_mfma_f32_16x16x32_bf16 v[50:53], v[158:161], v[202:205], v[50:53]
	v_mfma_f32_16x16x32_bf16 v[86:89], v[150:153], v[210:213], v[86:89]
	v_mfma_f32_16x16x32_bf16 v[74:77], v[158:161], v[210:213], v[74:77]
	s_setprio 0
	s_setprio 1
	v_mfma_f32_16x16x32_bf16 v[14:17], v[164:167], v[182:185], v[14:17]
	v_mfma_f32_16x16x32_bf16 v[2:5], v[174:177], v[182:185], v[2:5]
	v_mfma_f32_16x16x32_bf16 v[18:21], v[164:167], v[190:193], v[18:21]
	v_mfma_f32_16x16x32_bf16 v[6:9], v[174:177], v[190:193], v[6:9]
	v_mfma_f32_16x16x32_bf16 v[22:25], v[164:167], v[198:201], v[22:25]
	v_mfma_f32_16x16x32_bf16 v[10:13], v[174:177], v[198:201], v[10:13]
	v_mfma_f32_16x16x32_bf16 v[30:33], v[164:167], v[206:209], v[30:33]
	v_mfma_f32_16x16x32_bf16 v[26:29], v[174:177], v[206:209], v[26:29]
	v_mfma_f32_16x16x32_bf16 v[14:17], v[170:173], v[186:189], v[14:17]
	v_mfma_f32_16x16x32_bf16 v[2:5], v[178:181], v[186:189], v[2:5]
	v_mfma_f32_16x16x32_bf16 v[18:21], v[170:173], v[194:197], v[18:21]
	v_mfma_f32_16x16x32_bf16 v[6:9], v[178:181], v[194:197], v[6:9]
	v_mfma_f32_16x16x32_bf16 v[22:25], v[170:173], v[202:205], v[22:25]
	v_mfma_f32_16x16x32_bf16 v[10:13], v[178:181], v[202:205], v[10:13]
	v_mfma_f32_16x16x32_bf16 v[30:33], v[170:173], v[210:213], v[30:33]
	v_mfma_f32_16x16x32_bf16 v[26:29], v[178:181], v[210:213], v[26:29]
	s_setprio 0
	s_barrier
	s_mov_b32 m0, s48
	s_add_u32 s54, s14, s2
	s_addc_u32 s55, s15, s3
	s_add_u32 s14, s14, 0x2b0080
	ds_read_b128 v[182:185], v143 offset:49152
	ds_read_b128 v[186:189], v143 offset:50176
	ds_read_b128 v[190:193], v143 offset:51200
	ds_read_b128 v[194:197], v143 offset:52224
	ds_read_b128 v[198:201], v143 offset:53248
	ds_read_b128 v[202:205], v143 offset:54272
	ds_read_b128 v[206:209], v143 offset:55296
	ds_read_b128 v[210:213], v143 offset:56320
	global_load_lds_dwordx4 v132, s[54:55]
	s_mov_b32 m0, s49
	s_addc_u32 s15, s15, 0
	global_load_lds_dwordx4 v136, s[54:55]
	s_mov_b32 m0, s50
	s_nop 0
	global_load_lds_dwordx4 v132, s[14:15]
	s_mov_b32 m0, s51
	s_nop 0
	global_load_lds_dwordx4 v136, s[14:15]
	v_lshl_add_u64 v[214:215], v[218:219], 0, s[2:3]
	s_mov_b32 m0, s39
	s_nop 0
	global_load_lds_dwordx4 v[214:215], off
	v_lshl_add_u64 v[214:215], v[220:221], 0, s[2:3]
	s_mov_b32 m0, s40
	s_nop 0
	global_load_lds_dwordx4 v[214:215], off
	s_waitcnt vmcnt(8)
	s_waitcnt lgkmcnt(0)
	s_barrier
	s_setprio 1
	s_waitcnt lgkmcnt(0)
	v_mfma_f32_16x16x32_bf16 v[94:97], v[146:149], v[182:185], v[94:97]
	v_mfma_f32_16x16x32_bf16 v[90:93], v[154:157], v[182:185], v[90:93]
	v_mfma_f32_16x16x32_bf16 v[106:109], v[146:149], v[190:193], v[106:109]
	v_mfma_f32_16x16x32_bf16 v[98:101], v[154:157], v[190:193], v[98:101]
	v_mfma_f32_16x16x32_bf16 v[110:113], v[146:149], v[198:201], v[110:113]
	v_mfma_f32_16x16x32_bf16 v[102:105], v[154:157], v[198:201], v[102:105]
	v_mfma_f32_16x16x32_bf16 v[126:129], v[146:149], v[206:209], v[126:129]
	v_mfma_f32_16x16x32_bf16 v[122:125], v[154:157], v[206:209], v[122:125]
	v_mfma_f32_16x16x32_bf16 v[94:97], v[150:153], v[186:189], v[94:97]
	v_mfma_f32_16x16x32_bf16 v[90:93], v[158:161], v[186:189], v[90:93]
	v_mfma_f32_16x16x32_bf16 v[106:109], v[150:153], v[194:197], v[106:109]
	v_mfma_f32_16x16x32_bf16 v[98:101], v[158:161], v[194:197], v[98:101]
	v_mfma_f32_16x16x32_bf16 v[110:113], v[150:153], v[202:205], v[110:113]
	v_mfma_f32_16x16x32_bf16 v[102:105], v[158:161], v[202:205], v[102:105]
	v_mfma_f32_16x16x32_bf16 v[126:129], v[150:153], v[210:213], v[126:129]
	v_mfma_f32_16x16x32_bf16 v[122:125], v[158:161], v[210:213], v[122:125]
	s_setprio 0
	s_setprio 1
	v_mfma_f32_16x16x32_bf16 v[38:41], v[164:167], v[182:185], v[38:41]
	v_mfma_f32_16x16x32_bf16 v[34:37], v[174:177], v[182:185], v[34:37]
	v_mfma_f32_16x16x32_bf16 v[66:69], v[164:167], v[190:193], v[66:69]
	v_mfma_f32_16x16x32_bf16 v[46:49], v[174:177], v[190:193], v[46:49]
	v_mfma_f32_16x16x32_bf16 v[78:81], v[164:167], v[198:201], v[78:81]
	v_mfma_f32_16x16x32_bf16 v[62:65], v[174:177], v[198:201], v[62:65]
	v_mfma_f32_16x16x32_bf16 v[118:121], v[164:167], v[206:209], v[118:121]
	v_mfma_f32_16x16x32_bf16 v[114:117], v[174:177], v[206:209], v[114:117]
	v_mfma_f32_16x16x32_bf16 v[38:41], v[170:173], v[186:189], v[38:41]
	v_mfma_f32_16x16x32_bf16 v[34:37], v[178:181], v[186:189], v[34:37]
	v_mfma_f32_16x16x32_bf16 v[66:69], v[170:173], v[194:197], v[66:69]
	v_mfma_f32_16x16x32_bf16 v[46:49], v[178:181], v[194:197], v[46:49]
	v_mfma_f32_16x16x32_bf16 v[78:81], v[170:173], v[202:205], v[78:81]
	v_mfma_f32_16x16x32_bf16 v[62:65], v[178:181], v[202:205], v[62:65]
	v_mfma_f32_16x16x32_bf16 v[118:121], v[170:173], v[210:213], v[118:121]
	v_mfma_f32_16x16x32_bf16 v[114:117], v[178:181], v[210:213], v[114:117]
	s_setprio 0
	s_barrier
	s_add_i32 s41, s41, 2
	s_add_u32 s4, s4, 0x100
	s_addc_u32 s5, s5, 0
	s_cmpk_gt_u32 s41, 0xa9
	s_cbranch_scc0 .LBB0_1360
	s_cmpk_lt_u32 s26, 0x100
	s_cbranch_scc0 .LBB0_1363
	s_barrier

; #define PG8_STAGE(bufoff, gbase, voff) do { _Pragma("unroll") for (int _i = 0; _i < 2; ++_i) \
;         __builtin_amdgcn_global_load_lds((const unsigned*)((const char*)(gbase) + (voff)[_i]), (LAS unsigned*)(lds + (bufoff) + ldsw + _i * 8192), 16, 0, 0); } while (0)
; #define PG8_LDA(dst, b, h) do { _Pragma("unroll") for (int m = 0; m < 4; ++m) _Pragma("unroll") for (int k = 0; k < 2; ++k) dst[m][k] = *(const LAS bf16x8*)(lds + PG8_SA(b, h) + aoff + m * 2048 + k * 1024); } while (0)
; #define PG8_LDB(dst, b, h) do { _Pragma("unroll") for (int n = 0; n < 2; ++n) _Pragma("unroll") for (int k = 0; k < 2; ++k) dst[n][k] = *(const LAS bf16x8*)(lds + PG8_SB(b, h) + boff + n * 2048 + k * 1024); } while (0)
; #define PG8_MMA(ai, bj, At, Bt) do { __builtin_amdgcn_s_setprio(1); _Pragma("unroll") for (int m = 0; m < 4; ++m) _Pragma("unroll") for (int n = 0; n < 2; ++n) _Pragma("unroll") for (int k = 0; k < 2; ++k) \
;         acc[ai][bj][m][n] = __builtin_amdgcn_mfma_f32_16x16x32_bf16(Bt[n][k], At[m][k], acc[ai][bj][m][n], 0, 0, 0); __builtin_amdgcn_s_setprio(0); } while (0)
; #define PG8_WAIT_V(n) asm volatile("s_waitcnt vmcnt(" #n ")" ::: "memory")
; #define PG8_WAIT_L(n) asm volatile("s_waitcnt lgkmcnt(" #n ")" ::: "memory")
; #define PG8_BAR __builtin_amdgcn_s_barrier()
; template <class Epi, class Sched, bool ALIGN_EPI, class Hook = NoHook>
; __device__ __forceinline__ void gemm_phase(LAS unsigned char* lds, const Gemm g, const Sched& S, const Epi& E, const Hook& H = Hook()) {
;     ...
;             const bool last = (t == nt - 2);
;             const char* a1 = cA + (size_t)(t + 1) * kstep;
;             const char* a2 = last ? nA : cA + (size_t)(t + 2) * kstep; const char* b2 = last ? nB : cB + (size_t)(t + 2) * kstep;
;             const char* a3 = a2 + kstep; const char* b3 = b2 + kstep;
;             if (last && has_next) S.a_ready(nxt);
;             PG8_LDB(B0, 0, 0); PG8_LDB(B1, 0, 1); PG8_SCHED; PG8_LDA(At, 0, 0); PG8_STAGE(PG8_SA(1, 1), a1 + hA, voffA);
;             PG8_WAIT_V(8); PG8_WAIT_L(0); PG8_BAR; PG8_MMA(0, 0, At, B0); PG8_MMA(0, 1, At, B1); PG8_BAR; PG8_SCHED;
;             PG8_LDA(At, 0, 1); PG8_STAGE(PG8_SB(0, 0), b2, voffB); PG8_STAGE(PG8_SB(0, 1), b2 + hB, voffB); PG8_STAGE(PG8_SA(0, 0), a2, voffA);
;             PG8_WAIT_V(8); PG8_WAIT_L(0); PG8_BAR; PG8_MMA(1, 0, At, B0); PG8_MMA(1, 1, At, B1); PG8_BAR; PG8_SCHED;
.LBB0_1406:
	ds_read_b128 v[146:149], v140
	ds_read_b128 v[150:153], v140 offset:1024
	ds_read_b128 v[154:157], v140 offset:2048
	ds_read_b128 v[158:161], v140 offset:3072
	ds_read_b128 v[170:173], v141
	ds_read_b128 v[174:177], v141 offset:1024
	ds_read_b128 v[178:181], v141 offset:2048
	ds_read_b128 v[182:185], v141 offset:3072
	s_add_u32 s10, s4, 0xbb050080
	s_addc_u32 s11, s5, -1
	s_cmpk_lg_i32 s18, 0xa8
	s_cselect_b32 s10, s10, 0
	s_cselect_b32 s11, s11, 0
	s_add_u32 s16, s0, s10
	s_addc_u32 s17, s1, s11
	s_add_u32 s10, s12, s10
	s_addc_u32 s11, s13, s11
	s_mov_b32 m0, s19
	v_lshl_add_u64 v[218:219], v[136:137], 0, s[4:5]
	ds_read_b128 v[186:189], v142
	ds_read_b128 v[190:193], v142 offset:1024
	ds_read_b128 v[194:197], v142 offset:2048
	ds_read_b128 v[198:201], v142 offset:3072
	ds_read_b128 v[202:205], v142 offset:4096
	ds_read_b128 v[206:209], v142 offset:5120
	ds_read_b128 v[210:213], v142 offset:6144
	ds_read_b128 v[214:217], v142 offset:7168
	global_load_lds_dwordx4 v[218:219], off
	v_lshl_add_u64 v[218:219], v[138:139], 0, s[4:5]
	s_mov_b32 m0, s31
	s_nop 0
	global_load_lds_dwordx4 v[218:219], off
	s_waitcnt vmcnt(8)
	s_waitcnt lgkmcnt(0)
	s_barrier
	s_setprio 1
	s_waitcnt lgkmcnt(0)
	v_mfma_f32_16x16x32_bf16 v[82:85], v[146:149], v[186:189], v[82:85]
	v_mfma_f32_16x16x32_bf16 v[54:57], v[154:157], v[186:189], v[54:57]
	v_mfma_f32_16x16x32_bf16 v[58:61], v[146:149], v[194:197], v[58:61]
	v_mfma_f32_16x16x32_bf16 v[42:45], v[154:157], v[194:197], v[42:45]
	v_mfma_f32_16x16x32_bf16 v[70:73], v[146:149], v[202:205], v[70:73]
	v_mfma_f32_16x16x32_bf16 v[50:53], v[154:157], v[202:205], v[50:53]
	v_mfma_f32_16x16x32_bf16 v[86:89], v[146:149], v[210:213], v[86:89]
	v_mfma_f32_16x16x32_bf16 v[74:77], v[154:157], v[210:213], v[74:77]
	v_mfma_f32_16x16x32_bf16 v[82:85], v[150:153], v[190:193], v[82:85]
	v_mfma_f32_16x16x32_bf16 v[54:57], v[158:161], v[190:193], v[54:57]
	v_mfma_f32_16x16x32_bf16 v[58:61], v[150:153], v[198:201], v[58:61]
	v_mfma_f32_16x16x32_bf16 v[42:45], v[158:161], v[198:201], v[42:45]
	v_mfma_f32_16x16x32_bf16 v[70:73], v[150:153], v[206:209], v[70:73]
	v_mfma_f32_16x16x32_bf16 v[50:53], v[158:161], v[206:209], v[50:53]
	v_mfma_f32_16x16x32_bf16 v[86:89], v[150:153], v[214:217], v[86:89]
	v_mfma_f32_16x16x32_bf16 v[74:77], v[158:161], v[214:217], v[74:77]
	s_setprio 0
	s_setprio 1
	v_mfma_f32_16x16x32_bf16 v[14:17], v[170:173], v[186:189], v[14:17]
	v_mfma_f32_16x16x32_bf16 v[2:5], v[178:181], v[186:189], v[2:5]
	v_mfma_f32_16x16x32_bf16 v[18:21], v[170:173], v[194:197], v[18:21]
	v_mfma_f32_16x16x32_bf16 v[6:9], v[178:181], v[194:197], v[6:9]
	v_mfma_f32_16x16x32_bf16 v[22:25], v[170:173], v[202:205], v[22:25]
	v_mfma_f32_16x16x32_bf16 v[10:13], v[178:181], v[202:205], v[10:13]
	v_mfma_f32_16x16x32_bf16 v[30:33], v[170:173], v[210:213], v[30:33]
	v_mfma_f32_16x16x32_bf16 v[26:29], v[178:181], v[210:213], v[26:29]
	v_mfma_f32_16x16x32_bf16 v[14:17], v[174:177], v[190:193], v[14:17]
	v_mfma_f32_16x16x32_bf16 v[2:5], v[182:185], v[190:193], v[2:5]
	v_mfma_f32_16x16x32_bf16 v[18:21], v[174:177], v[198:201], v[18:21]
	v_mfma_f32_16x16x32_bf16 v[6:9], v[182:185], v[198:201], v[6:9]
	v_mfma_f32_16x16x32_bf16 v[22:25], v[174:177], v[206:209], v[22:25]
	v_mfma_f32_16x16x32_bf16 v[10:13], v[182:185], v[206:209], v[10:13]
	v_mfma_f32_16x16x32_bf16 v[30:33], v[174:177], v[214:217], v[30:33]
	v_mfma_f32_16x16x32_bf16 v[26:29], v[182:185], v[214:217], v[26:29]
	s_setprio 0
	s_barrier
	s_mov_b32 m0, s33
	s_add_u32 s46, s10, 0x2b0000
	ds_read_b128 v[186:189], v142 offset:16384
	ds_read_b128 v[190:193], v142 offset:17408
	ds_read_b128 v[194:197], v142 offset:18432
	ds_read_b128 v[198:201], v142 offset:19456
	ds_read_b128 v[202:205], v142 offset:20480
	ds_read_b128 v[206:209], v142 offset:21504
	ds_read_b128 v[210:213], v142 offset:22528
	ds_read_b128 v[214:217], v142 offset:23552
	global_load_lds_dwordx4 v162, s[10:11]
	s_mov_b32 m0, s34
	s_addc_u32 s47, s11, 0
	global_load_lds_dwordx4 v134, s[10:11]
	s_mov_b32 m0, s35
	v_lshl_add_u64 v[224:225], s[16:17], 0, v[132:133]
	global_load_lds_dwordx4 v162, s[46:47]
	s_mov_b32 m0, s43
	s_nop 0
	global_load_lds_dwordx4 v134, s[46:47]
	v_lshl_add_u64 v[222:223], s[16:17], 0, v[130:131]
	s_mov_b32 m0, s27
	s_nop 0
	global_load_lds_dwordx4 v130, s[16:17]
	s_mov_b32 m0, s28
	s_nop 0
	global_load_lds_dwordx4 v132, s[16:17]
	s_waitcnt vmcnt(8)
	s_waitcnt lgkmcnt(0)
	s_barrier
	s_setprio 1
	s_waitcnt lgkmcnt(0)
	v_mfma_f32_16x16x32_bf16 v[94:97], v[146:149], v[186:189], v[94:97]
	v_mfma_f32_16x16x32_bf16 v[90:93], v[154:157], v[186:189], v[90:93]
	v_mfma_f32_16x16x32_bf16 v[118:121], v[146:149], v[194:197], v[118:121]
	v_mfma_f32_16x16x32_bf16 v[98:101], v[154:157], v[194:197], v[98:101]
	v_mfma_f32_16x16x32_bf16 v[126:129], v[146:149], v[202:205], v[126:129]
	v_mfma_f32_16x16x32_bf16 v[110:113], v[154:157], v[202:205], v[110:113]
	v_mfma_f32_16x16x32_bf16 v[122:125], v[146:149], v[210:213], v[122:125]
	v_mfma_f32_16x16x32_bf16 v[114:117], v[154:157], v[210:213], v[114:117]
	v_mfma_f32_16x16x32_bf16 v[94:97], v[150:153], v[190:193], v[94:97]
	v_mfma_f32_16x16x32_bf16 v[90:93], v[158:161], v[190:193], v[90:93]
	v_mfma_f32_16x16x32_bf16 v[118:121], v[150:153], v[198:201], v[118:121]
	v_mfma_f32_16x16x32_bf16 v[98:101], v[158:161], v[198:201], v[98:101]
	v_mfma_f32_16x16x32_bf16 v[126:129], v[150:153], v[206:209], v[126:129]
	v_mfma_f32_16x16x32_bf16 v[110:113], v[158:161], v[206:209], v[110:113]
	v_mfma_f32_16x16x32_bf16 v[122:125], v[150:153], v[214:217], v[122:125]
	v_mfma_f32_16x16x32_bf16 v[114:117], v[158:161], v[214:217], v[114:117]
	s_setprio 0
	s_setprio 1
	v_mfma_f32_16x16x32_bf16 v[38:41], v[170:173], v[186:189], v[38:41]
	v_mfma_f32_16x16x32_bf16 v[34:37], v[178:181], v[186:189], v[34:37]
	v_mfma_f32_16x16x32_bf16 v[66:69], v[170:173], v[194:197], v[66:69]
	v_mfma_f32_16x16x32_bf16 v[46:49], v[178:181], v[194:197], v[46:49]
	v_mfma_f32_16x16x32_bf16 v[78:81], v[170:173], v[202:205], v[78:81]
	v_mfma_f32_16x16x32_bf16 v[62:65], v[178:181], v[202:205], v[62:65]
	v_mfma_f32_16x16x32_bf16 v[106:109], v[170:173], v[210:213], v[106:109]
	v_mfma_f32_16x16x32_bf16 v[102:105], v[178:181], v[210:213], v[102:105]
	v_mfma_f32_16x16x32_bf16 v[38:41], v[174:177], v[190:193], v[38:41]
	v_mfma_f32_16x16x32_bf16 v[34:37], v[182:185], v[190:193], v[34:37]
	v_mfma_f32_16x16x32_bf16 v[66:69], v[174:177], v[198:201], v[66:69]
	v_mfma_f32_16x16x32_bf16 v[46:49], v[182:185], v[198:201], v[46:49]
	v_mfma_f32_16x16x32_bf16 v[78:81], v[174:177], v[206:209], v[78:81]
	v_mfma_f32_16x16x32_bf16 v[62:65], v[182:185], v[206:209], v[62:65]
	v_mfma_f32_16x16x32_bf16 v[106:109], v[174:177], v[214:217], v[106:109]
	v_mfma_f32_16x16x32_bf16 v[102:105], v[182:185], v[214:217], v[102:105]
	s_setprio 0
	s_barrier
; #define PG8_STAGE(bufoff, gbase, voff) do { _Pragma("unroll") for (int _i = 0; _i < 2; ++_i) \
;         __builtin_amdgcn_global_load_lds((const unsigned*)((const char*)(gbase) + (voff)[_i]), (LAS unsigned*)(lds + (bufoff) + ldsw + _i * 8192), 16, 0, 0); } while (0)
; #define PG8_LDA(dst, b, h) do { _Pragma("unroll") for (int m = 0; m < 4; ++m) _Pragma("unroll") for (int k = 0; k < 2; ++k) dst[m][k] = *(const LAS bf16x8*)(lds + PG8_SA(b, h) + aoff + m * 2048 + k * 1024); } while (0)
; #define PG8_LDB(dst, b, h) do { _Pragma("unroll") for (int n = 0; n < 2; ++n) _Pragma("unroll") for (int k = 0; k < 2; ++k) dst[n][k] = *(const LAS bf16x8*)(lds + PG8_SB(b, h) + boff + n * 2048 + k * 1024); } while (0)
; #define PG8_MMA(ai, bj, At, Bt) do { __builtin_amdgcn_s_setprio(1); _Pragma("unroll") for (int m = 0; m < 4; ++m) _Pragma("unroll") for (int n = 0; n < 2; ++n) _Pragma("unroll") for (int k = 0; k < 2; ++k) \
;         acc[ai][bj][m][n] = __builtin_amdgcn_mfma_f32_16x16x32_bf16(Bt[n][k], At[m][k], acc[ai][bj][m][n], 0, 0, 0); __builtin_amdgcn_s_setprio(0); } while (0)
; #define PG8_WAIT_V(n) asm volatile("s_waitcnt vmcnt(" #n ")" ::: "memory")
; #define PG8_WAIT_L(n) asm volatile("s_waitcnt lgkmcnt(" #n ")" ::: "memory")
; #define PG8_BAR __builtin_amdgcn_s_barrier()
; #define PG8_SCHED __builtin_amdgcn_sched_barrier(0)
; template <class Epi, class Sched, bool ALIGN_EPI, class Hook = NoHook>
; __device__ __forceinline__ void gemm_phase(LAS unsigned char* lds, const Gemm g, const Sched& S, const Epi& E, const Hook& H = Hook()) {
;     ...
;             PG8_LDB(B0, 1, 0); PG8_LDB(B1, 1, 1); PG8_SCHED; PG8_LDA(At, 1, 0); PG8_STAGE(PG8_SA(0, 1), a2 + hA, voffA);
;             PG8_WAIT_V(8); PG8_WAIT_L(0); PG8_BAR; PG8_MMA(0, 0, At, B0); PG8_MMA(0, 1, At, B1); PG8_BAR; PG8_SCHED;
;             PG8_LDA(At, 1, 1); PG8_STAGE(PG8_SB(1, 0), b3, voffB); PG8_STAGE(PG8_SB(1, 1), b3 + hB, voffB); PG8_STAGE(PG8_SA(1, 0), a3, voffA);
;             PG8_WAIT_V(8); PG8_WAIT_L(0); PG8_BAR; PG8_MMA(1, 0, At, B0); PG8_MMA(1, 1, At, B1); PG8_BAR; PG8_SCHED;
;         }
;         if constexpr (Hook::ON) H.after(te, acc, cur, wr, wc, fr, fq);
;         }
;         if constexpr (ALIGN_EPI) { if (wr == 0) PG8_BAR; }
	ds_read_b128 v[146:149], v143
	ds_read_b128 v[150:153], v143 offset:1024
	ds_read_b128 v[154:157], v143 offset:2048
	ds_read_b128 v[158:161], v143 offset:3072
	ds_read_b128 v[170:173], v144
	ds_read_b128 v[174:177], v144 offset:1024
	ds_read_b128 v[178:181], v144 offset:2048
	ds_read_b128 v[182:185], v144 offset:3072
	s_add_u32 s16, s16, 0x2b0000
	s_addc_u32 s17, s17, 0
	s_mov_b32 m0, s29
	ds_read_b128 v[186:189], v142 offset:32768
	ds_read_b128 v[190:193], v142 offset:33792
	ds_read_b128 v[194:197], v142 offset:34816
	ds_read_b128 v[198:201], v142 offset:35840
	ds_read_b128 v[202:205], v142 offset:36864
	ds_read_b128 v[206:209], v142 offset:37888
	ds_read_b128 v[210:213], v142 offset:38912
	ds_read_b128 v[214:217], v142 offset:39936
	global_load_lds_dwordx4 v130, s[16:17]
	s_mov_b32 m0, s39
	s_nop 0
	global_load_lds_dwordx4 v132, s[16:17]
	s_waitcnt vmcnt(8)
	s_waitcnt lgkmcnt(0)
	s_barrier
	s_setprio 1
	s_waitcnt lgkmcnt(0)
	v_mfma_f32_16x16x32_bf16 v[82:85], v[146:149], v[186:189], v[82:85]
	v_mfma_f32_16x16x32_bf16 v[54:57], v[154:157], v[186:189], v[54:57]
	v_mfma_f32_16x16x32_bf16 v[58:61], v[146:149], v[194:197], v[58:61]
	v_mfma_f32_16x16x32_bf16 v[42:45], v[154:157], v[194:197], v[42:45]
	v_mfma_f32_16x16x32_bf16 v[70:73], v[146:149], v[202:205], v[70:73]
	v_mfma_f32_16x16x32_bf16 v[50:53], v[154:157], v[202:205], v[50:53]
	v_mfma_f32_16x16x32_bf16 v[86:89], v[146:149], v[210:213], v[86:89]
	v_mfma_f32_16x16x32_bf16 v[74:77], v[154:157], v[210:213], v[74:77]
	v_mfma_f32_16x16x32_bf16 v[82:85], v[150:153], v[190:193], v[82:85]
	v_mfma_f32_16x16x32_bf16 v[54:57], v[158:161], v[190:193], v[54:57]
	v_mfma_f32_16x16x32_bf16 v[58:61], v[150:153], v[198:201], v[58:61]
	v_mfma_f32_16x16x32_bf16 v[42:45], v[158:161], v[198:201], v[42:45]
	v_mfma_f32_16x16x32_bf16 v[70:73], v[150:153], v[206:209], v[70:73]
	v_mfma_f32_16x16x32_bf16 v[50:53], v[158:161], v[206:209], v[50:53]
	v_mfma_f32_16x16x32_bf16 v[86:89], v[150:153], v[214:217], v[86:89]
	v_mfma_f32_16x16x32_bf16 v[74:77], v[158:161], v[214:217], v[74:77]
	s_setprio 0
	s_setprio 1
	v_mfma_f32_16x16x32_bf16 v[14:17], v[170:173], v[186:189], v[14:17]
	v_mfma_f32_16x16x32_bf16 v[2:5], v[178:181], v[186:189], v[2:5]
	v_mfma_f32_16x16x32_bf16 v[18:21], v[170:173], v[194:197], v[18:21]
	v_mfma_f32_16x16x32_bf16 v[6:9], v[178:181], v[194:197], v[6:9]
	v_mfma_f32_16x16x32_bf16 v[22:25], v[170:173], v[202:205], v[22:25]
	v_mfma_f32_16x16x32_bf16 v[10:13], v[178:181], v[202:205], v[10:13]
	v_mfma_f32_16x16x32_bf16 v[30:33], v[170:173], v[210:213], v[30:33]
	v_mfma_f32_16x16x32_bf16 v[26:29], v[178:181], v[210:213], v[26:29]
	v_mfma_f32_16x16x32_bf16 v[14:17], v[174:177], v[190:193], v[14:17]
	v_mfma_f32_16x16x32_bf16 v[2:5], v[182:185], v[190:193], v[2:5]
	v_mfma_f32_16x16x32_bf16 v[18:21], v[174:177], v[198:201], v[18:21]
	v_mfma_f32_16x16x32_bf16 v[6:9], v[182:185], v[198:201], v[6:9]
	v_mfma_f32_16x16x32_bf16 v[22:25], v[174:177], v[206:209], v[22:25]
	v_mfma_f32_16x16x32_bf16 v[10:13], v[182:185], v[206:209], v[10:13]
	v_mfma_f32_16x16x32_bf16 v[30:33], v[174:177], v[214:217], v[30:33]
	v_mfma_f32_16x16x32_bf16 v[26:29], v[182:185], v[214:217], v[26:29]
	s_setprio 0
	s_barrier
	s_mov_b32 m0, s36
	s_add_u32 s52, s10, s2
	s_addc_u32 s53, s11, s3
	s_add_u32 s10, s10, 0x2b0080
	ds_read_b128 v[186:189], v142 offset:49152
	ds_read_b128 v[190:193], v142 offset:50176
	ds_read_b128 v[194:197], v142 offset:51200
	ds_read_b128 v[198:201], v142 offset:52224
	ds_read_b128 v[202:205], v142 offset:53248
	ds_read_b128 v[206:209], v142 offset:54272
	ds_read_b128 v[210:213], v142 offset:55296
	ds_read_b128 v[214:217], v142 offset:56320
	global_load_lds_dwordx4 v162, s[52:53]
	s_mov_b32 m0, s44
	s_addc_u32 s11, s11, 0
	global_load_lds_dwordx4 v134, s[52:53]
	s_mov_b32 m0, s37
	s_nop 0
	global_load_lds_dwordx4 v162, s[10:11]
	s_mov_b32 m0, s45
	s_nop 0
	global_load_lds_dwordx4 v134, s[10:11]
	v_lshl_add_u64 v[218:219], v[222:223], 0, s[2:3]
	s_mov_b32 m0, s41
	s_nop 0
	global_load_lds_dwordx4 v[218:219], off
	v_lshl_add_u64 v[218:219], v[224:225], 0, s[2:3]
	s_mov_b32 m0, s42
	s_nop 0
	global_load_lds_dwordx4 v[218:219], off
	s_waitcnt vmcnt(8)
	s_waitcnt lgkmcnt(0)
	s_barrier
	s_setprio 1
	s_waitcnt lgkmcnt(0)
	v_mfma_f32_16x16x32_bf16 v[94:97], v[146:149], v[186:189], v[94:97]
	v_mfma_f32_16x16x32_bf16 v[90:93], v[154:157], v[186:189], v[90:93]
	v_mfma_f32_16x16x32_bf16 v[118:121], v[146:149], v[194:197], v[118:121]
	v_mfma_f32_16x16x32_bf16 v[98:101], v[154:157], v[194:197], v[98:101]
	v_mfma_f32_16x16x32_bf16 v[126:129], v[146:149], v[202:205], v[126:129]
	v_mfma_f32_16x16x32_bf16 v[110:113], v[154:157], v[202:205], v[110:113]
	v_mfma_f32_16x16x32_bf16 v[122:125], v[146:149], v[210:213], v[122:125]
	v_mfma_f32_16x16x32_bf16 v[114:117], v[154:157], v[210:213], v[114:117]
	v_mfma_f32_16x16x32_bf16 v[94:97], v[150:153], v[190:193], v[94:97]
	v_mfma_f32_16x16x32_bf16 v[90:93], v[158:161], v[190:193], v[90:93]
	v_mfma_f32_16x16x32_bf16 v[118:121], v[150:153], v[198:201], v[118:121]
	v_mfma_f32_16x16x32_bf16 v[98:101], v[158:161], v[198:201], v[98:101]
	v_mfma_f32_16x16x32_bf16 v[126:129], v[150:153], v[206:209], v[126:129]
	v_mfma_f32_16x16x32_bf16 v[110:113], v[158:161], v[206:209], v[110:113]
	v_mfma_f32_16x16x32_bf16 v[122:125], v[150:153], v[214:217], v[122:125]
	v_mfma_f32_16x16x32_bf16 v[114:117], v[158:161], v[214:217], v[114:117]
	s_setprio 0
	s_setprio 1
	v_mfma_f32_16x16x32_bf16 v[38:41], v[170:173], v[186:189], v[38:41]
	v_mfma_f32_16x16x32_bf16 v[34:37], v[178:181], v[186:189], v[34:37]
	v_mfma_f32_16x16x32_bf16 v[66:69], v[170:173], v[194:197], v[66:69]
	v_mfma_f32_16x16x32_bf16 v[46:49], v[178:181], v[194:197], v[46:49]
	v_mfma_f32_16x16x32_bf16 v[78:81], v[170:173], v[202:205], v[78:81]
	v_mfma_f32_16x16x32_bf16 v[62:65], v[178:181], v[202:205], v[62:65]
	v_mfma_f32_16x16x32_bf16 v[106:109], v[170:173], v[210:213], v[106:109]
	v_mfma_f32_16x16x32_bf16 v[102:105], v[178:181], v[210:213], v[102:105]
	v_mfma_f32_16x16x32_bf16 v[38:41], v[174:177], v[190:193], v[38:41]
	v_mfma_f32_16x16x32_bf16 v[34:37], v[182:185], v[190:193], v[34:37]
	v_mfma_f32_16x16x32_bf16 v[66:69], v[174:177], v[198:201], v[66:69]
	v_mfma_f32_16x16x32_bf16 v[46:49], v[182:185], v[198:201], v[46:49]
	v_mfma_f32_16x16x32_bf16 v[78:81], v[174:177], v[206:209], v[78:81]
	v_mfma_f32_16x16x32_bf16 v[62:65], v[182:185], v[206:209], v[62:65]
	v_mfma_f32_16x16x32_bf16 v[106:109], v[174:177], v[214:217], v[106:109]
	v_mfma_f32_16x16x32_bf16 v[102:105], v[182:185], v[214:217], v[102:105]
	s_setprio 0
	s_barrier
	s_add_i32 s18, s18, 2
	s_add_u32 s4, s4, 0x100
	s_addc_u32 s5, s5, 0
	s_cmpk_gt_u32 s18, 0xa9
	s_cbranch_scc0 .LBB0_1406
	s_cmpk_lt_u32 s22, 0x100
	s_cbranch_scc0 .LBB0_1409
	s_barrier
